# merged GEMM K-loops without s_setprio flips (on top of v31)
# baseline (speedup 1.0000x reference)
.LBB0_99:
	v_add_u32_e32 v137, 0x10000, v135
	ds_read_b128 v[138:141], v137
	ds_read_b128 v[142:145], v137 offset:1024
	ds_read_b128 v[146:149], v137 offset:2048
	ds_read_b128 v[150:153], v137 offset:3072
	ds_read_b128 v[154:157], v136
	ds_read_b128 v[158:161], v136 offset:1024
	ds_read_b128 v[162:165], v136 offset:2048
	ds_read_b128 v[166:169], v136 offset:3072
	ds_read_b128 v[170:173], v136 offset:4096
	ds_read_b128 v[174:177], v136 offset:5120
	ds_read_b128 v[178:181], v136 offset:6144
	ds_read_b128 v[182:185], v136 offset:7168
	v_add_u32_e32 v137, 0x14000, v135
	ds_read_b128 v[186:189], v137
	ds_read_b128 v[194:197], v137 offset:1024
	ds_read_b128 v[198:201], v137 offset:2048
	ds_read_b128 v[202:205], v137 offset:3072
	s_add_i32 s35, s34, 0x100
	s_and_b64 s[28:29], s[28:29], exec
	s_cselect_b32 s29, 0, s35
	s_cselect_b32 s28, 0, 0
	s_add_u32 s38, s12, s29
	s_addc_u32 s39, s13, s28
	s_add_i32 s47, 0, 0x10000
	s_add_u32 s40, s2, s29
	s_addc_u32 s41, s3, s28
	s_add_u32 s48, s4, s34
	s_addc_u32 s49, s5, 0
	s_add_i32 vcc_lo, s47, s52
	s_add_i32 m0, s9, 0xc000
	s_add_i32 s53, s9, 0xe000
	s_add_i32 vcc_hi, 0, 0x14000
	s_add_i32 s46, vcc_lo, 0x2000
	s_add_u32 s36, s40, 0x28000
	s_addc_u32 s37, s41, 0
	s_add_i32 s75, vcc_hi, s52
	s_add_i32 s74, s75, 0x2000
	s_add_i32 s71, 0, 0x18000
	s_add_u32 s34, s38, 0x10000
	s_addc_u32 s35, s39, 0
	s_add_i32 s69, s71, s52
	s_add_i32 s67, 0, 0x1c000
	s_add_i32 s66, s69, 0x2000
	s_add_u32 s28, s40, 0x28080
	s_addc_u32 s29, s41, 0
	s_add_i32 s79, s67, s52
	s_add_i32 s78, s79, 0x2000
	v_lshl_add_u64 v[218:219], s[48:49], 0, v[128:129]
	v_lshl_add_u64 v[222:223], v[218:219], 0, s[72:73]
	global_load_lds_dwordx4 v[222:223], off
	v_lshl_add_u64 v[222:223], s[48:49], 0, v[130:131]
	v_lshl_add_u64 v[220:221], v[222:223], 0, s[72:73]
	s_mov_b32 m0, s53
	s_nop 0
	global_load_lds_dwordx4 v[220:221], off
	s_waitcnt vmcnt(8)
	s_waitcnt lgkmcnt(0)
	s_barrier
	v_mfma_f32_16x16x32_bf16 v[124:127], v[138:141], v[154:157], v[124:127]
	v_mfma_f32_16x16x32_bf16 v[120:123], v[146:149], v[154:157], v[120:123]
	v_mfma_f32_16x16x32_bf16 v[116:119], v[138:141], v[162:165], v[116:119]
	v_mfma_f32_16x16x32_bf16 v[108:111], v[146:149], v[162:165], v[108:111]
	v_mfma_f32_16x16x32_bf16 v[100:103], v[138:141], v[170:173], v[100:103]
	v_mfma_f32_16x16x32_bf16 v[92:95], v[146:149], v[170:173], v[92:95]
	v_mfma_f32_16x16x32_bf16 v[84:87], v[138:141], v[178:181], v[84:87]
	v_mfma_f32_16x16x32_bf16 v[76:79], v[146:149], v[178:181], v[76:79]
	v_mfma_f32_16x16x32_bf16 v[124:127], v[142:145], v[158:161], v[124:127]
	v_mfma_f32_16x16x32_bf16 v[120:123], v[150:153], v[158:161], v[120:123]
	v_mfma_f32_16x16x32_bf16 v[116:119], v[142:145], v[166:169], v[116:119]
	v_mfma_f32_16x16x32_bf16 v[108:111], v[150:153], v[166:169], v[108:111]
	v_mfma_f32_16x16x32_bf16 v[100:103], v[142:145], v[174:177], v[100:103]
	v_mfma_f32_16x16x32_bf16 v[92:95], v[150:153], v[174:177], v[92:95]
	v_mfma_f32_16x16x32_bf16 v[84:87], v[142:145], v[182:185], v[84:87]
	v_mfma_f32_16x16x32_bf16 v[76:79], v[150:153], v[182:185], v[76:79]
	v_mfma_f32_16x16x32_bf16 v[112:115], v[186:189], v[154:157], v[112:115]
	v_mfma_f32_16x16x32_bf16 v[104:107], v[198:201], v[154:157], v[104:107]
	v_mfma_f32_16x16x32_bf16 v[96:99], v[186:189], v[162:165], v[96:99]
	v_mfma_f32_16x16x32_bf16 v[88:91], v[198:201], v[162:165], v[88:91]
	v_mfma_f32_16x16x32_bf16 v[80:83], v[186:189], v[170:173], v[80:83]
	v_mfma_f32_16x16x32_bf16 v[72:75], v[198:201], v[170:173], v[72:75]
	v_mfma_f32_16x16x32_bf16 v[68:71], v[186:189], v[178:181], v[68:71]
	v_mfma_f32_16x16x32_bf16 v[64:67], v[198:201], v[178:181], v[64:67]
	v_mfma_f32_16x16x32_bf16 v[112:115], v[194:197], v[158:161], v[112:115]
	v_mfma_f32_16x16x32_bf16 v[104:107], v[202:205], v[158:161], v[104:107]
	v_mfma_f32_16x16x32_bf16 v[96:99], v[194:197], v[166:169], v[96:99]
	v_mfma_f32_16x16x32_bf16 v[88:91], v[202:205], v[166:169], v[88:91]
	v_mfma_f32_16x16x32_bf16 v[80:83], v[194:197], v[174:177], v[80:83]
	v_mfma_f32_16x16x32_bf16 v[72:75], v[202:205], v[174:177], v[72:75]
	v_mfma_f32_16x16x32_bf16 v[68:71], v[194:197], v[182:185], v[68:71]
	v_mfma_f32_16x16x32_bf16 v[64:67], v[202:205], v[182:185], v[64:67]
	s_barrier
	ds_read_b128 v[154:157], v136 offset:16384
	ds_read_b128 v[158:161], v136 offset:17408
	ds_read_b128 v[162:165], v136 offset:18432
	ds_read_b128 v[166:169], v136 offset:19456
	ds_read_b128 v[170:173], v136 offset:20480
	ds_read_b128 v[174:177], v136 offset:21504
	ds_read_b128 v[178:181], v136 offset:22528
	ds_read_b128 v[182:185], v136 offset:23552
	s_mov_b32 m0, vcc_lo
	v_lshl_add_u64 v[190:191], s[40:41], 0, v[192:193]
	global_load_lds_dwordx4 v[190:191], off
	v_lshl_add_u64 v[206:207], s[40:41], 0, v[132:133]
	s_mov_b32 m0, s46
	s_nop 0
	global_load_lds_dwordx4 v[206:207], off
	s_mov_b32 m0, s9
	v_lshl_add_u64 v[208:209], s[38:39], 0, v[128:129]
	global_load_lds_dwordx4 v[208:209], off
	v_lshl_add_u64 v[210:211], s[38:39], 0, v[130:131]
	s_mov_b32 m0, s54
	s_nop 0
	global_load_lds_dwordx4 v[210:211], off
	s_mov_b32 m0, s75
	v_lshl_add_u64 v[218:219], s[36:37], 0, v[192:193]
	global_load_lds_dwordx4 v[218:219], off
	v_lshl_add_u64 v[220:221], s[36:37], 0, v[132:133]
	s_mov_b32 m0, s74
	s_nop 0
	global_load_lds_dwordx4 v[220:221], off
	s_waitcnt vmcnt(8)
	s_waitcnt lgkmcnt(0)
	s_barrier
	v_mfma_f32_16x16x32_bf16 v[60:63], v[138:141], v[154:157], v[60:63]
	v_mfma_f32_16x16x32_bf16 v[56:59], v[146:149], v[154:157], v[56:59]
	v_mfma_f32_16x16x32_bf16 v[52:55], v[138:141], v[162:165], v[52:55]
	v_mfma_f32_16x16x32_bf16 v[44:47], v[146:149], v[162:165], v[44:47]
	v_mfma_f32_16x16x32_bf16 v[36:39], v[138:141], v[170:173], v[36:39]
	v_mfma_f32_16x16x32_bf16 v[28:31], v[146:149], v[170:173], v[28:31]
	v_mfma_f32_16x16x32_bf16 v[20:23], v[138:141], v[178:181], v[20:23]
	v_mfma_f32_16x16x32_bf16 v[12:15], v[146:149], v[178:181], v[12:15]
	v_mfma_f32_16x16x32_bf16 v[60:63], v[142:145], v[158:161], v[60:63]
	v_mfma_f32_16x16x32_bf16 v[56:59], v[150:153], v[158:161], v[56:59]
	v_mfma_f32_16x16x32_bf16 v[52:55], v[142:145], v[166:169], v[52:55]
	v_mfma_f32_16x16x32_bf16 v[44:47], v[150:153], v[166:169], v[44:47]
	v_mfma_f32_16x16x32_bf16 v[36:39], v[142:145], v[174:177], v[36:39]
	v_mfma_f32_16x16x32_bf16 v[28:31], v[150:153], v[174:177], v[28:31]
	v_mfma_f32_16x16x32_bf16 v[20:23], v[142:145], v[182:185], v[20:23]
	v_mfma_f32_16x16x32_bf16 v[12:15], v[150:153], v[182:185], v[12:15]
	v_mfma_f32_16x16x32_bf16 v[48:51], v[186:189], v[154:157], v[48:51]
	v_mfma_f32_16x16x32_bf16 v[40:43], v[198:201], v[154:157], v[40:43]
	v_mfma_f32_16x16x32_bf16 v[32:35], v[186:189], v[162:165], v[32:35]
	v_mfma_f32_16x16x32_bf16 v[24:27], v[198:201], v[162:165], v[24:27]
	v_mfma_f32_16x16x32_bf16 v[16:19], v[186:189], v[170:173], v[16:19]
	v_mfma_f32_16x16x32_bf16 v[8:11], v[198:201], v[170:173], v[8:11]
	v_mfma_f32_16x16x32_bf16 v[4:7], v[186:189], v[178:181], v[4:7]
	v_mfma_f32_16x16x32_bf16 v[0:3], v[198:201], v[178:181], v[0:3]
	v_mfma_f32_16x16x32_bf16 v[48:51], v[194:197], v[158:161], v[48:51]
	v_mfma_f32_16x16x32_bf16 v[40:43], v[202:205], v[158:161], v[40:43]
	v_mfma_f32_16x16x32_bf16 v[32:35], v[194:197], v[166:169], v[32:35]
	v_mfma_f32_16x16x32_bf16 v[24:27], v[202:205], v[166:169], v[24:27]
	v_mfma_f32_16x16x32_bf16 v[16:19], v[194:197], v[174:177], v[16:19]
	v_mfma_f32_16x16x32_bf16 v[8:11], v[202:205], v[174:177], v[8:11]
	v_mfma_f32_16x16x32_bf16 v[4:7], v[194:197], v[182:185], v[4:7]
	v_mfma_f32_16x16x32_bf16 v[0:3], v[202:205], v[182:185], v[0:3]
	s_barrier
	v_add_u32_e32 v137, 0x18000, v135
	ds_read_b128 v[138:141], v137
	ds_read_b128 v[142:145], v137 offset:1024
	ds_read_b128 v[146:149], v137 offset:2048
	ds_read_b128 v[150:153], v137 offset:3072
	ds_read_b128 v[154:157], v136 offset:32768
	ds_read_b128 v[158:161], v136 offset:33792
	ds_read_b128 v[162:165], v136 offset:34816
	ds_read_b128 v[166:169], v136 offset:35840
	ds_read_b128 v[170:173], v136 offset:36864
	ds_read_b128 v[174:177], v136 offset:37888
	ds_read_b128 v[178:181], v136 offset:38912
	ds_read_b128 v[182:185], v136 offset:39936
	v_add_u32_e32 v137, 0x1c000, v135
	ds_read_b128 v[186:189], v137
	ds_read_b128 v[194:197], v137 offset:1024
	ds_read_b128 v[198:201], v137 offset:2048
	ds_read_b128 v[202:205], v137 offset:3072
	s_mov_b32 m0, s55
	v_lshl_add_u64 v[218:219], s[34:35], 0, v[128:129]
	global_load_lds_dwordx4 v[218:219], off
	v_lshl_add_u64 v[220:221], s[34:35], 0, v[130:131]
	s_mov_b32 m0, s58
	s_nop 0
	global_load_lds_dwordx4 v[220:221], off
	s_waitcnt vmcnt(8)
	s_waitcnt lgkmcnt(0)
	s_barrier
	v_mfma_f32_16x16x32_bf16 v[124:127], v[138:141], v[154:157], v[124:127]
	v_mfma_f32_16x16x32_bf16 v[120:123], v[146:149], v[154:157], v[120:123]
	v_mfma_f32_16x16x32_bf16 v[116:119], v[138:141], v[162:165], v[116:119]
	v_mfma_f32_16x16x32_bf16 v[108:111], v[146:149], v[162:165], v[108:111]
	v_mfma_f32_16x16x32_bf16 v[100:103], v[138:141], v[170:173], v[100:103]
	v_mfma_f32_16x16x32_bf16 v[92:95], v[146:149], v[170:173], v[92:95]
	v_mfma_f32_16x16x32_bf16 v[84:87], v[138:141], v[178:181], v[84:87]
	v_mfma_f32_16x16x32_bf16 v[76:79], v[146:149], v[178:181], v[76:79]
	v_mfma_f32_16x16x32_bf16 v[124:127], v[142:145], v[158:161], v[124:127]
	v_mfma_f32_16x16x32_bf16 v[120:123], v[150:153], v[158:161], v[120:123]
	v_mfma_f32_16x16x32_bf16 v[116:119], v[142:145], v[166:169], v[116:119]
	v_mfma_f32_16x16x32_bf16 v[108:111], v[150:153], v[166:169], v[108:111]
	v_mfma_f32_16x16x32_bf16 v[100:103], v[142:145], v[174:177], v[100:103]
	v_mfma_f32_16x16x32_bf16 v[92:95], v[150:153], v[174:177], v[92:95]
	v_mfma_f32_16x16x32_bf16 v[84:87], v[142:145], v[182:185], v[84:87]
	v_mfma_f32_16x16x32_bf16 v[76:79], v[150:153], v[182:185], v[76:79]
	v_mfma_f32_16x16x32_bf16 v[112:115], v[186:189], v[154:157], v[112:115]
	v_mfma_f32_16x16x32_bf16 v[104:107], v[198:201], v[154:157], v[104:107]
	v_mfma_f32_16x16x32_bf16 v[96:99], v[186:189], v[162:165], v[96:99]
	v_mfma_f32_16x16x32_bf16 v[88:91], v[198:201], v[162:165], v[88:91]
	v_mfma_f32_16x16x32_bf16 v[80:83], v[186:189], v[170:173], v[80:83]
	v_mfma_f32_16x16x32_bf16 v[72:75], v[198:201], v[170:173], v[72:75]
	v_mfma_f32_16x16x32_bf16 v[68:71], v[186:189], v[178:181], v[68:71]
	v_mfma_f32_16x16x32_bf16 v[64:67], v[198:201], v[178:181], v[64:67]
	v_mfma_f32_16x16x32_bf16 v[112:115], v[194:197], v[158:161], v[112:115]
	v_mfma_f32_16x16x32_bf16 v[104:107], v[202:205], v[158:161], v[104:107]
	v_mfma_f32_16x16x32_bf16 v[96:99], v[194:197], v[166:169], v[96:99]
	v_mfma_f32_16x16x32_bf16 v[88:91], v[202:205], v[166:169], v[88:91]
	v_mfma_f32_16x16x32_bf16 v[80:83], v[194:197], v[174:177], v[80:83]
	v_mfma_f32_16x16x32_bf16 v[72:75], v[202:205], v[174:177], v[72:75]
	v_mfma_f32_16x16x32_bf16 v[68:71], v[194:197], v[182:185], v[68:71]
	v_mfma_f32_16x16x32_bf16 v[64:67], v[202:205], v[182:185], v[64:67]
	s_barrier
	ds_read_b128 v[154:157], v136 offset:49152
	ds_read_b128 v[158:161], v136 offset:50176
	ds_read_b128 v[162:165], v136 offset:51200
	ds_read_b128 v[166:169], v136 offset:52224
	ds_read_b128 v[170:173], v136 offset:53248
	ds_read_b128 v[174:177], v136 offset:54272
	ds_read_b128 v[178:181], v136 offset:55296
	ds_read_b128 v[182:185], v136 offset:56320
	s_mov_b32 m0, s69
	v_lshl_add_u64 v[190:191], v[190:191], 0, s[72:73]
	global_load_lds_dwordx4 v[190:191], off
	v_lshl_add_u64 v[190:191], v[206:207], 0, s[72:73]
	s_mov_b32 m0, s66
	s_nop 0
	global_load_lds_dwordx4 v[190:191], off
	s_mov_b32 m0, s59
	v_lshl_add_u64 v[190:191], v[208:209], 0, s[72:73]
	global_load_lds_dwordx4 v[190:191], off
	v_lshl_add_u64 v[190:191], v[210:211], 0, s[72:73]
	s_mov_b32 m0, s62
	s_nop 0
	global_load_lds_dwordx4 v[190:191], off
	s_mov_b32 m0, s79
	v_lshl_add_u64 v[218:219], s[28:29], 0, v[192:193]
	global_load_lds_dwordx4 v[218:219], off
	v_lshl_add_u64 v[220:221], s[28:29], 0, v[132:133]
	s_mov_b32 m0, s78
	s_nop 0
	global_load_lds_dwordx4 v[220:221], off
	s_waitcnt vmcnt(8)
	s_waitcnt lgkmcnt(0)
	s_barrier
	v_mfma_f32_16x16x32_bf16 v[60:63], v[138:141], v[154:157], v[60:63]
	v_mfma_f32_16x16x32_bf16 v[56:59], v[146:149], v[154:157], v[56:59]
	v_mfma_f32_16x16x32_bf16 v[52:55], v[138:141], v[162:165], v[52:55]
	v_mfma_f32_16x16x32_bf16 v[44:47], v[146:149], v[162:165], v[44:47]
	v_mfma_f32_16x16x32_bf16 v[36:39], v[138:141], v[170:173], v[36:39]
	v_mfma_f32_16x16x32_bf16 v[28:31], v[146:149], v[170:173], v[28:31]
	v_mfma_f32_16x16x32_bf16 v[20:23], v[138:141], v[178:181], v[20:23]
	v_mfma_f32_16x16x32_bf16 v[12:15], v[146:149], v[178:181], v[12:15]
	v_mfma_f32_16x16x32_bf16 v[60:63], v[142:145], v[158:161], v[60:63]
	v_mfma_f32_16x16x32_bf16 v[56:59], v[150:153], v[158:161], v[56:59]
	v_mfma_f32_16x16x32_bf16 v[52:55], v[142:145], v[166:169], v[52:55]
	v_mfma_f32_16x16x32_bf16 v[44:47], v[150:153], v[166:169], v[44:47]
	v_mfma_f32_16x16x32_bf16 v[36:39], v[142:145], v[174:177], v[36:39]
	v_mfma_f32_16x16x32_bf16 v[28:31], v[150:153], v[174:177], v[28:31]
	v_mfma_f32_16x16x32_bf16 v[20:23], v[142:145], v[182:185], v[20:23]
	v_mfma_f32_16x16x32_bf16 v[12:15], v[150:153], v[182:185], v[12:15]
	v_mfma_f32_16x16x32_bf16 v[48:51], v[186:189], v[154:157], v[48:51]
	v_mfma_f32_16x16x32_bf16 v[40:43], v[198:201], v[154:157], v[40:43]
	v_mfma_f32_16x16x32_bf16 v[32:35], v[186:189], v[162:165], v[32:35]
	v_mfma_f32_16x16x32_bf16 v[24:27], v[198:201], v[162:165], v[24:27]
	v_mfma_f32_16x16x32_bf16 v[16:19], v[186:189], v[170:173], v[16:19]
	v_mfma_f32_16x16x32_bf16 v[8:11], v[198:201], v[170:173], v[8:11]
	v_mfma_f32_16x16x32_bf16 v[4:7], v[186:189], v[178:181], v[4:7]
	v_mfma_f32_16x16x32_bf16 v[0:3], v[198:201], v[178:181], v[0:3]
	v_mfma_f32_16x16x32_bf16 v[48:51], v[194:197], v[158:161], v[48:51]
	v_mfma_f32_16x16x32_bf16 v[40:43], v[202:205], v[158:161], v[40:43]
	v_mfma_f32_16x16x32_bf16 v[32:35], v[194:197], v[166:169], v[32:35]
	v_mfma_f32_16x16x32_bf16 v[24:27], v[202:205], v[166:169], v[24:27]
	v_mfma_f32_16x16x32_bf16 v[16:19], v[194:197], v[174:177], v[16:19]
	v_mfma_f32_16x16x32_bf16 v[8:11], v[202:205], v[174:177], v[8:11]
	v_mfma_f32_16x16x32_bf16 v[4:7], v[194:197], v[182:185], v[4:7]
	v_mfma_f32_16x16x32_bf16 v[0:3], v[202:205], v[182:185], v[0:3]
	s_andn2_b64 vcc, exec, s[14:15]
	s_mov_b64 s[28:29], -1
	s_mov_b64 s[14:15], 0
	s_movk_i32 s34, 0x100
	s_barrier
	s_cbranch_vccz .LBB0_99
	s_mul_i32 s2, s10, 0x1400000
	s_mul_hi_i32 s3, s10, 0x1400000
	s_add_u32 s2, s26, s2
	v_and_b32_e32 v128, 63, v134
	s_addc_u32 s3, s27, s3
	v_mov_b32 v128, v128
	s_add_i32 s63, s63, s51
	v_and_or_b32 v130, v128, 15, s63
	s_lshl_b32 s4, s50, 8
	v_ashrrev_i32_e32 v128, 1, v128
	s_or_b32 s4, s64, s4
	v_and_b32_e32 v128, -8, v128
	v_add_u32_e32 v128, s4, v128
	v_ashrrev_i32_e32 v131, 31, v130
	v_ashrrev_i32_e32 v129, 31, v128
	v_lshlrev_b64 v[132:133], 12, v[130:131]
	v_lshl_add_u64 v[132:133], s[2:3], 0, v[132:133]
	v_lshlrev_b64 v[134:135], 1, v[128:129]
	v_lshl_add_u64 v[128:129], v[132:133], 0, v[134:135]
	v_cvt_pk_bf16_f32 v124, v124, v125
	v_cvt_pk_bf16_f32 v125, v126, v127
	v_cvt_pk_bf16_f32 v126, v120, v121
	v_cvt_pk_bf16_f32 v127, v122, v123
	global_store_dwordx4 v[128:129], v[124:127], off
	v_cvt_pk_bf16_f32 v112, v112, v113
	v_cvt_pk_bf16_f32 v113, v114, v115
	v_cvt_pk_bf16_f32 v114, v104, v105
	v_or_b32_e32 v104, 16, v130
	v_ashrrev_i32_e32 v105, 31, v104
	v_lshlrev_b64 v[104:105], 12, v[104:105]
	v_lshl_add_u64 v[104:105], s[2:3], 0, v[104:105]
	v_cvt_pk_bf16_f32 v115, v106, v107
	global_store_dwordx4 v[128:129], v[112:115], off offset:256
	s_cmpk_lt_u32 s11, 0x100
	s_nop 0
	v_lshl_add_u64 v[112:113], v[104:105], 0, v[134:135]
	v_cvt_pk_bf16_f32 v104, v116, v117
	v_cvt_pk_bf16_f32 v105, v118, v119
	v_cvt_pk_bf16_f32 v106, v108, v109
	v_cvt_pk_bf16_f32 v107, v110, v111
	global_store_dwordx4 v[112:113], v[104:107], off
	v_cvt_pk_bf16_f32 v96, v96, v97
	v_cvt_pk_bf16_f32 v97, v98, v99
	v_cvt_pk_bf16_f32 v98, v88, v89
	v_or_b32_e32 v88, 32, v130
	v_ashrrev_i32_e32 v89, 31, v88
	v_lshlrev_b64 v[88:89], 12, v[88:89]
	v_lshl_add_u64 v[88:89], s[2:3], 0, v[88:89]
	v_cvt_pk_bf16_f32 v99, v90, v91
	global_store_dwordx4 v[112:113], v[96:99], off offset:256
	s_nop 1
	v_lshl_add_u64 v[96:97], v[88:89], 0, v[134:135]
	v_cvt_pk_bf16_f32 v88, v100, v101
	v_cvt_pk_bf16_f32 v89, v102, v103
	v_cvt_pk_bf16_f32 v90, v92, v93
	v_cvt_pk_bf16_f32 v91, v94, v95
	global_store_dwordx4 v[96:97], v[88:91], off
	v_cvt_pk_bf16_f32 v80, v80, v81
	v_cvt_pk_bf16_f32 v81, v82, v83
	v_cvt_pk_bf16_f32 v82, v72, v73
	v_or_b32_e32 v72, 48, v130
	v_ashrrev_i32_e32 v73, 31, v72
	v_lshlrev_b64 v[72:73], 12, v[72:73]
	v_lshl_add_u64 v[72:73], s[2:3], 0, v[72:73]
	v_cvt_pk_bf16_f32 v83, v74, v75
	global_store_dwordx4 v[96:97], v[80:83], off offset:256
	s_mov_b64 s[2:3], 0x80000
	s_nop 0
	v_lshl_add_u64 v[80:81], v[72:73], 0, v[134:135]
	v_cvt_pk_bf16_f32 v72, v84, v85
	v_cvt_pk_bf16_f32 v73, v86, v87
	v_cvt_pk_bf16_f32 v74, v76, v77
	v_cvt_pk_bf16_f32 v75, v78, v79
	global_store_dwordx4 v[80:81], v[72:75], off
	v_cvt_pk_bf16_f32 v68, v68, v69
	v_cvt_pk_bf16_f32 v69, v70, v71
	v_cvt_pk_bf16_f32 v70, v64, v65
	v_lshl_add_u64 v[64:65], v[128:129], 0, s[2:3]
	s_mov_b32 s2, 0x80000
	v_cvt_pk_bf16_f32 v71, v66, v67
	global_store_dwordx4 v[80:81], v[68:71], off offset:256
	v_cvt_pk_bf16_f32 v60, v60, v61
	v_cvt_pk_bf16_f32 v61, v62, v63
	v_cvt_pk_bf16_f32 v62, v56, v57
	v_add_co_u32_e32 v56, vcc, s2, v128
	v_cvt_pk_bf16_f32 v63, v58, v59
	s_mov_b64 s[2:3], 0x90000
	s_nop 0
	v_addc_co_u32_e32 v57, vcc, 0, v129, vcc
	global_store_dwordx4 v[56:57], v[60:63], off
	v_cvt_pk_bf16_f32 v48, v48, v49
	v_cvt_pk_bf16_f32 v49, v50, v51
	v_cvt_pk_bf16_f32 v50, v40, v41
	v_cvt_pk_bf16_f32 v51, v42, v43
	global_store_dwordx4 v[64:65], v[48:51], off offset:256
	v_cvt_pk_bf16_f32 v40, v52, v53
	v_cvt_pk_bf16_f32 v41, v54, v55
	v_cvt_pk_bf16_f32 v42, v44, v45
	v_cvt_pk_bf16_f32 v43, v46, v47
	s_nop 1
	v_lshl_add_u64 v[48:49], v[128:129], 0, s[2:3]
	s_mov_b32 s2, 0x90000
	v_add_co_u32_e32 v44, vcc, s2, v128
	s_mov_b64 s[2:3], 0xa0000
	s_nop 0
	v_addc_co_u32_e32 v45, vcc, 0, v129, vcc
	global_store_dwordx4 v[44:45], v[40:43], off
	v_cvt_pk_bf16_f32 v32, v32, v33
	v_cvt_pk_bf16_f32 v33, v34, v35
	v_cvt_pk_bf16_f32 v34, v24, v25
	v_cvt_pk_bf16_f32 v35, v26, v27
	global_store_dwordx4 v[48:49], v[32:35], off offset:256
	v_cvt_pk_bf16_f32 v24, v36, v37
	v_cvt_pk_bf16_f32 v25, v38, v39
	v_cvt_pk_bf16_f32 v26, v28, v29
	v_cvt_pk_bf16_f32 v27, v30, v31
	s_nop 1
	v_lshl_add_u64 v[32:33], v[128:129], 0, s[2:3]
	s_mov_b32 s2, 0xa0000
	v_add_co_u32_e32 v28, vcc, s2, v128
	s_mov_b64 s[2:3], 0xb0000
	s_nop 0
	v_addc_co_u32_e32 v29, vcc, 0, v129, vcc
	global_store_dwordx4 v[28:29], v[24:27], off
	v_cvt_pk_bf16_f32 v16, v16, v17
	v_cvt_pk_bf16_f32 v17, v18, v19
	v_cvt_pk_bf16_f32 v18, v8, v9
	v_cvt_pk_bf16_f32 v19, v10, v11
	global_store_dwordx4 v[32:33], v[16:19], off offset:256
	v_cvt_pk_bf16_f32 v8, v20, v21
	v_cvt_pk_bf16_f32 v9, v22, v23
	v_cvt_pk_bf16_f32 v10, v12, v13
	v_cvt_pk_bf16_f32 v11, v14, v15
	s_nop 1
	v_lshl_add_u64 v[16:17], v[128:129], 0, s[2:3]
	s_mov_b32 s2, 0xb0000
	v_add_co_u32_e32 v12, vcc, s2, v128
	s_nop 1
	v_addc_co_u32_e32 v13, vcc, 0, v129, vcc
	global_store_dwordx4 v[12:13], v[8:11], off
	v_cvt_pk_bf16_f32 v4, v4, v5
	v_cvt_pk_bf16_f32 v5, v6, v7
	v_cvt_pk_bf16_f32 v6, v0, v1
	v_cvt_pk_bf16_f32 v7, v2, v3
	global_store_dwordx4 v[16:17], v[4:7], off offset:256
	s_waitcnt vmcnt(0)
	s_cbranch_scc0 .LBB0_95
	s_barrier
	s_branch .LBB0_95

.LBB0_106:
	v_add_u32_e32 v141, 0x10000, v139
	ds_read_b128 v[142:145], v141
	ds_read_b128 v[146:149], v141 offset:1024
	ds_read_b128 v[150:153], v141 offset:2048
	ds_read_b128 v[154:157], v141 offset:3072
	ds_read_b128 v[158:161], v140
	ds_read_b128 v[162:165], v140 offset:1024
	ds_read_b128 v[166:169], v140 offset:2048
	ds_read_b128 v[170:173], v140 offset:3072
	ds_read_b128 v[174:177], v140 offset:4096
	ds_read_b128 v[178:181], v140 offset:5120
	ds_read_b128 v[182:185], v140 offset:6144
	ds_read_b128 v[186:189], v140 offset:7168
	v_add_u32_e32 v141, 0x14000, v139
	ds_read_b128 v[194:197], v141
	ds_read_b128 v[198:201], v141 offset:1024
	ds_read_b128 v[202:205], v141 offset:2048
	ds_read_b128 v[206:209], v141 offset:3072
	s_add_u32 s4, s2, 0x100
	s_addc_u32 s5, s3, 0
	s_cmp_lg_u32 s54, 4
	s_cselect_b32 s28, s4, 0
	s_cselect_b32 s9, s5, 0
	s_add_u32 s34, s12, s28
	s_addc_u32 s35, s13, s9
	s_add_i32 s46, 0, 0x10000
	s_add_u32 s28, s14, s28
	s_addc_u32 s29, s15, s9
	v_lshl_add_u64 v[190:191], v[134:135], 0, s[2:3]
	s_add_i32 m0, s40, 0xc000
	s_nop 0
	global_load_lds_dwordx4 v[190:191], off
	v_lshl_add_u64 v[190:191], v[136:137], 0, s[2:3]
	s_add_i32 m0, s40, 0xe000
	s_nop 0
	global_load_lds_dwordx4 v[190:191], off
	s_waitcnt vmcnt(8)
	s_waitcnt lgkmcnt(0)
	s_barrier
	v_mfma_f32_16x16x32_bf16 v[124:127], v[142:145], v[158:161], v[124:127]
	v_mfma_f32_16x16x32_bf16 v[120:123], v[150:153], v[158:161], v[120:123]
	v_mfma_f32_16x16x32_bf16 v[116:119], v[142:145], v[166:169], v[116:119]
	v_mfma_f32_16x16x32_bf16 v[108:111], v[150:153], v[166:169], v[108:111]
	v_mfma_f32_16x16x32_bf16 v[100:103], v[142:145], v[174:177], v[100:103]
	v_mfma_f32_16x16x32_bf16 v[92:95], v[150:153], v[174:177], v[92:95]
	v_mfma_f32_16x16x32_bf16 v[84:87], v[142:145], v[182:185], v[84:87]
	v_mfma_f32_16x16x32_bf16 v[76:79], v[150:153], v[182:185], v[76:79]
	v_mfma_f32_16x16x32_bf16 v[124:127], v[146:149], v[162:165], v[124:127]
	v_mfma_f32_16x16x32_bf16 v[120:123], v[154:157], v[162:165], v[120:123]
	v_mfma_f32_16x16x32_bf16 v[116:119], v[146:149], v[170:173], v[116:119]
	v_mfma_f32_16x16x32_bf16 v[108:111], v[154:157], v[170:173], v[108:111]
	v_mfma_f32_16x16x32_bf16 v[100:103], v[146:149], v[178:181], v[100:103]
	v_mfma_f32_16x16x32_bf16 v[92:95], v[154:157], v[178:181], v[92:95]
	v_mfma_f32_16x16x32_bf16 v[84:87], v[146:149], v[186:189], v[84:87]
	v_mfma_f32_16x16x32_bf16 v[76:79], v[154:157], v[186:189], v[76:79]
	v_mfma_f32_16x16x32_bf16 v[112:115], v[194:197], v[158:161], v[112:115]
	v_mfma_f32_16x16x32_bf16 v[104:107], v[202:205], v[158:161], v[104:107]
	v_mfma_f32_16x16x32_bf16 v[96:99], v[194:197], v[166:169], v[96:99]
	v_mfma_f32_16x16x32_bf16 v[88:91], v[202:205], v[166:169], v[88:91]
	v_mfma_f32_16x16x32_bf16 v[80:83], v[194:197], v[174:177], v[80:83]
	v_mfma_f32_16x16x32_bf16 v[72:75], v[202:205], v[174:177], v[72:75]
	v_mfma_f32_16x16x32_bf16 v[68:71], v[194:197], v[182:185], v[68:71]
	v_mfma_f32_16x16x32_bf16 v[64:67], v[202:205], v[182:185], v[64:67]
	v_mfma_f32_16x16x32_bf16 v[112:115], v[198:201], v[162:165], v[112:115]
	v_mfma_f32_16x16x32_bf16 v[104:107], v[206:209], v[162:165], v[104:107]
	v_mfma_f32_16x16x32_bf16 v[96:99], v[198:201], v[170:173], v[96:99]
	v_mfma_f32_16x16x32_bf16 v[88:91], v[206:209], v[170:173], v[88:91]
	v_mfma_f32_16x16x32_bf16 v[80:83], v[198:201], v[178:181], v[80:83]
	v_mfma_f32_16x16x32_bf16 v[72:75], v[206:209], v[178:181], v[72:75]
	v_mfma_f32_16x16x32_bf16 v[68:71], v[198:201], v[186:189], v[68:71]
	v_mfma_f32_16x16x32_bf16 v[64:67], v[206:209], v[186:189], v[64:67]
	s_barrier
	ds_read_b128 v[158:161], v140 offset:16384
	ds_read_b128 v[162:165], v140 offset:17408
	ds_read_b128 v[166:169], v140 offset:18432
	ds_read_b128 v[170:173], v140 offset:19456
	ds_read_b128 v[174:177], v140 offset:20480
	ds_read_b128 v[178:181], v140 offset:21504
	ds_read_b128 v[182:185], v140 offset:22528
	ds_read_b128 v[186:189], v140 offset:23552
	s_add_i32 s9, 0, 0x14000
	s_add_i32 s2, s46, s39
	v_lshl_add_u64 v[190:191], s[28:29], 0, v[192:193]
	s_mov_b32 m0, s2
	s_nop 0
	global_load_lds_dwordx4 v[190:191], off
	v_lshl_add_u64 v[210:211], s[28:29], 0, v[132:133]
	s_add_i32 m0, s2, 0x2000
	s_nop 0
	global_load_lds_dwordx4 v[210:211], off
	s_mov_b32 m0, s40
	v_lshl_add_u64 v[212:213], s[34:35], 0, v[128:129]
	global_load_lds_dwordx4 v[212:213], off
	v_lshl_add_u64 v[214:215], s[34:35], 0, v[130:131]
	s_mov_b32 m0, s41
	s_nop 0
	global_load_lds_dwordx4 v[214:215], off
	s_add_u32 s2, s28, 0x20000
	s_addc_u32 s3, s29, 0
	s_add_i32 s9, s9, s39
	v_lshl_add_u64 v[218:219], s[2:3], 0, v[192:193]
	s_mov_b32 m0, s9
	s_nop 0
	global_load_lds_dwordx4 v[218:219], off
	v_lshl_add_u64 v[220:221], s[2:3], 0, v[132:133]
	s_add_i32 m0, s9, 0x2000
	s_nop 0
	global_load_lds_dwordx4 v[220:221], off
	s_waitcnt vmcnt(8)
	s_waitcnt lgkmcnt(0)
	s_barrier
	v_mfma_f32_16x16x32_bf16 v[60:63], v[142:145], v[158:161], v[60:63]
	v_mfma_f32_16x16x32_bf16 v[56:59], v[150:153], v[158:161], v[56:59]
	v_mfma_f32_16x16x32_bf16 v[52:55], v[142:145], v[166:169], v[52:55]
	v_mfma_f32_16x16x32_bf16 v[44:47], v[150:153], v[166:169], v[44:47]
	v_mfma_f32_16x16x32_bf16 v[36:39], v[142:145], v[174:177], v[36:39]
	v_mfma_f32_16x16x32_bf16 v[28:31], v[150:153], v[174:177], v[28:31]
	v_mfma_f32_16x16x32_bf16 v[20:23], v[142:145], v[182:185], v[20:23]
	v_mfma_f32_16x16x32_bf16 v[12:15], v[150:153], v[182:185], v[12:15]
	v_mfma_f32_16x16x32_bf16 v[60:63], v[146:149], v[162:165], v[60:63]
	v_mfma_f32_16x16x32_bf16 v[56:59], v[154:157], v[162:165], v[56:59]
	v_mfma_f32_16x16x32_bf16 v[52:55], v[146:149], v[170:173], v[52:55]
	v_mfma_f32_16x16x32_bf16 v[44:47], v[154:157], v[170:173], v[44:47]
	v_mfma_f32_16x16x32_bf16 v[36:39], v[146:149], v[178:181], v[36:39]
	v_mfma_f32_16x16x32_bf16 v[28:31], v[154:157], v[178:181], v[28:31]
	v_mfma_f32_16x16x32_bf16 v[20:23], v[146:149], v[186:189], v[20:23]
	v_mfma_f32_16x16x32_bf16 v[12:15], v[154:157], v[186:189], v[12:15]
	v_mfma_f32_16x16x32_bf16 v[48:51], v[194:197], v[158:161], v[48:51]
	v_mfma_f32_16x16x32_bf16 v[40:43], v[202:205], v[158:161], v[40:43]
	v_mfma_f32_16x16x32_bf16 v[32:35], v[194:197], v[166:169], v[32:35]
	v_mfma_f32_16x16x32_bf16 v[24:27], v[202:205], v[166:169], v[24:27]
	v_mfma_f32_16x16x32_bf16 v[16:19], v[194:197], v[174:177], v[16:19]
	v_mfma_f32_16x16x32_bf16 v[8:11], v[202:205], v[174:177], v[8:11]
	v_mfma_f32_16x16x32_bf16 v[4:7], v[194:197], v[182:185], v[4:7]
	v_mfma_f32_16x16x32_bf16 v[0:3], v[202:205], v[182:185], v[0:3]
	v_mfma_f32_16x16x32_bf16 v[48:51], v[198:201], v[162:165], v[48:51]
	v_mfma_f32_16x16x32_bf16 v[40:43], v[206:209], v[162:165], v[40:43]
	v_mfma_f32_16x16x32_bf16 v[32:35], v[198:201], v[170:173], v[32:35]
	v_mfma_f32_16x16x32_bf16 v[24:27], v[206:209], v[170:173], v[24:27]
	v_mfma_f32_16x16x32_bf16 v[16:19], v[198:201], v[178:181], v[16:19]
	v_mfma_f32_16x16x32_bf16 v[8:11], v[206:209], v[178:181], v[8:11]
	v_mfma_f32_16x16x32_bf16 v[4:7], v[198:201], v[186:189], v[4:7]
	v_mfma_f32_16x16x32_bf16 v[0:3], v[206:209], v[186:189], v[0:3]
	s_barrier
	v_add_u32_e32 v141, 0x18000, v139
	ds_read_b128 v[142:145], v141
	ds_read_b128 v[146:149], v141 offset:1024
	ds_read_b128 v[150:153], v141 offset:2048
	ds_read_b128 v[154:157], v141 offset:3072
	ds_read_b128 v[158:161], v140 offset:32768
	ds_read_b128 v[162:165], v140 offset:33792
	ds_read_b128 v[166:169], v140 offset:34816
	ds_read_b128 v[170:173], v140 offset:35840
	ds_read_b128 v[174:177], v140 offset:36864
	ds_read_b128 v[178:181], v140 offset:37888
	ds_read_b128 v[182:185], v140 offset:38912
	ds_read_b128 v[186:189], v140 offset:39936
	v_add_u32_e32 v141, 0x1c000, v139
	ds_read_b128 v[194:197], v141
	ds_read_b128 v[198:201], v141 offset:1024
	ds_read_b128 v[202:205], v141 offset:2048
	ds_read_b128 v[206:209], v141 offset:3072
	s_add_i32 s9, 0, 0x18000
	s_add_u32 s2, s34, 0x20000
	s_addc_u32 s3, s35, 0
	s_mov_b32 m0, s48
	v_lshl_add_u64 v[218:219], s[2:3], 0, v[128:129]
	global_load_lds_dwordx4 v[218:219], off
	v_lshl_add_u64 v[220:221], s[2:3], 0, v[130:131]
	s_mov_b32 m0, s49
	s_nop 0
	global_load_lds_dwordx4 v[220:221], off
	s_waitcnt vmcnt(8)
	s_waitcnt lgkmcnt(0)
	s_barrier
	v_mfma_f32_16x16x32_bf16 v[124:127], v[142:145], v[158:161], v[124:127]
	v_mfma_f32_16x16x32_bf16 v[120:123], v[150:153], v[158:161], v[120:123]
	v_mfma_f32_16x16x32_bf16 v[116:119], v[142:145], v[166:169], v[116:119]
	v_mfma_f32_16x16x32_bf16 v[108:111], v[150:153], v[166:169], v[108:111]
	v_mfma_f32_16x16x32_bf16 v[100:103], v[142:145], v[174:177], v[100:103]
	v_mfma_f32_16x16x32_bf16 v[92:95], v[150:153], v[174:177], v[92:95]
	v_mfma_f32_16x16x32_bf16 v[84:87], v[142:145], v[182:185], v[84:87]
	v_mfma_f32_16x16x32_bf16 v[76:79], v[150:153], v[182:185], v[76:79]
	v_mfma_f32_16x16x32_bf16 v[124:127], v[146:149], v[162:165], v[124:127]
	v_mfma_f32_16x16x32_bf16 v[120:123], v[154:157], v[162:165], v[120:123]
	v_mfma_f32_16x16x32_bf16 v[116:119], v[146:149], v[170:173], v[116:119]
	v_mfma_f32_16x16x32_bf16 v[108:111], v[154:157], v[170:173], v[108:111]
	v_mfma_f32_16x16x32_bf16 v[100:103], v[146:149], v[178:181], v[100:103]
	v_mfma_f32_16x16x32_bf16 v[92:95], v[154:157], v[178:181], v[92:95]
	v_mfma_f32_16x16x32_bf16 v[84:87], v[146:149], v[186:189], v[84:87]
	v_mfma_f32_16x16x32_bf16 v[76:79], v[154:157], v[186:189], v[76:79]
	v_mfma_f32_16x16x32_bf16 v[112:115], v[194:197], v[158:161], v[112:115]
	v_mfma_f32_16x16x32_bf16 v[104:107], v[202:205], v[158:161], v[104:107]
	v_mfma_f32_16x16x32_bf16 v[96:99], v[194:197], v[166:169], v[96:99]
	v_mfma_f32_16x16x32_bf16 v[88:91], v[202:205], v[166:169], v[88:91]
	v_mfma_f32_16x16x32_bf16 v[80:83], v[194:197], v[174:177], v[80:83]
	v_mfma_f32_16x16x32_bf16 v[72:75], v[202:205], v[174:177], v[72:75]
	v_mfma_f32_16x16x32_bf16 v[68:71], v[194:197], v[182:185], v[68:71]
	v_mfma_f32_16x16x32_bf16 v[64:67], v[202:205], v[182:185], v[64:67]
	v_mfma_f32_16x16x32_bf16 v[112:115], v[198:201], v[162:165], v[112:115]
	v_mfma_f32_16x16x32_bf16 v[104:107], v[206:209], v[162:165], v[104:107]
	v_mfma_f32_16x16x32_bf16 v[96:99], v[198:201], v[170:173], v[96:99]
	v_mfma_f32_16x16x32_bf16 v[88:91], v[206:209], v[170:173], v[88:91]
	v_mfma_f32_16x16x32_bf16 v[80:83], v[198:201], v[178:181], v[80:83]
	v_mfma_f32_16x16x32_bf16 v[72:75], v[206:209], v[178:181], v[72:75]
	v_mfma_f32_16x16x32_bf16 v[68:71], v[198:201], v[186:189], v[68:71]
	v_mfma_f32_16x16x32_bf16 v[64:67], v[206:209], v[186:189], v[64:67]
	s_barrier
	ds_read_b128 v[158:161], v140 offset:49152
	ds_read_b128 v[162:165], v140 offset:50176
	ds_read_b128 v[166:169], v140 offset:51200
	ds_read_b128 v[170:173], v140 offset:52224
	ds_read_b128 v[174:177], v140 offset:53248
	ds_read_b128 v[178:181], v140 offset:54272
	ds_read_b128 v[182:185], v140 offset:55296
	ds_read_b128 v[186:189], v140 offset:56320
	s_add_i32 s34, 0, 0x1c000
	s_add_i32 s2, s9, s39
	v_lshl_add_u64 v[190:191], v[190:191], 0, s[72:73]
	s_mov_b32 m0, s2
	s_nop 0
	global_load_lds_dwordx4 v[190:191], off
	v_lshl_add_u64 v[190:191], v[210:211], 0, s[72:73]
	s_add_i32 m0, s2, 0x2000
	s_nop 0
	global_load_lds_dwordx4 v[190:191], off
	s_mov_b32 m0, s50
	v_lshl_add_u64 v[190:191], v[212:213], 0, s[72:73]
	global_load_lds_dwordx4 v[190:191], off
	v_lshl_add_u64 v[190:191], v[214:215], 0, s[72:73]
	s_mov_b32 m0, s51
	s_nop 0
	global_load_lds_dwordx4 v[190:191], off
	s_add_u32 s2, s28, 0x20080
	s_addc_u32 s3, s29, 0
	s_add_i32 s9, s34, s39
	v_lshl_add_u64 v[218:219], s[2:3], 0, v[192:193]
	s_mov_b32 m0, s9
	s_nop 0
	global_load_lds_dwordx4 v[218:219], off
	v_lshl_add_u64 v[220:221], s[2:3], 0, v[132:133]
	s_add_i32 m0, s9, 0x2000
	s_nop 0
	global_load_lds_dwordx4 v[220:221], off
	s_waitcnt vmcnt(8)
	s_waitcnt lgkmcnt(0)
	s_barrier
	v_mfma_f32_16x16x32_bf16 v[60:63], v[142:145], v[158:161], v[60:63]
	v_mfma_f32_16x16x32_bf16 v[56:59], v[150:153], v[158:161], v[56:59]
	v_mfma_f32_16x16x32_bf16 v[52:55], v[142:145], v[166:169], v[52:55]
	v_mfma_f32_16x16x32_bf16 v[44:47], v[150:153], v[166:169], v[44:47]
	v_mfma_f32_16x16x32_bf16 v[36:39], v[142:145], v[174:177], v[36:39]
	v_mfma_f32_16x16x32_bf16 v[28:31], v[150:153], v[174:177], v[28:31]
	v_mfma_f32_16x16x32_bf16 v[20:23], v[142:145], v[182:185], v[20:23]
	v_mfma_f32_16x16x32_bf16 v[12:15], v[150:153], v[182:185], v[12:15]
	v_mfma_f32_16x16x32_bf16 v[60:63], v[146:149], v[162:165], v[60:63]
	v_mfma_f32_16x16x32_bf16 v[56:59], v[154:157], v[162:165], v[56:59]
	v_mfma_f32_16x16x32_bf16 v[52:55], v[146:149], v[170:173], v[52:55]
	v_mfma_f32_16x16x32_bf16 v[44:47], v[154:157], v[170:173], v[44:47]
	v_mfma_f32_16x16x32_bf16 v[36:39], v[146:149], v[178:181], v[36:39]
	v_mfma_f32_16x16x32_bf16 v[28:31], v[154:157], v[178:181], v[28:31]
	v_mfma_f32_16x16x32_bf16 v[20:23], v[146:149], v[186:189], v[20:23]
	v_mfma_f32_16x16x32_bf16 v[12:15], v[154:157], v[186:189], v[12:15]
	v_mfma_f32_16x16x32_bf16 v[48:51], v[194:197], v[158:161], v[48:51]
	v_mfma_f32_16x16x32_bf16 v[40:43], v[202:205], v[158:161], v[40:43]
	v_mfma_f32_16x16x32_bf16 v[32:35], v[194:197], v[166:169], v[32:35]
	v_mfma_f32_16x16x32_bf16 v[24:27], v[202:205], v[166:169], v[24:27]
	v_mfma_f32_16x16x32_bf16 v[16:19], v[194:197], v[174:177], v[16:19]
	v_mfma_f32_16x16x32_bf16 v[8:11], v[202:205], v[174:177], v[8:11]
	v_mfma_f32_16x16x32_bf16 v[4:7], v[194:197], v[182:185], v[4:7]
	v_mfma_f32_16x16x32_bf16 v[0:3], v[202:205], v[182:185], v[0:3]
	v_mfma_f32_16x16x32_bf16 v[48:51], v[198:201], v[162:165], v[48:51]
	v_mfma_f32_16x16x32_bf16 v[40:43], v[206:209], v[162:165], v[40:43]
	v_mfma_f32_16x16x32_bf16 v[32:35], v[198:201], v[170:173], v[32:35]
	v_mfma_f32_16x16x32_bf16 v[24:27], v[206:209], v[170:173], v[24:27]
	v_mfma_f32_16x16x32_bf16 v[16:19], v[198:201], v[178:181], v[16:19]
	v_mfma_f32_16x16x32_bf16 v[8:11], v[206:209], v[178:181], v[8:11]
	v_mfma_f32_16x16x32_bf16 v[4:7], v[198:201], v[186:189], v[4:7]
	v_mfma_f32_16x16x32_bf16 v[0:3], v[206:209], v[186:189], v[0:3]
	s_add_i32 s54, s54, 2
	s_cmp_gt_u32 s54, 5
	s_mov_b64 s[2:3], s[4:5]
	s_barrier
	s_cbranch_scc0 .LBB0_106
	s_lshl_b64 s[2:3], s[10:11], 23
	s_add_u32 s2, s26, s2
	s_addc_u32 s3, s27, s3
	s_add_u32 s2, s2, 0x2e00400
	s_addc_u32 s3, s3, 0
	v_and_b32_e32 v128, 63, v138
	s_lshl_b32 s4, s38, 8
	v_mov_b32 v128, v128
	s_add_i32 s52, s52, s4
	v_and_or_b32 v130, v128, 15, s52
	s_lshl_b32 s4, s37, 8
	v_ashrrev_i32_e32 v128, 1, v128
	s_or_b32 s4, s53, s4
	v_and_b32_e32 v128, -8, v128
	v_add_u32_e32 v128, s4, v128
	v_ashrrev_i32_e32 v131, 31, v130
	v_ashrrev_i32_e32 v129, 31, v128
	v_lshlrev_b64 v[132:133], 12, v[130:131]
	v_lshl_add_u64 v[132:133], s[2:3], 0, v[132:133]
	v_lshlrev_b64 v[134:135], 1, v[128:129]
	v_lshl_add_u64 v[128:129], v[132:133], 0, v[134:135]
	v_cvt_pk_bf16_f32 v124, v124, v125
	v_cvt_pk_bf16_f32 v125, v126, v127
	v_cvt_pk_bf16_f32 v126, v120, v121
	v_cvt_pk_bf16_f32 v127, v122, v123
	global_store_dwordx4 v[128:129], v[124:127], off
	v_cvt_pk_bf16_f32 v112, v112, v113
	v_cvt_pk_bf16_f32 v113, v114, v115
	v_cvt_pk_bf16_f32 v114, v104, v105
	v_or_b32_e32 v104, 16, v130
	v_ashrrev_i32_e32 v105, 31, v104
	v_lshlrev_b64 v[104:105], 12, v[104:105]
	v_lshl_add_u64 v[104:105], s[2:3], 0, v[104:105]
	v_cvt_pk_bf16_f32 v115, v106, v107
	global_store_dwordx4 v[128:129], v[112:115], off offset:256
	s_cmpk_lt_u32 s36, 0x100
	s_nop 0
	v_lshl_add_u64 v[112:113], v[104:105], 0, v[134:135]
	v_cvt_pk_bf16_f32 v104, v116, v117
	v_cvt_pk_bf16_f32 v105, v118, v119
	v_cvt_pk_bf16_f32 v106, v108, v109
	v_cvt_pk_bf16_f32 v107, v110, v111
	global_store_dwordx4 v[112:113], v[104:107], off
	v_cvt_pk_bf16_f32 v96, v96, v97
	v_cvt_pk_bf16_f32 v97, v98, v99
	v_cvt_pk_bf16_f32 v98, v88, v89
	v_or_b32_e32 v88, 32, v130
	v_ashrrev_i32_e32 v89, 31, v88
	v_lshlrev_b64 v[88:89], 12, v[88:89]
	v_lshl_add_u64 v[88:89], s[2:3], 0, v[88:89]
	v_cvt_pk_bf16_f32 v99, v90, v91
	global_store_dwordx4 v[112:113], v[96:99], off offset:256
	s_nop 1
	v_lshl_add_u64 v[96:97], v[88:89], 0, v[134:135]
	v_cvt_pk_bf16_f32 v88, v100, v101
	v_cvt_pk_bf16_f32 v89, v102, v103
	v_cvt_pk_bf16_f32 v90, v92, v93
	v_cvt_pk_bf16_f32 v91, v94, v95
	global_store_dwordx4 v[96:97], v[88:91], off
	v_cvt_pk_bf16_f32 v80, v80, v81
	v_cvt_pk_bf16_f32 v81, v82, v83
	v_cvt_pk_bf16_f32 v82, v72, v73
	v_or_b32_e32 v72, 48, v130
	v_ashrrev_i32_e32 v73, 31, v72
	v_lshlrev_b64 v[72:73], 12, v[72:73]
	v_lshl_add_u64 v[72:73], s[2:3], 0, v[72:73]
	v_cvt_pk_bf16_f32 v83, v74, v75
	global_store_dwordx4 v[96:97], v[80:83], off offset:256
	s_mov_b64 s[2:3], 0x80000
	s_nop 0
	v_lshl_add_u64 v[80:81], v[72:73], 0, v[134:135]
	v_cvt_pk_bf16_f32 v72, v84, v85
	v_cvt_pk_bf16_f32 v73, v86, v87
	v_cvt_pk_bf16_f32 v74, v76, v77
	v_cvt_pk_bf16_f32 v75, v78, v79
	global_store_dwordx4 v[80:81], v[72:75], off
	v_cvt_pk_bf16_f32 v68, v68, v69
	v_cvt_pk_bf16_f32 v69, v70, v71
	v_cvt_pk_bf16_f32 v70, v64, v65
	v_lshl_add_u64 v[64:65], v[128:129], 0, s[2:3]
	s_mov_b32 s2, 0x80000
	v_cvt_pk_bf16_f32 v71, v66, v67
	global_store_dwordx4 v[80:81], v[68:71], off offset:256
	v_cvt_pk_bf16_f32 v60, v60, v61
	v_cvt_pk_bf16_f32 v61, v62, v63
	v_cvt_pk_bf16_f32 v62, v56, v57
	v_add_co_u32_e32 v56, vcc, s2, v128
	v_cvt_pk_bf16_f32 v63, v58, v59
	s_mov_b64 s[2:3], 0x90000
	s_nop 0
	v_addc_co_u32_e32 v57, vcc, 0, v129, vcc
	global_store_dwordx4 v[56:57], v[60:63], off
	v_cvt_pk_bf16_f32 v48, v48, v49
	v_cvt_pk_bf16_f32 v49, v50, v51
	v_cvt_pk_bf16_f32 v50, v40, v41
	v_cvt_pk_bf16_f32 v51, v42, v43
	global_store_dwordx4 v[64:65], v[48:51], off offset:256
	v_cvt_pk_bf16_f32 v40, v52, v53
	v_cvt_pk_bf16_f32 v41, v54, v55
	v_cvt_pk_bf16_f32 v42, v44, v45
	v_cvt_pk_bf16_f32 v43, v46, v47
	s_nop 1
	v_lshl_add_u64 v[48:49], v[128:129], 0, s[2:3]
	s_mov_b32 s2, 0x90000
	v_add_co_u32_e32 v44, vcc, s2, v128
	s_mov_b64 s[2:3], 0xa0000
	s_nop 0
	v_addc_co_u32_e32 v45, vcc, 0, v129, vcc
	global_store_dwordx4 v[44:45], v[40:43], off
	v_cvt_pk_bf16_f32 v32, v32, v33
	v_cvt_pk_bf16_f32 v33, v34, v35
	v_cvt_pk_bf16_f32 v34, v24, v25
	v_cvt_pk_bf16_f32 v35, v26, v27
	global_store_dwordx4 v[48:49], v[32:35], off offset:256
	v_cvt_pk_bf16_f32 v24, v36, v37
	v_cvt_pk_bf16_f32 v25, v38, v39
	v_cvt_pk_bf16_f32 v26, v28, v29
	v_cvt_pk_bf16_f32 v27, v30, v31
	s_nop 1
	v_lshl_add_u64 v[32:33], v[128:129], 0, s[2:3]
	s_mov_b32 s2, 0xa0000
	v_add_co_u32_e32 v28, vcc, s2, v128
	s_mov_b64 s[2:3], 0xb0000
	s_nop 0
	v_addc_co_u32_e32 v29, vcc, 0, v129, vcc
	global_store_dwordx4 v[28:29], v[24:27], off
	v_cvt_pk_bf16_f32 v16, v16, v17
	v_cvt_pk_bf16_f32 v17, v18, v19
	v_cvt_pk_bf16_f32 v18, v8, v9
	v_cvt_pk_bf16_f32 v19, v10, v11
	global_store_dwordx4 v[32:33], v[16:19], off offset:256
	v_cvt_pk_bf16_f32 v8, v20, v21
	v_cvt_pk_bf16_f32 v9, v22, v23
	v_cvt_pk_bf16_f32 v10, v12, v13
	v_cvt_pk_bf16_f32 v11, v14, v15
	s_nop 1
	v_lshl_add_u64 v[16:17], v[128:129], 0, s[2:3]
	s_mov_b32 s2, 0xb0000
	v_add_co_u32_e32 v12, vcc, s2, v128
	s_nop 1
	v_addc_co_u32_e32 v13, vcc, 0, v129, vcc
	global_store_dwordx4 v[12:13], v[8:11], off
	v_cvt_pk_bf16_f32 v4, v4, v5
	v_cvt_pk_bf16_f32 v5, v6, v7
	v_cvt_pk_bf16_f32 v6, v0, v1
	v_cvt_pk_bf16_f32 v7, v2, v3
	global_store_dwordx4 v[16:17], v[4:7], off offset:256
	s_waitcnt vmcnt(0)
	s_cbranch_scc0 .LBB0_102
	s_barrier
	s_branch .LBB0_102

.LBB0_132:
	v_add_u32_e32 v138, 0x10000, v141
	ds_read_b128 v[144:147], v138
	ds_read_b128 v[148:151], v138 offset:1024
	ds_read_b128 v[152:155], v138 offset:2048
	ds_read_b128 v[156:159], v138 offset:3072
	ds_read_b128 v[160:163], v142
	ds_read_b128 v[164:167], v142 offset:1024
	ds_read_b128 v[168:171], v142 offset:2048
	ds_read_b128 v[172:175], v142 offset:3072
	ds_read_b128 v[176:179], v142 offset:4096
	ds_read_b128 v[180:183], v142 offset:5120
	ds_read_b128 v[184:187], v142 offset:6144
	ds_read_b128 v[188:191], v142 offset:7168
	v_add_u32_e32 v138, 0x14000, v141
	ds_read_b128 v[194:197], v138
	ds_read_b128 v[198:201], v138 offset:1024
	ds_read_b128 v[202:205], v138 offset:2048
	ds_read_b128 v[206:209], v138 offset:3072
	s_add_i32 s71, s4, 2
	s_add_u32 s5, s2, 0xfff80080
	s_addc_u32 s9, s3, -1
	s_add_i32 s46, 0, 0x10000
	s_cmp_eq_u32 s64, s4
	s_cselect_b32 s4, s28, s67
	s_cselect_b32 s35, s13, s9
	s_cselect_b32 s34, s12, s5
	s_cselect_b32 s5, s29, s69
	v_lshl_add_u64 v[138:139], s[2:3], 0, v[134:135]
	s_add_i32 m0, s40, 0xc000
	s_nop 0
	global_load_lds_dwordx4 v[138:139], off
	v_lshl_add_u64 v[138:139], s[2:3], 0, v[136:137]
	s_add_i32 m0, s40, 0xe000
	s_nop 0
	global_load_lds_dwordx4 v[138:139], off
	s_waitcnt vmcnt(8)
	s_waitcnt lgkmcnt(0)
	s_barrier
	v_mfma_f32_16x16x32_bf16 v[124:127], v[144:147], v[160:163], v[124:127]
	v_mfma_f32_16x16x32_bf16 v[120:123], v[152:155], v[160:163], v[120:123]
	v_mfma_f32_16x16x32_bf16 v[116:119], v[144:147], v[168:171], v[116:119]
	v_mfma_f32_16x16x32_bf16 v[108:111], v[152:155], v[168:171], v[108:111]
	v_mfma_f32_16x16x32_bf16 v[100:103], v[144:147], v[176:179], v[100:103]
	v_mfma_f32_16x16x32_bf16 v[92:95], v[152:155], v[176:179], v[92:95]
	v_mfma_f32_16x16x32_bf16 v[84:87], v[144:147], v[184:187], v[84:87]
	v_mfma_f32_16x16x32_bf16 v[76:79], v[152:155], v[184:187], v[76:79]
	v_mfma_f32_16x16x32_bf16 v[124:127], v[148:151], v[164:167], v[124:127]
	v_mfma_f32_16x16x32_bf16 v[120:123], v[156:159], v[164:167], v[120:123]
	v_mfma_f32_16x16x32_bf16 v[116:119], v[148:151], v[172:175], v[116:119]
	v_mfma_f32_16x16x32_bf16 v[108:111], v[156:159], v[172:175], v[108:111]
	v_mfma_f32_16x16x32_bf16 v[100:103], v[148:151], v[180:183], v[100:103]
	v_mfma_f32_16x16x32_bf16 v[92:95], v[156:159], v[180:183], v[92:95]
	v_mfma_f32_16x16x32_bf16 v[84:87], v[148:151], v[188:191], v[84:87]
	v_mfma_f32_16x16x32_bf16 v[76:79], v[156:159], v[188:191], v[76:79]
	v_mfma_f32_16x16x32_bf16 v[112:115], v[194:197], v[160:163], v[112:115]
	v_mfma_f32_16x16x32_bf16 v[104:107], v[202:205], v[160:163], v[104:107]
	v_mfma_f32_16x16x32_bf16 v[96:99], v[194:197], v[168:171], v[96:99]
	v_mfma_f32_16x16x32_bf16 v[88:91], v[202:205], v[168:171], v[88:91]
	v_mfma_f32_16x16x32_bf16 v[80:83], v[194:197], v[176:179], v[80:83]
	v_mfma_f32_16x16x32_bf16 v[72:75], v[202:205], v[176:179], v[72:75]
	v_mfma_f32_16x16x32_bf16 v[68:71], v[194:197], v[184:187], v[68:71]
	v_mfma_f32_16x16x32_bf16 v[64:67], v[202:205], v[184:187], v[64:67]
	v_mfma_f32_16x16x32_bf16 v[112:115], v[198:201], v[164:167], v[112:115]
	v_mfma_f32_16x16x32_bf16 v[104:107], v[206:209], v[164:167], v[104:107]
	v_mfma_f32_16x16x32_bf16 v[96:99], v[198:201], v[172:175], v[96:99]
	v_mfma_f32_16x16x32_bf16 v[88:91], v[206:209], v[172:175], v[88:91]
	v_mfma_f32_16x16x32_bf16 v[80:83], v[198:201], v[180:183], v[80:83]
	v_mfma_f32_16x16x32_bf16 v[72:75], v[206:209], v[180:183], v[72:75]
	v_mfma_f32_16x16x32_bf16 v[68:71], v[198:201], v[188:191], v[68:71]
	v_mfma_f32_16x16x32_bf16 v[64:67], v[206:209], v[188:191], v[64:67]
	s_barrier
	ds_read_b128 v[160:163], v142 offset:16384
	ds_read_b128 v[164:167], v142 offset:17408
	ds_read_b128 v[168:171], v142 offset:18432
	ds_read_b128 v[172:175], v142 offset:19456
	ds_read_b128 v[176:179], v142 offset:20480
	ds_read_b128 v[180:183], v142 offset:21504
	ds_read_b128 v[184:187], v142 offset:22528
	ds_read_b128 v[188:191], v142 offset:23552
	s_add_i32 s9, 0, 0x14000
	s_add_i32 s46, s46, s39
	v_lshl_add_u64 v[138:139], s[4:5], 0, v[192:193]
	s_mov_b32 m0, s46
	v_lshl_add_u64 v[210:211], s[4:5], 0, v[132:133]
	global_load_lds_dwordx4 v[138:139], off
	s_add_i32 m0, s46, 0x2000
	s_nop 0
	global_load_lds_dwordx4 v[210:211], off
	s_mov_b32 m0, s40
	v_lshl_add_u64 v[212:213], s[34:35], 0, v[128:129]
	global_load_lds_dwordx4 v[212:213], off
	v_lshl_add_u64 v[214:215], s[34:35], 0, v[130:131]
	s_mov_b32 m0, s41
	s_nop 0
	global_load_lds_dwordx4 v[214:215], off
	s_add_u32 s46, s4, 0x80000
	s_addc_u32 s47, s5, 0
	s_add_i32 s9, s9, s39
	v_lshl_add_u64 v[218:219], s[46:47], 0, v[192:193]
	s_mov_b32 m0, s9
	s_nop 0
	global_load_lds_dwordx4 v[218:219], off
	v_lshl_add_u64 v[220:221], s[46:47], 0, v[132:133]
	s_add_i32 m0, s9, 0x2000
	s_nop 0
	global_load_lds_dwordx4 v[220:221], off
	s_waitcnt vmcnt(8)
	s_waitcnt lgkmcnt(0)
	s_barrier
	v_mfma_f32_16x16x32_bf16 v[60:63], v[144:147], v[160:163], v[60:63]
	v_mfma_f32_16x16x32_bf16 v[56:59], v[152:155], v[160:163], v[56:59]
	v_mfma_f32_16x16x32_bf16 v[52:55], v[144:147], v[168:171], v[52:55]
	v_mfma_f32_16x16x32_bf16 v[44:47], v[152:155], v[168:171], v[44:47]
	v_mfma_f32_16x16x32_bf16 v[36:39], v[144:147], v[176:179], v[36:39]
	v_mfma_f32_16x16x32_bf16 v[28:31], v[152:155], v[176:179], v[28:31]
	v_mfma_f32_16x16x32_bf16 v[20:23], v[144:147], v[184:187], v[20:23]
	v_mfma_f32_16x16x32_bf16 v[12:15], v[152:155], v[184:187], v[12:15]
	v_mfma_f32_16x16x32_bf16 v[60:63], v[148:151], v[164:167], v[60:63]
	v_mfma_f32_16x16x32_bf16 v[56:59], v[156:159], v[164:167], v[56:59]
	v_mfma_f32_16x16x32_bf16 v[52:55], v[148:151], v[172:175], v[52:55]
	v_mfma_f32_16x16x32_bf16 v[44:47], v[156:159], v[172:175], v[44:47]
	v_mfma_f32_16x16x32_bf16 v[36:39], v[148:151], v[180:183], v[36:39]
	v_mfma_f32_16x16x32_bf16 v[28:31], v[156:159], v[180:183], v[28:31]
	v_mfma_f32_16x16x32_bf16 v[20:23], v[148:151], v[188:191], v[20:23]
	v_mfma_f32_16x16x32_bf16 v[12:15], v[156:159], v[188:191], v[12:15]
	v_mfma_f32_16x16x32_bf16 v[48:51], v[194:197], v[160:163], v[48:51]
	v_mfma_f32_16x16x32_bf16 v[40:43], v[202:205], v[160:163], v[40:43]
	v_mfma_f32_16x16x32_bf16 v[32:35], v[194:197], v[168:171], v[32:35]
	v_mfma_f32_16x16x32_bf16 v[24:27], v[202:205], v[168:171], v[24:27]
	v_mfma_f32_16x16x32_bf16 v[16:19], v[194:197], v[176:179], v[16:19]
	v_mfma_f32_16x16x32_bf16 v[8:11], v[202:205], v[176:179], v[8:11]
	v_mfma_f32_16x16x32_bf16 v[4:7], v[194:197], v[184:187], v[4:7]
	v_mfma_f32_16x16x32_bf16 v[0:3], v[202:205], v[184:187], v[0:3]
	v_mfma_f32_16x16x32_bf16 v[48:51], v[198:201], v[164:167], v[48:51]
	v_mfma_f32_16x16x32_bf16 v[40:43], v[206:209], v[164:167], v[40:43]
	v_mfma_f32_16x16x32_bf16 v[32:35], v[198:201], v[172:175], v[32:35]
	v_mfma_f32_16x16x32_bf16 v[24:27], v[206:209], v[172:175], v[24:27]
	v_mfma_f32_16x16x32_bf16 v[16:19], v[198:201], v[180:183], v[16:19]
	v_mfma_f32_16x16x32_bf16 v[8:11], v[206:209], v[180:183], v[8:11]
	v_mfma_f32_16x16x32_bf16 v[4:7], v[198:201], v[188:191], v[4:7]
	v_mfma_f32_16x16x32_bf16 v[0:3], v[206:209], v[188:191], v[0:3]
	s_barrier
	v_add_u32_e32 v143, 0x18000, v141
	ds_read_b128 v[144:147], v143
	ds_read_b128 v[148:151], v143 offset:1024
	ds_read_b128 v[152:155], v143 offset:2048
	ds_read_b128 v[156:159], v143 offset:3072
	ds_read_b128 v[160:163], v142 offset:32768
	ds_read_b128 v[164:167], v142 offset:33792
	ds_read_b128 v[168:171], v142 offset:34816
	ds_read_b128 v[172:175], v142 offset:35840
	ds_read_b128 v[176:179], v142 offset:36864
	ds_read_b128 v[180:183], v142 offset:37888
	ds_read_b128 v[184:187], v142 offset:38912
	ds_read_b128 v[188:191], v142 offset:39936
	v_add_u32_e32 v143, 0x1c000, v141
	ds_read_b128 v[194:197], v143
	ds_read_b128 v[198:201], v143 offset:1024
	ds_read_b128 v[202:205], v143 offset:2048
	ds_read_b128 v[206:209], v143 offset:3072
	s_add_i32 s9, 0, 0x18000
	s_add_u32 s34, s34, 0x80000
	s_addc_u32 s35, s35, 0
	s_mov_b32 m0, s48
	v_lshl_add_u64 v[218:219], s[34:35], 0, v[128:129]
	global_load_lds_dwordx4 v[218:219], off
	v_lshl_add_u64 v[220:221], s[34:35], 0, v[130:131]
	s_mov_b32 m0, s49
	s_nop 0
	global_load_lds_dwordx4 v[220:221], off
	s_waitcnt vmcnt(8)
	s_waitcnt lgkmcnt(0)
	s_barrier
	v_mfma_f32_16x16x32_bf16 v[124:127], v[144:147], v[160:163], v[124:127]
	v_mfma_f32_16x16x32_bf16 v[120:123], v[152:155], v[160:163], v[120:123]
	v_mfma_f32_16x16x32_bf16 v[116:119], v[144:147], v[168:171], v[116:119]
	v_mfma_f32_16x16x32_bf16 v[108:111], v[152:155], v[168:171], v[108:111]
	v_mfma_f32_16x16x32_bf16 v[100:103], v[144:147], v[176:179], v[100:103]
	v_mfma_f32_16x16x32_bf16 v[92:95], v[152:155], v[176:179], v[92:95]
	v_mfma_f32_16x16x32_bf16 v[84:87], v[144:147], v[184:187], v[84:87]
	v_mfma_f32_16x16x32_bf16 v[76:79], v[152:155], v[184:187], v[76:79]
	v_mfma_f32_16x16x32_bf16 v[124:127], v[148:151], v[164:167], v[124:127]
	v_mfma_f32_16x16x32_bf16 v[120:123], v[156:159], v[164:167], v[120:123]
	v_mfma_f32_16x16x32_bf16 v[116:119], v[148:151], v[172:175], v[116:119]
	v_mfma_f32_16x16x32_bf16 v[108:111], v[156:159], v[172:175], v[108:111]
	v_mfma_f32_16x16x32_bf16 v[100:103], v[148:151], v[180:183], v[100:103]
	v_mfma_f32_16x16x32_bf16 v[92:95], v[156:159], v[180:183], v[92:95]
	v_mfma_f32_16x16x32_bf16 v[84:87], v[148:151], v[188:191], v[84:87]
	v_mfma_f32_16x16x32_bf16 v[76:79], v[156:159], v[188:191], v[76:79]
	v_mfma_f32_16x16x32_bf16 v[112:115], v[194:197], v[160:163], v[112:115]
	v_mfma_f32_16x16x32_bf16 v[104:107], v[202:205], v[160:163], v[104:107]
	v_mfma_f32_16x16x32_bf16 v[96:99], v[194:197], v[168:171], v[96:99]
	v_mfma_f32_16x16x32_bf16 v[88:91], v[202:205], v[168:171], v[88:91]
	v_mfma_f32_16x16x32_bf16 v[80:83], v[194:197], v[176:179], v[80:83]
	v_mfma_f32_16x16x32_bf16 v[72:75], v[202:205], v[176:179], v[72:75]
	v_mfma_f32_16x16x32_bf16 v[68:71], v[194:197], v[184:187], v[68:71]
	v_mfma_f32_16x16x32_bf16 v[64:67], v[202:205], v[184:187], v[64:67]
	v_mfma_f32_16x16x32_bf16 v[112:115], v[198:201], v[164:167], v[112:115]
	v_mfma_f32_16x16x32_bf16 v[104:107], v[206:209], v[164:167], v[104:107]
	v_mfma_f32_16x16x32_bf16 v[96:99], v[198:201], v[172:175], v[96:99]
	v_mfma_f32_16x16x32_bf16 v[88:91], v[206:209], v[172:175], v[88:91]
	v_mfma_f32_16x16x32_bf16 v[80:83], v[198:201], v[180:183], v[80:83]
	v_mfma_f32_16x16x32_bf16 v[72:75], v[206:209], v[180:183], v[72:75]
	v_mfma_f32_16x16x32_bf16 v[68:71], v[198:201], v[188:191], v[68:71]
	v_mfma_f32_16x16x32_bf16 v[64:67], v[206:209], v[188:191], v[64:67]
	s_barrier
	ds_read_b128 v[160:163], v142 offset:49152
	ds_read_b128 v[164:167], v142 offset:50176
	ds_read_b128 v[168:171], v142 offset:51200
	ds_read_b128 v[172:175], v142 offset:52224
	ds_read_b128 v[176:179], v142 offset:53248
	ds_read_b128 v[180:183], v142 offset:54272
	ds_read_b128 v[184:187], v142 offset:55296
	ds_read_b128 v[188:191], v142 offset:56320
	s_add_i32 s34, 0, 0x1c000
	s_add_i32 s9, s9, s39
	v_lshl_add_u64 v[138:139], v[138:139], 0, s[72:73]
	s_mov_b32 m0, s9
	s_nop 0
	global_load_lds_dwordx4 v[138:139], off
	v_lshl_add_u64 v[138:139], v[210:211], 0, s[72:73]
	s_add_i32 m0, s9, 0x2000
	s_nop 0
	global_load_lds_dwordx4 v[138:139], off
	s_mov_b32 m0, s50
	v_lshl_add_u64 v[138:139], v[212:213], 0, s[72:73]
	global_load_lds_dwordx4 v[138:139], off
	v_lshl_add_u64 v[138:139], v[214:215], 0, s[72:73]
	s_mov_b32 m0, s51
	s_nop 0
	global_load_lds_dwordx4 v[138:139], off
	s_add_u32 s4, s4, 0x80080
	s_addc_u32 s5, s5, 0
	s_add_i32 s9, s34, s39
	v_lshl_add_u64 v[138:139], s[4:5], 0, v[192:193]
	s_mov_b32 m0, s9
	s_nop 0
	global_load_lds_dwordx4 v[138:139], off
	v_lshl_add_u64 v[138:139], s[4:5], 0, v[132:133]
	s_add_i32 m0, s9, 0x2000
	s_nop 0
	global_load_lds_dwordx4 v[138:139], off
	s_waitcnt vmcnt(8)
	s_waitcnt lgkmcnt(0)
	s_barrier
	v_mfma_f32_16x16x32_bf16 v[60:63], v[144:147], v[160:163], v[60:63]
	v_mfma_f32_16x16x32_bf16 v[56:59], v[152:155], v[160:163], v[56:59]
	v_mfma_f32_16x16x32_bf16 v[52:55], v[144:147], v[168:171], v[52:55]
	v_mfma_f32_16x16x32_bf16 v[44:47], v[152:155], v[168:171], v[44:47]
	v_mfma_f32_16x16x32_bf16 v[36:39], v[144:147], v[176:179], v[36:39]
	v_mfma_f32_16x16x32_bf16 v[28:31], v[152:155], v[176:179], v[28:31]
	v_mfma_f32_16x16x32_bf16 v[20:23], v[144:147], v[184:187], v[20:23]
	v_mfma_f32_16x16x32_bf16 v[12:15], v[152:155], v[184:187], v[12:15]
	v_mfma_f32_16x16x32_bf16 v[60:63], v[148:151], v[164:167], v[60:63]
	v_mfma_f32_16x16x32_bf16 v[56:59], v[156:159], v[164:167], v[56:59]
	v_mfma_f32_16x16x32_bf16 v[52:55], v[148:151], v[172:175], v[52:55]
	v_mfma_f32_16x16x32_bf16 v[44:47], v[156:159], v[172:175], v[44:47]
	v_mfma_f32_16x16x32_bf16 v[36:39], v[148:151], v[180:183], v[36:39]
	v_mfma_f32_16x16x32_bf16 v[28:31], v[156:159], v[180:183], v[28:31]
	v_mfma_f32_16x16x32_bf16 v[20:23], v[148:151], v[188:191], v[20:23]
	v_mfma_f32_16x16x32_bf16 v[12:15], v[156:159], v[188:191], v[12:15]
	v_mfma_f32_16x16x32_bf16 v[48:51], v[194:197], v[160:163], v[48:51]
	v_mfma_f32_16x16x32_bf16 v[40:43], v[202:205], v[160:163], v[40:43]
	v_mfma_f32_16x16x32_bf16 v[32:35], v[194:197], v[168:171], v[32:35]
	v_mfma_f32_16x16x32_bf16 v[24:27], v[202:205], v[168:171], v[24:27]
	v_mfma_f32_16x16x32_bf16 v[16:19], v[194:197], v[176:179], v[16:19]
	v_mfma_f32_16x16x32_bf16 v[8:11], v[202:205], v[176:179], v[8:11]
	v_mfma_f32_16x16x32_bf16 v[4:7], v[194:197], v[184:187], v[4:7]
	v_mfma_f32_16x16x32_bf16 v[0:3], v[202:205], v[184:187], v[0:3]
	v_mfma_f32_16x16x32_bf16 v[48:51], v[198:201], v[164:167], v[48:51]
	v_mfma_f32_16x16x32_bf16 v[40:43], v[206:209], v[164:167], v[40:43]
	v_mfma_f32_16x16x32_bf16 v[32:35], v[198:201], v[172:175], v[32:35]
	v_mfma_f32_16x16x32_bf16 v[24:27], v[206:209], v[172:175], v[24:27]
	v_mfma_f32_16x16x32_bf16 v[16:19], v[198:201], v[180:183], v[16:19]
	v_mfma_f32_16x16x32_bf16 v[8:11], v[206:209], v[180:183], v[8:11]
	v_mfma_f32_16x16x32_bf16 v[4:7], v[198:201], v[188:191], v[4:7]
	v_mfma_f32_16x16x32_bf16 v[0:3], v[206:209], v[188:191], v[0:3]
	s_add_u32 s2, s2, 0x100
	s_addc_u32 s3, s3, 0
	s_add_u32 s67, s67, 0x100
	s_addc_u32 s69, s69, 0
	s_cmp_ge_i32 s71, s63
	s_mov_b32 s4, s71
	s_barrier
	s_cbranch_scc0 .LBB0_132
	v_sub_co_u32_e64 v138, s[2:3], s66, 1
	s_nop 0
	v_readfirstlane_b32 s64, v138
	s_lshl_b64 s[4:5], s[64:65], 22
	v_readlane_b32 s34, v252, 9
	v_readlane_b32 s35, v252, 10
	s_add_u32 s4, s34, s4
	s_addc_u32 s5, s35, s5
	s_sub_i32 s9, s62, 32
	s_and_b64 s[2:3], s[2:3], exec
	v_readlane_b32 s34, v252, 7
	s_cselect_b32 s2, s62, s9
	v_readlane_b32 s35, v252, 8
	s_cselect_b32 s5, s35, s5
	s_cselect_b32 s4, s34, s4
	s_ashr_i32 s3, s2, 31
	s_lshl_b64 s[2:3], s[2:3], 20
	s_add_u32 s2, s4, s2
	v_mov_b32 v139, v140
	s_addc_u32 s3, s5, s3
	v_ashrrev_i32_e32 v138, 1, v139
	s_lshl_b32 s4, s58, 8
	v_and_b32_e32 v138, -8, v138
	s_or_b32 s4, s4, s53
	v_add_u32_e32 v138, s4, v138
	v_and_or_b32 v144, v139, 15, s52
	v_ashrrev_i32_e32 v139, 31, v138
	v_ashrrev_i32_e32 v145, 31, v144
	v_lshl_add_u64 v[146:147], v[138:139], 1, s[2:3]
	v_lshlrev_b64 v[138:139], 12, v[144:145]
	v_lshl_add_u64 v[138:139], v[146:147], 0, v[138:139]
	v_cvt_pk_bf16_f32 v124, v124, v125
	v_cvt_pk_bf16_f32 v125, v126, v127
	v_cvt_pk_bf16_f32 v126, v120, v121
	v_cvt_pk_bf16_f32 v127, v122, v123
	global_store_dwordx4 v[138:139], v[124:127], off
	v_cvt_pk_bf16_f32 v112, v112, v113
	v_cvt_pk_bf16_f32 v113, v114, v115
	v_cvt_pk_bf16_f32 v114, v104, v105
	v_or_b32_e32 v104, 16, v144
	v_ashrrev_i32_e32 v105, 31, v104
	v_lshlrev_b64 v[104:105], 12, v[104:105]
	v_cvt_pk_bf16_f32 v115, v106, v107
	global_store_dwordx4 v[138:139], v[112:115], off offset:256
	s_mov_b64 s[2:3], 0x80000
	s_mov_b32 s58, s55
	v_lshl_add_u64 v[112:113], v[146:147], 0, v[104:105]
	v_cvt_pk_bf16_f32 v104, v116, v117
	v_cvt_pk_bf16_f32 v105, v118, v119
	v_cvt_pk_bf16_f32 v106, v108, v109
	v_cvt_pk_bf16_f32 v107, v110, v111
	global_store_dwordx4 v[112:113], v[104:107], off
	v_cvt_pk_bf16_f32 v96, v96, v97
	v_cvt_pk_bf16_f32 v97, v98, v99
	v_cvt_pk_bf16_f32 v98, v88, v89
	v_or_b32_e32 v88, 32, v144
	v_ashrrev_i32_e32 v89, 31, v88
	v_lshlrev_b64 v[88:89], 12, v[88:89]
	v_cvt_pk_bf16_f32 v99, v90, v91
	global_store_dwordx4 v[112:113], v[96:99], off offset:256
	s_mov_b32 s62, s14
	s_mov_b32 s66, s15
	v_lshl_add_u64 v[96:97], v[146:147], 0, v[88:89]
	v_cvt_pk_bf16_f32 v88, v100, v101
	v_cvt_pk_bf16_f32 v89, v102, v103
	v_cvt_pk_bf16_f32 v90, v92, v93
	v_cvt_pk_bf16_f32 v91, v94, v95
	global_store_dwordx4 v[96:97], v[88:91], off
	v_cvt_pk_bf16_f32 v80, v80, v81
	v_cvt_pk_bf16_f32 v81, v82, v83
	v_cvt_pk_bf16_f32 v82, v72, v73
	v_or_b32_e32 v72, 48, v144
	v_ashrrev_i32_e32 v73, 31, v72
	v_lshlrev_b64 v[72:73], 12, v[72:73]
	v_cvt_pk_bf16_f32 v83, v74, v75
	global_store_dwordx4 v[96:97], v[80:83], off offset:256
	s_mov_b32 s63, s59
	s_mov_b64 s[4:5], s[28:29]
	v_lshl_add_u64 v[80:81], v[146:147], 0, v[72:73]
	v_cvt_pk_bf16_f32 v72, v84, v85
	v_cvt_pk_bf16_f32 v73, v86, v87
	v_cvt_pk_bf16_f32 v74, v76, v77
	v_cvt_pk_bf16_f32 v75, v78, v79
	global_store_dwordx4 v[80:81], v[72:75], off
	v_cvt_pk_bf16_f32 v68, v68, v69
	v_cvt_pk_bf16_f32 v69, v70, v71
	v_cvt_pk_bf16_f32 v70, v64, v65
	v_lshl_add_u64 v[64:65], v[138:139], 0, s[2:3]
	s_mov_b32 s2, 0x80000
	v_cvt_pk_bf16_f32 v71, v66, v67
	global_store_dwordx4 v[80:81], v[68:71], off offset:256
	v_cvt_pk_bf16_f32 v60, v60, v61
	v_cvt_pk_bf16_f32 v61, v62, v63
	v_cvt_pk_bf16_f32 v62, v56, v57
	v_add_co_u32_e32 v56, vcc, s2, v138
	v_cvt_pk_bf16_f32 v63, v58, v59
	s_mov_b64 s[2:3], 0x90000
	s_nop 0
	v_addc_co_u32_e32 v57, vcc, 0, v139, vcc
	global_store_dwordx4 v[56:57], v[60:63], off
	v_cvt_pk_bf16_f32 v48, v48, v49
	v_cvt_pk_bf16_f32 v49, v50, v51
	v_cvt_pk_bf16_f32 v50, v40, v41
	v_cvt_pk_bf16_f32 v51, v42, v43
	global_store_dwordx4 v[64:65], v[48:51], off offset:256
	v_cvt_pk_bf16_f32 v40, v52, v53
	v_cvt_pk_bf16_f32 v41, v54, v55
	v_cvt_pk_bf16_f32 v42, v44, v45
	v_cvt_pk_bf16_f32 v43, v46, v47
	s_nop 1
	v_lshl_add_u64 v[48:49], v[138:139], 0, s[2:3]
	s_mov_b32 s2, 0x90000
	v_add_co_u32_e32 v44, vcc, s2, v138
	s_mov_b64 s[2:3], 0xa0000
	s_nop 0
	v_addc_co_u32_e32 v45, vcc, 0, v139, vcc
	global_store_dwordx4 v[44:45], v[40:43], off
	v_cvt_pk_bf16_f32 v32, v32, v33
	v_cvt_pk_bf16_f32 v33, v34, v35
	v_cvt_pk_bf16_f32 v34, v24, v25
	v_cvt_pk_bf16_f32 v35, v26, v27
	global_store_dwordx4 v[48:49], v[32:35], off offset:256
	v_cvt_pk_bf16_f32 v24, v36, v37
	v_cvt_pk_bf16_f32 v25, v38, v39
	v_cvt_pk_bf16_f32 v26, v28, v29
	v_cvt_pk_bf16_f32 v27, v30, v31
	s_nop 1
	v_lshl_add_u64 v[32:33], v[138:139], 0, s[2:3]
	s_mov_b32 s2, 0xa0000
	v_add_co_u32_e32 v28, vcc, s2, v138
	s_mov_b64 s[2:3], 0xb0000
	s_nop 0
	v_addc_co_u32_e32 v29, vcc, 0, v139, vcc
	global_store_dwordx4 v[28:29], v[24:27], off
	v_cvt_pk_bf16_f32 v16, v16, v17
	v_cvt_pk_bf16_f32 v17, v18, v19
	v_cvt_pk_bf16_f32 v18, v8, v9
	v_cvt_pk_bf16_f32 v19, v10, v11
	global_store_dwordx4 v[32:33], v[16:19], off offset:256
	v_cvt_pk_bf16_f32 v8, v20, v21
	v_cvt_pk_bf16_f32 v9, v22, v23
	v_cvt_pk_bf16_f32 v10, v12, v13
	v_cvt_pk_bf16_f32 v11, v14, v15
	s_nop 1
	v_lshl_add_u64 v[16:17], v[138:139], 0, s[2:3]
	s_mov_b32 s2, 0xb0000
	v_add_co_u32_e32 v12, vcc, s2, v138
	s_mov_b64 s[2:3], s[12:13]
	s_nop 0
	v_addc_co_u32_e32 v13, vcc, 0, v139, vcc
	s_and_b64 vcc, exec, s[0:1]
	global_store_dwordx4 v[12:13], v[8:11], off
	v_cvt_pk_bf16_f32 v4, v4, v5
	v_cvt_pk_bf16_f32 v5, v6, v7
	v_cvt_pk_bf16_f32 v6, v0, v1
	v_cvt_pk_bf16_f32 v7, v2, v3
	global_store_dwordx4 v[16:17], v[4:7], off offset:256
	s_cbranch_vccz .LBB0_122
	s_waitcnt vmcnt(0)
	s_cmpk_gt_u32 s36, 0xff
	s_cbranch_scc1 .LBB0_136
	s_barrier

.LBB0_198:
	v_add_u32_e32 v141, 0x10000, v139
	ds_read_b128 v[142:145], v141
	ds_read_b128 v[146:149], v141 offset:1024
	ds_read_b128 v[150:153], v141 offset:2048
	ds_read_b128 v[154:157], v141 offset:3072
	ds_read_b128 v[158:161], v140
	ds_read_b128 v[164:167], v140 offset:1024
	ds_read_b128 v[168:171], v140 offset:2048
	ds_read_b128 v[172:175], v140 offset:3072
	ds_read_b128 v[176:179], v140 offset:4096
	ds_read_b128 v[180:183], v140 offset:5120
	ds_read_b128 v[184:187], v140 offset:6144
	ds_read_b128 v[188:191], v140 offset:7168
	v_add_u32_e32 v141, 0x14000, v139
	ds_read_b128 v[194:197], v141
	ds_read_b128 v[198:201], v141 offset:1024
	ds_read_b128 v[202:205], v141 offset:2048
	ds_read_b128 v[206:209], v141 offset:3072
	s_add_u32 s2, s0, 0xf2ce0080
	s_addc_u32 s3, s1, -1
	s_cmp_lg_u32 vcc_lo, 4
	s_cselect_b32 s2, s2, 0
	s_cselect_b32 s3, s3, 0
	s_add_u32 s4, s16, s2
	s_addc_u32 s5, s17, s3
	s_add_i32 s9, 0, 0x10000
	s_add_u32 s2, s10, s2
	s_addc_u32 s3, s11, s3
	v_lshl_add_u64 v[218:219], v[134:135], 0, s[0:1]
	s_add_i32 m0, s49, 0xc000
	s_nop 0
	global_load_lds_dwordx4 v[218:219], off
	v_lshl_add_u64 v[220:221], v[136:137], 0, s[0:1]
	s_add_i32 m0, s49, 0xe000
	s_nop 0
	global_load_lds_dwordx4 v[220:221], off
	s_waitcnt vmcnt(8)
	s_waitcnt lgkmcnt(0)
	s_barrier
	v_mfma_f32_16x16x32_bf16 v[124:127], v[142:145], v[158:161], v[124:127]
	v_mfma_f32_16x16x32_bf16 v[120:123], v[150:153], v[158:161], v[120:123]
	v_mfma_f32_16x16x32_bf16 v[116:119], v[142:145], v[168:171], v[116:119]
	v_mfma_f32_16x16x32_bf16 v[108:111], v[150:153], v[168:171], v[108:111]
	v_mfma_f32_16x16x32_bf16 v[100:103], v[142:145], v[176:179], v[100:103]
	v_mfma_f32_16x16x32_bf16 v[92:95], v[150:153], v[176:179], v[92:95]
	v_mfma_f32_16x16x32_bf16 v[84:87], v[142:145], v[184:187], v[84:87]
	v_mfma_f32_16x16x32_bf16 v[76:79], v[150:153], v[184:187], v[76:79]
	v_mfma_f32_16x16x32_bf16 v[124:127], v[146:149], v[164:167], v[124:127]
	v_mfma_f32_16x16x32_bf16 v[120:123], v[154:157], v[164:167], v[120:123]
	v_mfma_f32_16x16x32_bf16 v[116:119], v[146:149], v[172:175], v[116:119]
	v_mfma_f32_16x16x32_bf16 v[108:111], v[154:157], v[172:175], v[108:111]
	v_mfma_f32_16x16x32_bf16 v[100:103], v[146:149], v[180:183], v[100:103]
	v_mfma_f32_16x16x32_bf16 v[92:95], v[154:157], v[180:183], v[92:95]
	v_mfma_f32_16x16x32_bf16 v[84:87], v[146:149], v[188:191], v[84:87]
	v_mfma_f32_16x16x32_bf16 v[76:79], v[154:157], v[188:191], v[76:79]
	v_mfma_f32_16x16x32_bf16 v[112:115], v[194:197], v[158:161], v[112:115]
	v_mfma_f32_16x16x32_bf16 v[104:107], v[202:205], v[158:161], v[104:107]
	v_mfma_f32_16x16x32_bf16 v[96:99], v[194:197], v[168:171], v[96:99]
	v_mfma_f32_16x16x32_bf16 v[88:91], v[202:205], v[168:171], v[88:91]
	v_mfma_f32_16x16x32_bf16 v[80:83], v[194:197], v[176:179], v[80:83]
	v_mfma_f32_16x16x32_bf16 v[72:75], v[202:205], v[176:179], v[72:75]
	v_mfma_f32_16x16x32_bf16 v[68:71], v[194:197], v[184:187], v[68:71]
	v_mfma_f32_16x16x32_bf16 v[64:67], v[202:205], v[184:187], v[64:67]
	v_mfma_f32_16x16x32_bf16 v[112:115], v[198:201], v[164:167], v[112:115]
	v_mfma_f32_16x16x32_bf16 v[104:107], v[206:209], v[164:167], v[104:107]
	v_mfma_f32_16x16x32_bf16 v[96:99], v[198:201], v[172:175], v[96:99]
	v_mfma_f32_16x16x32_bf16 v[88:91], v[206:209], v[172:175], v[88:91]
	v_mfma_f32_16x16x32_bf16 v[80:83], v[198:201], v[180:183], v[80:83]
	v_mfma_f32_16x16x32_bf16 v[72:75], v[206:209], v[180:183], v[72:75]
	v_mfma_f32_16x16x32_bf16 v[68:71], v[198:201], v[188:191], v[68:71]
	v_mfma_f32_16x16x32_bf16 v[64:67], v[206:209], v[188:191], v[64:67]
	s_barrier
	ds_read_b128 v[158:161], v140 offset:16384
	ds_read_b128 v[164:167], v140 offset:17408
	ds_read_b128 v[168:171], v140 offset:18432
	ds_read_b128 v[172:175], v140 offset:19456
	ds_read_b128 v[176:179], v140 offset:20480
	ds_read_b128 v[180:183], v140 offset:21504
	ds_read_b128 v[184:187], v140 offset:22528
	ds_read_b128 v[188:191], v140 offset:23552
	s_add_i32 vcc_hi, 0, 0x14000
	s_add_i32 s9, s9, s48
	v_lshl_add_u64 v[210:211], s[2:3], 0, v[192:193]
	s_mov_b32 m0, s9
	s_nop 0
	global_load_lds_dwordx4 v[210:211], off
	v_lshl_add_u64 v[212:213], s[2:3], 0, v[132:133]
	s_add_i32 m0, s9, 0x2000
	s_nop 0
	global_load_lds_dwordx4 v[212:213], off
	s_mov_b32 m0, s49
	v_lshl_add_u64 v[214:215], s[4:5], 0, v[128:129]
	global_load_lds_dwordx4 v[214:215], off
	v_lshl_add_u64 v[216:217], s[4:5], 0, v[130:131]
	s_mov_b32 m0, s58
	s_nop 0
	global_load_lds_dwordx4 v[216:217], off
	s_add_u32 s46, s2, 0x80000
	s_addc_u32 s47, s3, 0
	s_add_i32 s9, vcc_hi, s48
	v_lshl_add_u64 v[218:219], s[46:47], 0, v[192:193]
	s_mov_b32 m0, s9
	s_nop 0
	global_load_lds_dwordx4 v[218:219], off
	v_lshl_add_u64 v[220:221], s[46:47], 0, v[132:133]
	s_add_i32 m0, s9, 0x2000
	s_nop 0
	global_load_lds_dwordx4 v[220:221], off
	s_waitcnt vmcnt(8)
	s_waitcnt lgkmcnt(0)
	s_barrier
	v_mfma_f32_16x16x32_bf16 v[60:63], v[142:145], v[158:161], v[60:63]
	v_mfma_f32_16x16x32_bf16 v[56:59], v[150:153], v[158:161], v[56:59]
	v_mfma_f32_16x16x32_bf16 v[52:55], v[142:145], v[168:171], v[52:55]
	v_mfma_f32_16x16x32_bf16 v[44:47], v[150:153], v[168:171], v[44:47]
	v_mfma_f32_16x16x32_bf16 v[36:39], v[142:145], v[176:179], v[36:39]
	v_mfma_f32_16x16x32_bf16 v[28:31], v[150:153], v[176:179], v[28:31]
	v_mfma_f32_16x16x32_bf16 v[20:23], v[142:145], v[184:187], v[20:23]
	v_mfma_f32_16x16x32_bf16 v[12:15], v[150:153], v[184:187], v[12:15]
	v_mfma_f32_16x16x32_bf16 v[60:63], v[146:149], v[164:167], v[60:63]
	v_mfma_f32_16x16x32_bf16 v[56:59], v[154:157], v[164:167], v[56:59]
	v_mfma_f32_16x16x32_bf16 v[52:55], v[146:149], v[172:175], v[52:55]
	v_mfma_f32_16x16x32_bf16 v[44:47], v[154:157], v[172:175], v[44:47]
	v_mfma_f32_16x16x32_bf16 v[36:39], v[146:149], v[180:183], v[36:39]
	v_mfma_f32_16x16x32_bf16 v[28:31], v[154:157], v[180:183], v[28:31]
	v_mfma_f32_16x16x32_bf16 v[20:23], v[146:149], v[188:191], v[20:23]
	v_mfma_f32_16x16x32_bf16 v[12:15], v[154:157], v[188:191], v[12:15]
	v_mfma_f32_16x16x32_bf16 v[48:51], v[194:197], v[158:161], v[48:51]
	v_mfma_f32_16x16x32_bf16 v[40:43], v[202:205], v[158:161], v[40:43]
	v_mfma_f32_16x16x32_bf16 v[32:35], v[194:197], v[168:171], v[32:35]
	v_mfma_f32_16x16x32_bf16 v[24:27], v[202:205], v[168:171], v[24:27]
	v_mfma_f32_16x16x32_bf16 v[16:19], v[194:197], v[176:179], v[16:19]
	v_mfma_f32_16x16x32_bf16 v[8:11], v[202:205], v[176:179], v[8:11]
	v_mfma_f32_16x16x32_bf16 v[4:7], v[194:197], v[184:187], v[4:7]
	v_mfma_f32_16x16x32_bf16 v[0:3], v[202:205], v[184:187], v[0:3]
	v_mfma_f32_16x16x32_bf16 v[48:51], v[198:201], v[164:167], v[48:51]
	v_mfma_f32_16x16x32_bf16 v[40:43], v[206:209], v[164:167], v[40:43]
	v_mfma_f32_16x16x32_bf16 v[32:35], v[198:201], v[172:175], v[32:35]
	v_mfma_f32_16x16x32_bf16 v[24:27], v[206:209], v[172:175], v[24:27]
	v_mfma_f32_16x16x32_bf16 v[16:19], v[198:201], v[180:183], v[16:19]
	v_mfma_f32_16x16x32_bf16 v[8:11], v[206:209], v[180:183], v[8:11]
	v_mfma_f32_16x16x32_bf16 v[4:7], v[198:201], v[188:191], v[4:7]
	v_mfma_f32_16x16x32_bf16 v[0:3], v[206:209], v[188:191], v[0:3]
	s_barrier
	v_add_u32_e32 v141, 0x18000, v139
	ds_read_b128 v[142:145], v141
	ds_read_b128 v[146:149], v141 offset:1024
	ds_read_b128 v[150:153], v141 offset:2048
	ds_read_b128 v[154:157], v141 offset:3072
	ds_read_b128 v[158:161], v140 offset:32768
	ds_read_b128 v[164:167], v140 offset:33792
	ds_read_b128 v[168:171], v140 offset:34816
	ds_read_b128 v[172:175], v140 offset:35840
	ds_read_b128 v[176:179], v140 offset:36864
	ds_read_b128 v[180:183], v140 offset:37888
	ds_read_b128 v[184:187], v140 offset:38912
	ds_read_b128 v[188:191], v140 offset:39936
	v_add_u32_e32 v141, 0x1c000, v139
	ds_read_b128 v[194:197], v141
	ds_read_b128 v[198:201], v141 offset:1024
	ds_read_b128 v[202:205], v141 offset:2048
	ds_read_b128 v[206:209], v141 offset:3072
	s_add_i32 s9, 0, 0x18000
	s_add_u32 s4, s4, 0x20000
	s_addc_u32 s5, s5, 0
	s_mov_b32 m0, s59
	v_lshl_add_u64 v[218:219], s[4:5], 0, v[128:129]
	global_load_lds_dwordx4 v[218:219], off
	v_lshl_add_u64 v[220:221], s[4:5], 0, v[130:131]
	s_mov_b32 m0, s62
	s_nop 0
	global_load_lds_dwordx4 v[220:221], off
	s_waitcnt vmcnt(8)
	s_waitcnt lgkmcnt(0)
	s_barrier
	v_mfma_f32_16x16x32_bf16 v[124:127], v[142:145], v[158:161], v[124:127]
	v_mfma_f32_16x16x32_bf16 v[120:123], v[150:153], v[158:161], v[120:123]
	v_mfma_f32_16x16x32_bf16 v[116:119], v[142:145], v[168:171], v[116:119]
	v_mfma_f32_16x16x32_bf16 v[108:111], v[150:153], v[168:171], v[108:111]
	v_mfma_f32_16x16x32_bf16 v[100:103], v[142:145], v[176:179], v[100:103]
	v_mfma_f32_16x16x32_bf16 v[92:95], v[150:153], v[176:179], v[92:95]
	v_mfma_f32_16x16x32_bf16 v[84:87], v[142:145], v[184:187], v[84:87]
	v_mfma_f32_16x16x32_bf16 v[76:79], v[150:153], v[184:187], v[76:79]
	v_mfma_f32_16x16x32_bf16 v[124:127], v[146:149], v[164:167], v[124:127]
	v_mfma_f32_16x16x32_bf16 v[120:123], v[154:157], v[164:167], v[120:123]
	v_mfma_f32_16x16x32_bf16 v[116:119], v[146:149], v[172:175], v[116:119]
	v_mfma_f32_16x16x32_bf16 v[108:111], v[154:157], v[172:175], v[108:111]
	v_mfma_f32_16x16x32_bf16 v[100:103], v[146:149], v[180:183], v[100:103]
	v_mfma_f32_16x16x32_bf16 v[92:95], v[154:157], v[180:183], v[92:95]
	v_mfma_f32_16x16x32_bf16 v[84:87], v[146:149], v[188:191], v[84:87]
	v_mfma_f32_16x16x32_bf16 v[76:79], v[154:157], v[188:191], v[76:79]
	v_mfma_f32_16x16x32_bf16 v[112:115], v[194:197], v[158:161], v[112:115]
	v_mfma_f32_16x16x32_bf16 v[104:107], v[202:205], v[158:161], v[104:107]
	v_mfma_f32_16x16x32_bf16 v[96:99], v[194:197], v[168:171], v[96:99]
	v_mfma_f32_16x16x32_bf16 v[88:91], v[202:205], v[168:171], v[88:91]
	v_mfma_f32_16x16x32_bf16 v[80:83], v[194:197], v[176:179], v[80:83]
	v_mfma_f32_16x16x32_bf16 v[72:75], v[202:205], v[176:179], v[72:75]
	v_mfma_f32_16x16x32_bf16 v[68:71], v[194:197], v[184:187], v[68:71]
	v_mfma_f32_16x16x32_bf16 v[64:67], v[202:205], v[184:187], v[64:67]
	v_mfma_f32_16x16x32_bf16 v[112:115], v[198:201], v[164:167], v[112:115]
	v_mfma_f32_16x16x32_bf16 v[104:107], v[206:209], v[164:167], v[104:107]
	v_mfma_f32_16x16x32_bf16 v[96:99], v[198:201], v[172:175], v[96:99]
	v_mfma_f32_16x16x32_bf16 v[88:91], v[206:209], v[172:175], v[88:91]
	v_mfma_f32_16x16x32_bf16 v[80:83], v[198:201], v[180:183], v[80:83]
	v_mfma_f32_16x16x32_bf16 v[72:75], v[206:209], v[180:183], v[72:75]
	v_mfma_f32_16x16x32_bf16 v[68:71], v[198:201], v[188:191], v[68:71]
	v_mfma_f32_16x16x32_bf16 v[64:67], v[206:209], v[188:191], v[64:67]
	s_barrier
	ds_read_b128 v[158:161], v140 offset:49152
	ds_read_b128 v[164:167], v140 offset:50176
	ds_read_b128 v[168:171], v140 offset:51200
	ds_read_b128 v[172:175], v140 offset:52224
	ds_read_b128 v[176:179], v140 offset:53248
	ds_read_b128 v[180:183], v140 offset:54272
	ds_read_b128 v[184:187], v140 offset:55296
	ds_read_b128 v[188:191], v140 offset:56320
	s_add_i32 s4, 0, 0x1c000
	s_add_i32 s5, s9, s48
	v_lshl_add_u64 v[210:211], v[210:211], 0, s[72:73]
	s_mov_b32 m0, s5
	s_nop 0
	global_load_lds_dwordx4 v[210:211], off
	v_lshl_add_u64 v[210:211], v[212:213], 0, s[72:73]
	s_add_i32 m0, s5, 0x2000
	s_nop 0
	global_load_lds_dwordx4 v[210:211], off
	s_mov_b32 m0, s63
	v_lshl_add_u64 v[210:211], v[214:215], 0, s[72:73]
	global_load_lds_dwordx4 v[210:211], off
	v_lshl_add_u64 v[210:211], v[216:217], 0, s[72:73]
	s_mov_b32 m0, s64
	s_nop 0
	global_load_lds_dwordx4 v[210:211], off
	s_add_u32 s2, s2, 0x80080
	s_addc_u32 s3, s3, 0
	s_add_i32 s4, s4, s48
	v_lshl_add_u64 v[218:219], s[2:3], 0, v[192:193]
	s_mov_b32 m0, s4
	s_nop 0
	global_load_lds_dwordx4 v[218:219], off
	v_lshl_add_u64 v[220:221], s[2:3], 0, v[132:133]
	s_add_i32 m0, s4, 0x2000
	s_nop 0
	global_load_lds_dwordx4 v[220:221], off
	s_waitcnt vmcnt(8)
	s_waitcnt lgkmcnt(0)
	s_barrier
	v_mfma_f32_16x16x32_bf16 v[60:63], v[142:145], v[158:161], v[60:63]
	v_mfma_f32_16x16x32_bf16 v[56:59], v[150:153], v[158:161], v[56:59]
	v_mfma_f32_16x16x32_bf16 v[52:55], v[142:145], v[168:171], v[52:55]
	v_mfma_f32_16x16x32_bf16 v[44:47], v[150:153], v[168:171], v[44:47]
	v_mfma_f32_16x16x32_bf16 v[36:39], v[142:145], v[176:179], v[36:39]
	v_mfma_f32_16x16x32_bf16 v[28:31], v[150:153], v[176:179], v[28:31]
	v_mfma_f32_16x16x32_bf16 v[20:23], v[142:145], v[184:187], v[20:23]
	v_mfma_f32_16x16x32_bf16 v[12:15], v[150:153], v[184:187], v[12:15]
	v_mfma_f32_16x16x32_bf16 v[60:63], v[146:149], v[164:167], v[60:63]
	v_mfma_f32_16x16x32_bf16 v[56:59], v[154:157], v[164:167], v[56:59]
	v_mfma_f32_16x16x32_bf16 v[52:55], v[146:149], v[172:175], v[52:55]
	v_mfma_f32_16x16x32_bf16 v[44:47], v[154:157], v[172:175], v[44:47]
	v_mfma_f32_16x16x32_bf16 v[36:39], v[146:149], v[180:183], v[36:39]
	v_mfma_f32_16x16x32_bf16 v[28:31], v[154:157], v[180:183], v[28:31]
	v_mfma_f32_16x16x32_bf16 v[20:23], v[146:149], v[188:191], v[20:23]
	v_mfma_f32_16x16x32_bf16 v[12:15], v[154:157], v[188:191], v[12:15]
	v_mfma_f32_16x16x32_bf16 v[48:51], v[194:197], v[158:161], v[48:51]
	v_mfma_f32_16x16x32_bf16 v[40:43], v[202:205], v[158:161], v[40:43]
	v_mfma_f32_16x16x32_bf16 v[32:35], v[194:197], v[168:171], v[32:35]
	v_mfma_f32_16x16x32_bf16 v[24:27], v[202:205], v[168:171], v[24:27]
	v_mfma_f32_16x16x32_bf16 v[16:19], v[194:197], v[176:179], v[16:19]
	v_mfma_f32_16x16x32_bf16 v[8:11], v[202:205], v[176:179], v[8:11]
	v_mfma_f32_16x16x32_bf16 v[4:7], v[194:197], v[184:187], v[4:7]
	v_mfma_f32_16x16x32_bf16 v[0:3], v[202:205], v[184:187], v[0:3]
	v_mfma_f32_16x16x32_bf16 v[48:51], v[198:201], v[164:167], v[48:51]
	v_mfma_f32_16x16x32_bf16 v[40:43], v[206:209], v[164:167], v[40:43]
	v_mfma_f32_16x16x32_bf16 v[32:35], v[198:201], v[172:175], v[32:35]
	v_mfma_f32_16x16x32_bf16 v[24:27], v[206:209], v[172:175], v[24:27]
	v_mfma_f32_16x16x32_bf16 v[16:19], v[198:201], v[180:183], v[16:19]
	v_mfma_f32_16x16x32_bf16 v[8:11], v[206:209], v[180:183], v[8:11]
	v_mfma_f32_16x16x32_bf16 v[4:7], v[198:201], v[188:191], v[4:7]
	v_mfma_f32_16x16x32_bf16 v[0:3], v[206:209], v[188:191], v[0:3]
	s_add_i32 vcc_lo, vcc_lo, 2
	s_add_u32 s0, s0, 0x100
	s_addc_u32 s1, s1, 0
	s_cmp_gt_u32 vcc_lo, 5
	s_barrier
	s_cbranch_scc0 .LBB0_198
	v_and_b32_e32 v128, 63, v138
	v_mov_b32 v128, v128
	s_or_b32 s0, s74, s81
	v_and_or_b32 v130, v128, 15, s71
	v_ashrrev_i32_e32 v128, 1, v128
	v_and_b32_e32 v128, -8, v128
	v_add_u32_e32 v128, s0, v128
	v_ashrrev_i32_e32 v131, 31, v130
	v_ashrrev_i32_e32 v129, 31, v128
	v_lshlrev_b64 v[132:133], 12, v[130:131]
	v_lshl_add_u64 v[132:133], s[14:15], 0, v[132:133]
	v_lshlrev_b64 v[134:135], 1, v[128:129]
	v_lshl_add_u64 v[128:129], v[132:133], 0, v[134:135]
	v_cvt_pk_bf16_f32 v124, v124, v125
	v_cvt_pk_bf16_f32 v125, v126, v127
	v_cvt_pk_bf16_f32 v126, v120, v121
	v_cvt_pk_bf16_f32 v127, v122, v123
	global_store_dwordx4 v[128:129], v[124:127], off
	v_cvt_pk_bf16_f32 v112, v112, v113
	v_cvt_pk_bf16_f32 v113, v114, v115
	v_cvt_pk_bf16_f32 v114, v104, v105
	v_or_b32_e32 v104, 16, v130
	v_ashrrev_i32_e32 v105, 31, v104
	v_lshlrev_b64 v[104:105], 12, v[104:105]
	v_lshl_add_u64 v[104:105], s[14:15], 0, v[104:105]
	v_cvt_pk_bf16_f32 v115, v106, v107
	global_store_dwordx4 v[128:129], v[112:115], off offset:256
	s_mov_b64 s[0:1], 0x80000
	s_cmpk_lt_u32 s31, 0x100
	v_lshl_add_u64 v[112:113], v[104:105], 0, v[134:135]
	v_cvt_pk_bf16_f32 v104, v116, v117
	v_cvt_pk_bf16_f32 v105, v118, v119
	v_cvt_pk_bf16_f32 v106, v108, v109
	v_cvt_pk_bf16_f32 v107, v110, v111
	global_store_dwordx4 v[112:113], v[104:107], off
	v_cvt_pk_bf16_f32 v96, v96, v97
	v_cvt_pk_bf16_f32 v97, v98, v99
	v_cvt_pk_bf16_f32 v98, v88, v89
	v_or_b32_e32 v88, 32, v130
	v_ashrrev_i32_e32 v89, 31, v88
	v_lshlrev_b64 v[88:89], 12, v[88:89]
	v_lshl_add_u64 v[88:89], s[14:15], 0, v[88:89]
	v_cvt_pk_bf16_f32 v99, v90, v91
	global_store_dwordx4 v[112:113], v[96:99], off offset:256
	s_nop 1
	v_lshl_add_u64 v[96:97], v[88:89], 0, v[134:135]
	v_cvt_pk_bf16_f32 v88, v100, v101
	v_cvt_pk_bf16_f32 v89, v102, v103
	v_cvt_pk_bf16_f32 v90, v92, v93
	v_cvt_pk_bf16_f32 v91, v94, v95
	global_store_dwordx4 v[96:97], v[88:91], off
	v_cvt_pk_bf16_f32 v80, v80, v81
	v_cvt_pk_bf16_f32 v81, v82, v83
	v_cvt_pk_bf16_f32 v82, v72, v73
	v_or_b32_e32 v72, 48, v130
	v_ashrrev_i32_e32 v73, 31, v72
	v_lshlrev_b64 v[72:73], 12, v[72:73]
	v_lshl_add_u64 v[72:73], s[14:15], 0, v[72:73]
	v_cvt_pk_bf16_f32 v83, v74, v75
	global_store_dwordx4 v[96:97], v[80:83], off offset:256
	s_nop 1
	v_lshl_add_u64 v[80:81], v[72:73], 0, v[134:135]
	v_cvt_pk_bf16_f32 v72, v84, v85
	v_cvt_pk_bf16_f32 v73, v86, v87
	v_cvt_pk_bf16_f32 v74, v76, v77
	v_cvt_pk_bf16_f32 v75, v78, v79
	global_store_dwordx4 v[80:81], v[72:75], off
	v_cvt_pk_bf16_f32 v68, v68, v69
	v_cvt_pk_bf16_f32 v69, v70, v71
	v_cvt_pk_bf16_f32 v70, v64, v65
	v_lshl_add_u64 v[64:65], v[128:129], 0, s[0:1]
	s_mov_b32 s0, 0x80000
	v_cvt_pk_bf16_f32 v71, v66, v67
	global_store_dwordx4 v[80:81], v[68:71], off offset:256
	v_cvt_pk_bf16_f32 v60, v60, v61
	v_cvt_pk_bf16_f32 v61, v62, v63
	v_cvt_pk_bf16_f32 v62, v56, v57
	v_add_co_u32_e32 v56, vcc, s0, v128
	v_cvt_pk_bf16_f32 v63, v58, v59
	s_mov_b64 s[0:1], 0x90000
	s_nop 0
	v_addc_co_u32_e32 v57, vcc, 0, v129, vcc
	global_store_dwordx4 v[56:57], v[60:63], off
	v_cvt_pk_bf16_f32 v48, v48, v49
	v_cvt_pk_bf16_f32 v49, v50, v51
	v_cvt_pk_bf16_f32 v50, v40, v41
	v_cvt_pk_bf16_f32 v51, v42, v43
	global_store_dwordx4 v[64:65], v[48:51], off offset:256
	v_cvt_pk_bf16_f32 v40, v52, v53
	v_cvt_pk_bf16_f32 v41, v54, v55
	v_cvt_pk_bf16_f32 v42, v44, v45
	v_cvt_pk_bf16_f32 v43, v46, v47
	s_nop 1
	v_lshl_add_u64 v[48:49], v[128:129], 0, s[0:1]
	s_mov_b32 s0, 0x90000
	v_add_co_u32_e32 v44, vcc, s0, v128
	s_mov_b64 s[0:1], 0xa0000
	s_nop 0
	v_addc_co_u32_e32 v45, vcc, 0, v129, vcc
	global_store_dwordx4 v[44:45], v[40:43], off
	v_cvt_pk_bf16_f32 v32, v32, v33
	v_cvt_pk_bf16_f32 v33, v34, v35
	v_cvt_pk_bf16_f32 v34, v24, v25
	v_cvt_pk_bf16_f32 v35, v26, v27
	global_store_dwordx4 v[48:49], v[32:35], off offset:256
	v_cvt_pk_bf16_f32 v24, v36, v37
	v_cvt_pk_bf16_f32 v25, v38, v39
	v_cvt_pk_bf16_f32 v26, v28, v29
	v_cvt_pk_bf16_f32 v27, v30, v31
	s_nop 1
	v_lshl_add_u64 v[32:33], v[128:129], 0, s[0:1]
	s_mov_b32 s0, 0xa0000
	v_add_co_u32_e32 v28, vcc, s0, v128
	s_mov_b64 s[0:1], 0xb0000
	s_nop 0
	v_addc_co_u32_e32 v29, vcc, 0, v129, vcc
	global_store_dwordx4 v[28:29], v[24:27], off
	v_cvt_pk_bf16_f32 v16, v16, v17
	v_cvt_pk_bf16_f32 v17, v18, v19
	v_cvt_pk_bf16_f32 v18, v8, v9
	v_cvt_pk_bf16_f32 v19, v10, v11
	global_store_dwordx4 v[32:33], v[16:19], off offset:256
	v_cvt_pk_bf16_f32 v8, v20, v21
	v_cvt_pk_bf16_f32 v9, v22, v23
	v_cvt_pk_bf16_f32 v10, v12, v13
	v_cvt_pk_bf16_f32 v11, v14, v15
	s_nop 1
	v_lshl_add_u64 v[16:17], v[128:129], 0, s[0:1]
	s_mov_b32 s0, 0xb0000
	v_add_co_u32_e32 v12, vcc, s0, v128
	s_nop 1
	v_addc_co_u32_e32 v13, vcc, 0, v129, vcc
	global_store_dwordx4 v[12:13], v[8:11], off
	v_cvt_pk_bf16_f32 v4, v4, v5
	v_cvt_pk_bf16_f32 v5, v6, v7
	v_cvt_pk_bf16_f32 v6, v0, v1
	v_cvt_pk_bf16_f32 v7, v2, v3
	global_store_dwordx4 v[16:17], v[4:7], off offset:256
	s_waitcnt vmcnt(0)
	s_cbranch_scc0 .LBB0_201
	s_barrier

.LBB0_242:
	v_add_u32_e32 v138, 0x10000, v141
	ds_read_b128 v[144:147], v138
	ds_read_b128 v[148:151], v138 offset:1024
	ds_read_b128 v[152:155], v138 offset:2048
	ds_read_b128 v[156:159], v138 offset:3072
	ds_read_b128 v[160:163], v142
	ds_read_b128 v[164:167], v142 offset:1024
	ds_read_b128 v[168:171], v142 offset:2048
	ds_read_b128 v[172:175], v142 offset:3072
	ds_read_b128 v[176:179], v142 offset:4096
	ds_read_b128 v[180:183], v142 offset:5120
	ds_read_b128 v[184:187], v142 offset:6144
	ds_read_b128 v[188:191], v142 offset:7168
	v_add_u32_e32 v138, 0x14000, v141
	ds_read_b128 v[194:197], v138
	ds_read_b128 v[198:201], v138 offset:1024
	ds_read_b128 v[202:205], v138 offset:2048
	ds_read_b128 v[206:209], v138 offset:3072
	s_add_i32 s79, s4, 2
	s_add_u32 s5, s2, 0xffe00080
	s_addc_u32 s9, s3, -1
	s_add_i32 s46, 0, 0x10000
	s_cmp_eq_u32 s64, s4
	s_cselect_b32 s4, s36, s75
	s_cselect_b32 s39, s29, s9
	s_cselect_b32 s38, s28, s5
	s_cselect_b32 s5, s37, s78
	v_lshl_add_u64 v[138:139], s[2:3], 0, v[134:135]
	s_add_i32 m0, s50, 0xc000
	s_nop 0
	global_load_lds_dwordx4 v[138:139], off
	v_lshl_add_u64 v[138:139], s[2:3], 0, v[136:137]
	s_add_i32 m0, s50, 0xe000
	s_nop 0
	global_load_lds_dwordx4 v[138:139], off
	s_waitcnt vmcnt(8)
	s_waitcnt lgkmcnt(0)
	s_barrier
	v_mfma_f32_16x16x32_bf16 v[124:127], v[144:147], v[160:163], v[124:127]
	v_mfma_f32_16x16x32_bf16 v[120:123], v[152:155], v[160:163], v[120:123]
	v_mfma_f32_16x16x32_bf16 v[116:119], v[144:147], v[168:171], v[116:119]
	v_mfma_f32_16x16x32_bf16 v[108:111], v[152:155], v[168:171], v[108:111]
	v_mfma_f32_16x16x32_bf16 v[100:103], v[144:147], v[176:179], v[100:103]
	v_mfma_f32_16x16x32_bf16 v[92:95], v[152:155], v[176:179], v[92:95]
	v_mfma_f32_16x16x32_bf16 v[84:87], v[144:147], v[184:187], v[84:87]
	v_mfma_f32_16x16x32_bf16 v[76:79], v[152:155], v[184:187], v[76:79]
	v_mfma_f32_16x16x32_bf16 v[124:127], v[148:151], v[164:167], v[124:127]
	v_mfma_f32_16x16x32_bf16 v[120:123], v[156:159], v[164:167], v[120:123]
	v_mfma_f32_16x16x32_bf16 v[116:119], v[148:151], v[172:175], v[116:119]
	v_mfma_f32_16x16x32_bf16 v[108:111], v[156:159], v[172:175], v[108:111]
	v_mfma_f32_16x16x32_bf16 v[100:103], v[148:151], v[180:183], v[100:103]
	v_mfma_f32_16x16x32_bf16 v[92:95], v[156:159], v[180:183], v[92:95]
	v_mfma_f32_16x16x32_bf16 v[84:87], v[148:151], v[188:191], v[84:87]
	v_mfma_f32_16x16x32_bf16 v[76:79], v[156:159], v[188:191], v[76:79]
	v_mfma_f32_16x16x32_bf16 v[112:115], v[194:197], v[160:163], v[112:115]
	v_mfma_f32_16x16x32_bf16 v[104:107], v[202:205], v[160:163], v[104:107]
	v_mfma_f32_16x16x32_bf16 v[96:99], v[194:197], v[168:171], v[96:99]
	v_mfma_f32_16x16x32_bf16 v[88:91], v[202:205], v[168:171], v[88:91]
	v_mfma_f32_16x16x32_bf16 v[80:83], v[194:197], v[176:179], v[80:83]
	v_mfma_f32_16x16x32_bf16 v[72:75], v[202:205], v[176:179], v[72:75]
	v_mfma_f32_16x16x32_bf16 v[68:71], v[194:197], v[184:187], v[68:71]
	v_mfma_f32_16x16x32_bf16 v[64:67], v[202:205], v[184:187], v[64:67]
	v_mfma_f32_16x16x32_bf16 v[112:115], v[198:201], v[164:167], v[112:115]
	v_mfma_f32_16x16x32_bf16 v[104:107], v[206:209], v[164:167], v[104:107]
	v_mfma_f32_16x16x32_bf16 v[96:99], v[198:201], v[172:175], v[96:99]
	v_mfma_f32_16x16x32_bf16 v[88:91], v[206:209], v[172:175], v[88:91]
	v_mfma_f32_16x16x32_bf16 v[80:83], v[198:201], v[180:183], v[80:83]
	v_mfma_f32_16x16x32_bf16 v[72:75], v[206:209], v[180:183], v[72:75]
	v_mfma_f32_16x16x32_bf16 v[68:71], v[198:201], v[188:191], v[68:71]
	v_mfma_f32_16x16x32_bf16 v[64:67], v[206:209], v[188:191], v[64:67]
	s_barrier
	ds_read_b128 v[160:163], v142 offset:16384
	ds_read_b128 v[164:167], v142 offset:17408
	ds_read_b128 v[168:171], v142 offset:18432
	ds_read_b128 v[172:175], v142 offset:19456
	ds_read_b128 v[176:179], v142 offset:20480
	ds_read_b128 v[180:183], v142 offset:21504
	ds_read_b128 v[184:187], v142 offset:22528
	ds_read_b128 v[188:191], v142 offset:23552
	s_add_i32 s9, 0, 0x14000
	s_add_i32 s46, s46, s49
	v_lshl_add_u64 v[138:139], s[4:5], 0, v[192:193]
	s_mov_b32 m0, s46
	v_lshl_add_u64 v[210:211], s[4:5], 0, v[132:133]
	global_load_lds_dwordx4 v[138:139], off
	s_add_i32 m0, s46, 0x2000
	s_nop 0
	global_load_lds_dwordx4 v[210:211], off
	s_mov_b32 m0, s50
	v_lshl_add_u64 v[212:213], s[38:39], 0, v[128:129]
	global_load_lds_dwordx4 v[212:213], off
	v_lshl_add_u64 v[214:215], s[38:39], 0, v[130:131]
	s_mov_b32 m0, s51
	s_nop 0
	global_load_lds_dwordx4 v[214:215], off
	s_add_u32 s46, s4, 0x200000
	s_addc_u32 s47, s5, 0
	s_add_i32 s9, s9, s49
	v_lshl_add_u64 v[218:219], s[46:47], 0, v[192:193]
	s_mov_b32 m0, s9
	s_nop 0
	global_load_lds_dwordx4 v[218:219], off
	v_lshl_add_u64 v[220:221], s[46:47], 0, v[132:133]
	s_add_i32 m0, s9, 0x2000
	s_nop 0
	global_load_lds_dwordx4 v[220:221], off
	s_waitcnt vmcnt(8)
	s_waitcnt lgkmcnt(0)
	s_barrier
	v_mfma_f32_16x16x32_bf16 v[60:63], v[144:147], v[160:163], v[60:63]
	v_mfma_f32_16x16x32_bf16 v[56:59], v[152:155], v[160:163], v[56:59]
	v_mfma_f32_16x16x32_bf16 v[52:55], v[144:147], v[168:171], v[52:55]
	v_mfma_f32_16x16x32_bf16 v[44:47], v[152:155], v[168:171], v[44:47]
	v_mfma_f32_16x16x32_bf16 v[36:39], v[144:147], v[176:179], v[36:39]
	v_mfma_f32_16x16x32_bf16 v[28:31], v[152:155], v[176:179], v[28:31]
	v_mfma_f32_16x16x32_bf16 v[20:23], v[144:147], v[184:187], v[20:23]
	v_mfma_f32_16x16x32_bf16 v[12:15], v[152:155], v[184:187], v[12:15]
	v_mfma_f32_16x16x32_bf16 v[60:63], v[148:151], v[164:167], v[60:63]
	v_mfma_f32_16x16x32_bf16 v[56:59], v[156:159], v[164:167], v[56:59]
	v_mfma_f32_16x16x32_bf16 v[52:55], v[148:151], v[172:175], v[52:55]
	v_mfma_f32_16x16x32_bf16 v[44:47], v[156:159], v[172:175], v[44:47]
	v_mfma_f32_16x16x32_bf16 v[36:39], v[148:151], v[180:183], v[36:39]
	v_mfma_f32_16x16x32_bf16 v[28:31], v[156:159], v[180:183], v[28:31]
	v_mfma_f32_16x16x32_bf16 v[20:23], v[148:151], v[188:191], v[20:23]
	v_mfma_f32_16x16x32_bf16 v[12:15], v[156:159], v[188:191], v[12:15]
	v_mfma_f32_16x16x32_bf16 v[48:51], v[194:197], v[160:163], v[48:51]
	v_mfma_f32_16x16x32_bf16 v[40:43], v[202:205], v[160:163], v[40:43]
	v_mfma_f32_16x16x32_bf16 v[32:35], v[194:197], v[168:171], v[32:35]
	v_mfma_f32_16x16x32_bf16 v[24:27], v[202:205], v[168:171], v[24:27]
	v_mfma_f32_16x16x32_bf16 v[16:19], v[194:197], v[176:179], v[16:19]
	v_mfma_f32_16x16x32_bf16 v[8:11], v[202:205], v[176:179], v[8:11]
	v_mfma_f32_16x16x32_bf16 v[4:7], v[194:197], v[184:187], v[4:7]
	v_mfma_f32_16x16x32_bf16 v[0:3], v[202:205], v[184:187], v[0:3]
	v_mfma_f32_16x16x32_bf16 v[48:51], v[198:201], v[164:167], v[48:51]
	v_mfma_f32_16x16x32_bf16 v[40:43], v[206:209], v[164:167], v[40:43]
	v_mfma_f32_16x16x32_bf16 v[32:35], v[198:201], v[172:175], v[32:35]
	v_mfma_f32_16x16x32_bf16 v[24:27], v[206:209], v[172:175], v[24:27]
	v_mfma_f32_16x16x32_bf16 v[16:19], v[198:201], v[180:183], v[16:19]
	v_mfma_f32_16x16x32_bf16 v[8:11], v[206:209], v[180:183], v[8:11]
	v_mfma_f32_16x16x32_bf16 v[4:7], v[198:201], v[188:191], v[4:7]
	v_mfma_f32_16x16x32_bf16 v[0:3], v[206:209], v[188:191], v[0:3]
	s_barrier
	v_add_u32_e32 v143, 0x18000, v141
	ds_read_b128 v[144:147], v143
	ds_read_b128 v[148:151], v143 offset:1024
	ds_read_b128 v[152:155], v143 offset:2048
	ds_read_b128 v[156:159], v143 offset:3072
	ds_read_b128 v[160:163], v142 offset:32768
	ds_read_b128 v[164:167], v142 offset:33792
	ds_read_b128 v[168:171], v142 offset:34816
	ds_read_b128 v[172:175], v142 offset:35840
	ds_read_b128 v[176:179], v142 offset:36864
	ds_read_b128 v[180:183], v142 offset:37888
	ds_read_b128 v[184:187], v142 offset:38912
	ds_read_b128 v[188:191], v142 offset:39936
	v_add_u32_e32 v143, 0x1c000, v141
	ds_read_b128 v[194:197], v143
	ds_read_b128 v[198:201], v143 offset:1024
	ds_read_b128 v[202:205], v143 offset:2048
	ds_read_b128 v[206:209], v143 offset:3072
	s_add_i32 s9, 0, 0x18000
	s_add_u32 s38, s38, 0x200000
	s_addc_u32 s39, s39, 0
	s_mov_b32 m0, s52
	v_lshl_add_u64 v[218:219], s[38:39], 0, v[128:129]
	global_load_lds_dwordx4 v[218:219], off
	v_lshl_add_u64 v[220:221], s[38:39], 0, v[130:131]
	s_mov_b32 m0, s53
	s_nop 0
	global_load_lds_dwordx4 v[220:221], off
	s_waitcnt vmcnt(8)
	s_waitcnt lgkmcnt(0)
	s_barrier
	v_mfma_f32_16x16x32_bf16 v[124:127], v[144:147], v[160:163], v[124:127]
	v_mfma_f32_16x16x32_bf16 v[120:123], v[152:155], v[160:163], v[120:123]
	v_mfma_f32_16x16x32_bf16 v[116:119], v[144:147], v[168:171], v[116:119]
	v_mfma_f32_16x16x32_bf16 v[108:111], v[152:155], v[168:171], v[108:111]
	v_mfma_f32_16x16x32_bf16 v[100:103], v[144:147], v[176:179], v[100:103]
	v_mfma_f32_16x16x32_bf16 v[92:95], v[152:155], v[176:179], v[92:95]
	v_mfma_f32_16x16x32_bf16 v[84:87], v[144:147], v[184:187], v[84:87]
	v_mfma_f32_16x16x32_bf16 v[76:79], v[152:155], v[184:187], v[76:79]
	v_mfma_f32_16x16x32_bf16 v[124:127], v[148:151], v[164:167], v[124:127]
	v_mfma_f32_16x16x32_bf16 v[120:123], v[156:159], v[164:167], v[120:123]
	v_mfma_f32_16x16x32_bf16 v[116:119], v[148:151], v[172:175], v[116:119]
	v_mfma_f32_16x16x32_bf16 v[108:111], v[156:159], v[172:175], v[108:111]
	v_mfma_f32_16x16x32_bf16 v[100:103], v[148:151], v[180:183], v[100:103]
	v_mfma_f32_16x16x32_bf16 v[92:95], v[156:159], v[180:183], v[92:95]
	v_mfma_f32_16x16x32_bf16 v[84:87], v[148:151], v[188:191], v[84:87]
	v_mfma_f32_16x16x32_bf16 v[76:79], v[156:159], v[188:191], v[76:79]
	v_mfma_f32_16x16x32_bf16 v[112:115], v[194:197], v[160:163], v[112:115]
	v_mfma_f32_16x16x32_bf16 v[104:107], v[202:205], v[160:163], v[104:107]
	v_mfma_f32_16x16x32_bf16 v[96:99], v[194:197], v[168:171], v[96:99]
	v_mfma_f32_16x16x32_bf16 v[88:91], v[202:205], v[168:171], v[88:91]
	v_mfma_f32_16x16x32_bf16 v[80:83], v[194:197], v[176:179], v[80:83]
	v_mfma_f32_16x16x32_bf16 v[72:75], v[202:205], v[176:179], v[72:75]
	v_mfma_f32_16x16x32_bf16 v[68:71], v[194:197], v[184:187], v[68:71]
	v_mfma_f32_16x16x32_bf16 v[64:67], v[202:205], v[184:187], v[64:67]
	v_mfma_f32_16x16x32_bf16 v[112:115], v[198:201], v[164:167], v[112:115]
	v_mfma_f32_16x16x32_bf16 v[104:107], v[206:209], v[164:167], v[104:107]
	v_mfma_f32_16x16x32_bf16 v[96:99], v[198:201], v[172:175], v[96:99]
	v_mfma_f32_16x16x32_bf16 v[88:91], v[206:209], v[172:175], v[88:91]
	v_mfma_f32_16x16x32_bf16 v[80:83], v[198:201], v[180:183], v[80:83]
	v_mfma_f32_16x16x32_bf16 v[72:75], v[206:209], v[180:183], v[72:75]
	v_mfma_f32_16x16x32_bf16 v[68:71], v[198:201], v[188:191], v[68:71]
	v_mfma_f32_16x16x32_bf16 v[64:67], v[206:209], v[188:191], v[64:67]
	s_barrier
	ds_read_b128 v[160:163], v142 offset:49152
	ds_read_b128 v[164:167], v142 offset:50176
	ds_read_b128 v[168:171], v142 offset:51200
	ds_read_b128 v[172:175], v142 offset:52224
	ds_read_b128 v[176:179], v142 offset:53248
	ds_read_b128 v[180:183], v142 offset:54272
	ds_read_b128 v[184:187], v142 offset:55296
	ds_read_b128 v[188:191], v142 offset:56320
	s_add_i32 s38, 0, 0x1c000
	s_add_i32 s9, s9, s49
	v_lshl_add_u64 v[138:139], v[138:139], 0, s[72:73]
	s_mov_b32 m0, s9
	s_nop 0
	global_load_lds_dwordx4 v[138:139], off
	v_lshl_add_u64 v[138:139], v[210:211], 0, s[72:73]
	s_add_i32 m0, s9, 0x2000
	s_nop 0
	global_load_lds_dwordx4 v[138:139], off
	s_mov_b32 m0, s54
	v_lshl_add_u64 v[138:139], v[212:213], 0, s[72:73]
	global_load_lds_dwordx4 v[138:139], off
	v_lshl_add_u64 v[138:139], v[214:215], 0, s[72:73]
	s_mov_b32 m0, s55
	s_nop 0
	global_load_lds_dwordx4 v[138:139], off
	s_add_u32 s4, s4, 0x200080
	s_addc_u32 s5, s5, 0
	s_add_i32 s9, s38, s49
	v_lshl_add_u64 v[138:139], s[4:5], 0, v[192:193]
	s_mov_b32 m0, s9
	s_nop 0
	global_load_lds_dwordx4 v[138:139], off
	v_lshl_add_u64 v[138:139], s[4:5], 0, v[132:133]
	s_add_i32 m0, s9, 0x2000
	s_nop 0
	global_load_lds_dwordx4 v[138:139], off
	s_waitcnt vmcnt(8)
	s_waitcnt lgkmcnt(0)
	s_barrier
	v_mfma_f32_16x16x32_bf16 v[60:63], v[144:147], v[160:163], v[60:63]
	v_mfma_f32_16x16x32_bf16 v[56:59], v[152:155], v[160:163], v[56:59]
	v_mfma_f32_16x16x32_bf16 v[52:55], v[144:147], v[168:171], v[52:55]
	v_mfma_f32_16x16x32_bf16 v[44:47], v[152:155], v[168:171], v[44:47]
	v_mfma_f32_16x16x32_bf16 v[36:39], v[144:147], v[176:179], v[36:39]
	v_mfma_f32_16x16x32_bf16 v[28:31], v[152:155], v[176:179], v[28:31]
	v_mfma_f32_16x16x32_bf16 v[20:23], v[144:147], v[184:187], v[20:23]
	v_mfma_f32_16x16x32_bf16 v[12:15], v[152:155], v[184:187], v[12:15]
	v_mfma_f32_16x16x32_bf16 v[60:63], v[148:151], v[164:167], v[60:63]
	v_mfma_f32_16x16x32_bf16 v[56:59], v[156:159], v[164:167], v[56:59]
	v_mfma_f32_16x16x32_bf16 v[52:55], v[148:151], v[172:175], v[52:55]
	v_mfma_f32_16x16x32_bf16 v[44:47], v[156:159], v[172:175], v[44:47]
	v_mfma_f32_16x16x32_bf16 v[36:39], v[148:151], v[180:183], v[36:39]
	v_mfma_f32_16x16x32_bf16 v[28:31], v[156:159], v[180:183], v[28:31]
	v_mfma_f32_16x16x32_bf16 v[20:23], v[148:151], v[188:191], v[20:23]
	v_mfma_f32_16x16x32_bf16 v[12:15], v[156:159], v[188:191], v[12:15]
	v_mfma_f32_16x16x32_bf16 v[48:51], v[194:197], v[160:163], v[48:51]
	v_mfma_f32_16x16x32_bf16 v[40:43], v[202:205], v[160:163], v[40:43]
	v_mfma_f32_16x16x32_bf16 v[32:35], v[194:197], v[168:171], v[32:35]
	v_mfma_f32_16x16x32_bf16 v[24:27], v[202:205], v[168:171], v[24:27]
	v_mfma_f32_16x16x32_bf16 v[16:19], v[194:197], v[176:179], v[16:19]
	v_mfma_f32_16x16x32_bf16 v[8:11], v[202:205], v[176:179], v[8:11]
	v_mfma_f32_16x16x32_bf16 v[4:7], v[194:197], v[184:187], v[4:7]
	v_mfma_f32_16x16x32_bf16 v[0:3], v[202:205], v[184:187], v[0:3]
	v_mfma_f32_16x16x32_bf16 v[48:51], v[198:201], v[164:167], v[48:51]
	v_mfma_f32_16x16x32_bf16 v[40:43], v[206:209], v[164:167], v[40:43]
	v_mfma_f32_16x16x32_bf16 v[32:35], v[198:201], v[172:175], v[32:35]
	v_mfma_f32_16x16x32_bf16 v[24:27], v[206:209], v[172:175], v[24:27]
	v_mfma_f32_16x16x32_bf16 v[16:19], v[198:201], v[180:183], v[16:19]
	v_mfma_f32_16x16x32_bf16 v[8:11], v[206:209], v[180:183], v[8:11]
	v_mfma_f32_16x16x32_bf16 v[4:7], v[198:201], v[188:191], v[4:7]
	v_mfma_f32_16x16x32_bf16 v[0:3], v[206:209], v[188:191], v[0:3]
	s_add_u32 s2, s2, 0x100
	s_addc_u32 s3, s3, 0
	s_add_u32 s75, s75, 0x100
	s_addc_u32 s78, s78, 0
	s_cmp_ge_i32 s79, s71
	s_mov_b32 s4, s79
	s_barrier
	s_cbranch_scc0 .LBB0_242
	v_sub_co_u32_e64 v138, s[2:3], s74, 1
	s_nop 0
	v_readfirstlane_b32 s64, v138
	s_lshl_b64 s[4:5], s[64:65], 22
	v_readlane_b32 s38, v252, 9
	v_readlane_b32 s39, v252, 10
	s_add_u32 s4, s38, s4
	s_addc_u32 s5, s39, s5
	s_sub_i32 s9, s69, 32
	s_and_b64 s[2:3], s[2:3], exec
	v_readlane_b32 s38, v252, 7
	s_cselect_b32 s2, s69, s9
	v_readlane_b32 s39, v252, 8
	s_cselect_b32 s5, s39, s5
	s_cselect_b32 s4, s38, s4
	s_ashr_i32 s3, s2, 31
	s_lshl_b64 s[2:3], s[2:3], 20
	s_add_u32 s2, s4, s2
	v_mov_b32 v139, v140
	s_addc_u32 s3, s5, s3
	v_ashrrev_i32_e32 v138, 1, v139
	s_lshl_b32 s4, s66, 8
	v_and_b32_e32 v138, -8, v138
	s_or_b32 s4, s4, s59
	v_add_u32_e32 v138, s4, v138
	v_and_or_b32 v144, v139, 15, s58
	v_ashrrev_i32_e32 v139, 31, v138
	v_ashrrev_i32_e32 v145, 31, v144
	v_lshl_add_u64 v[146:147], v[138:139], 1, s[2:3]
	v_lshlrev_b64 v[138:139], 12, v[144:145]
	v_lshl_add_u64 v[138:139], v[146:147], 0, v[138:139]
	v_cvt_pk_bf16_f32 v124, v124, v125
	v_cvt_pk_bf16_f32 v125, v126, v127
	v_cvt_pk_bf16_f32 v126, v120, v121
	v_cvt_pk_bf16_f32 v127, v122, v123
	global_store_dwordx4 v[138:139], v[124:127], off
	v_cvt_pk_bf16_f32 v112, v112, v113
	v_cvt_pk_bf16_f32 v113, v114, v115
	v_cvt_pk_bf16_f32 v114, v104, v105
	v_or_b32_e32 v104, 16, v144
	v_ashrrev_i32_e32 v105, 31, v104
	v_lshlrev_b64 v[104:105], 12, v[104:105]
	v_cvt_pk_bf16_f32 v115, v106, v107
	global_store_dwordx4 v[138:139], v[112:115], off offset:256
	s_mov_b64 s[2:3], 0x80000
	s_mov_b32 s66, s63
	v_lshl_add_u64 v[112:113], v[146:147], 0, v[104:105]
	v_cvt_pk_bf16_f32 v104, v116, v117
	v_cvt_pk_bf16_f32 v105, v118, v119
	v_cvt_pk_bf16_f32 v106, v108, v109
	v_cvt_pk_bf16_f32 v107, v110, v111
	global_store_dwordx4 v[112:113], v[104:107], off
	v_cvt_pk_bf16_f32 v96, v96, v97
	v_cvt_pk_bf16_f32 v97, v98, v99
	v_cvt_pk_bf16_f32 v98, v88, v89
	v_or_b32_e32 v88, 32, v144
	v_ashrrev_i32_e32 v89, 31, v88
	v_lshlrev_b64 v[88:89], 12, v[88:89]
	v_cvt_pk_bf16_f32 v99, v90, v91
	global_store_dwordx4 v[112:113], v[96:99], off offset:256
	s_mov_b32 s69, s34
	s_mov_b32 s74, s35
	v_lshl_add_u64 v[96:97], v[146:147], 0, v[88:89]
	v_cvt_pk_bf16_f32 v88, v100, v101
	v_cvt_pk_bf16_f32 v89, v102, v103
	v_cvt_pk_bf16_f32 v90, v92, v93
	v_cvt_pk_bf16_f32 v91, v94, v95
	global_store_dwordx4 v[96:97], v[88:91], off
	v_cvt_pk_bf16_f32 v80, v80, v81
	v_cvt_pk_bf16_f32 v81, v82, v83
	v_cvt_pk_bf16_f32 v82, v72, v73
	v_or_b32_e32 v72, 48, v144
	v_ashrrev_i32_e32 v73, 31, v72
	v_lshlrev_b64 v[72:73], 12, v[72:73]
	v_cvt_pk_bf16_f32 v83, v74, v75
	global_store_dwordx4 v[96:97], v[80:83], off offset:256
	s_mov_b32 s71, s67
	s_mov_b64 s[4:5], s[36:37]
	v_lshl_add_u64 v[80:81], v[146:147], 0, v[72:73]
	v_cvt_pk_bf16_f32 v72, v84, v85
	v_cvt_pk_bf16_f32 v73, v86, v87
	v_cvt_pk_bf16_f32 v74, v76, v77
	v_cvt_pk_bf16_f32 v75, v78, v79
	global_store_dwordx4 v[80:81], v[72:75], off
	v_cvt_pk_bf16_f32 v68, v68, v69
	v_cvt_pk_bf16_f32 v69, v70, v71
	v_cvt_pk_bf16_f32 v70, v64, v65
	v_lshl_add_u64 v[64:65], v[138:139], 0, s[2:3]
	s_mov_b32 s2, 0x80000
	v_cvt_pk_bf16_f32 v71, v66, v67
	global_store_dwordx4 v[80:81], v[68:71], off offset:256
	v_cvt_pk_bf16_f32 v60, v60, v61
	v_cvt_pk_bf16_f32 v61, v62, v63
	v_cvt_pk_bf16_f32 v62, v56, v57
	v_add_co_u32_e32 v56, vcc, s2, v138
	v_cvt_pk_bf16_f32 v63, v58, v59
	s_mov_b64 s[2:3], 0x90000
	s_nop 0
	v_addc_co_u32_e32 v57, vcc, 0, v139, vcc
	global_store_dwordx4 v[56:57], v[60:63], off
	v_cvt_pk_bf16_f32 v48, v48, v49
	v_cvt_pk_bf16_f32 v49, v50, v51
	v_cvt_pk_bf16_f32 v50, v40, v41
	v_cvt_pk_bf16_f32 v51, v42, v43
	global_store_dwordx4 v[64:65], v[48:51], off offset:256
	v_cvt_pk_bf16_f32 v40, v52, v53
	v_cvt_pk_bf16_f32 v41, v54, v55
	v_cvt_pk_bf16_f32 v42, v44, v45
	v_cvt_pk_bf16_f32 v43, v46, v47
	s_mov_b64 s[78:79], 0x2000
	s_nop 0
	v_lshl_add_u64 v[48:49], v[138:139], 0, s[2:3]
	s_mov_b32 s2, 0x90000
	v_add_co_u32_e32 v44, vcc, s2, v138
	s_mov_b64 s[2:3], 0xa0000
	s_nop 0
	v_addc_co_u32_e32 v45, vcc, 0, v139, vcc
	global_store_dwordx4 v[44:45], v[40:43], off
	v_cvt_pk_bf16_f32 v32, v32, v33
	v_cvt_pk_bf16_f32 v33, v34, v35
	v_cvt_pk_bf16_f32 v34, v24, v25
	v_cvt_pk_bf16_f32 v35, v26, v27
	global_store_dwordx4 v[48:49], v[32:35], off offset:256
	v_cvt_pk_bf16_f32 v24, v36, v37
	v_cvt_pk_bf16_f32 v25, v38, v39
	v_cvt_pk_bf16_f32 v26, v28, v29
	v_cvt_pk_bf16_f32 v27, v30, v31
	s_nop 1
	v_lshl_add_u64 v[32:33], v[138:139], 0, s[2:3]
	s_mov_b32 s2, 0xa0000
	v_add_co_u32_e32 v28, vcc, s2, v138
	s_mov_b64 s[2:3], 0xb0000
	s_nop 0
	v_addc_co_u32_e32 v29, vcc, 0, v139, vcc
	global_store_dwordx4 v[28:29], v[24:27], off
	v_cvt_pk_bf16_f32 v16, v16, v17
	v_cvt_pk_bf16_f32 v17, v18, v19
	v_cvt_pk_bf16_f32 v18, v8, v9
	v_cvt_pk_bf16_f32 v19, v10, v11
	global_store_dwordx4 v[32:33], v[16:19], off offset:256
	v_cvt_pk_bf16_f32 v8, v20, v21
	v_cvt_pk_bf16_f32 v9, v22, v23
	v_cvt_pk_bf16_f32 v10, v12, v13
	v_cvt_pk_bf16_f32 v11, v14, v15
	s_nop 1
	v_lshl_add_u64 v[16:17], v[138:139], 0, s[2:3]
	s_mov_b32 s2, 0xb0000
	v_add_co_u32_e32 v12, vcc, s2, v138
	s_mov_b64 s[2:3], s[28:29]
	s_nop 0
	v_addc_co_u32_e32 v13, vcc, 0, v139, vcc
	s_and_b64 vcc, exec, s[14:15]
	global_store_dwordx4 v[12:13], v[8:11], off
	v_cvt_pk_bf16_f32 v4, v4, v5
	v_cvt_pk_bf16_f32 v5, v6, v7
	v_cvt_pk_bf16_f32 v6, v0, v1
	v_cvt_pk_bf16_f32 v7, v2, v3
	global_store_dwordx4 v[16:17], v[4:7], off offset:256
	s_cbranch_vccz .LBB0_232
	s_waitcnt vmcnt(0)
	s_cmpk_gt_u32 s40, 0xff
	s_cbranch_scc1 .LBB0_246
	s_barrier

.LBB0_256:
	v_add_u32_e32 v138, 0x10000, v141
	ds_read_b128 v[144:147], v138
	ds_read_b128 v[148:151], v138 offset:1024
	ds_read_b128 v[152:155], v138 offset:2048
	ds_read_b128 v[156:159], v138 offset:3072
	ds_read_b128 v[160:163], v142
	ds_read_b128 v[164:167], v142 offset:1024
	ds_read_b128 v[168:171], v142 offset:2048
	ds_read_b128 v[172:175], v142 offset:3072
	ds_read_b128 v[176:179], v142 offset:4096
	ds_read_b128 v[180:183], v142 offset:5120
	ds_read_b128 v[184:187], v142 offset:6144
	ds_read_b128 v[188:191], v142 offset:7168
	v_add_u32_e32 v138, 0x14000, v141
	ds_read_b128 v[194:197], v138
	ds_read_b128 v[198:201], v138 offset:1024
	ds_read_b128 v[202:205], v138 offset:2048
	ds_read_b128 v[206:209], v138 offset:3072
	s_add_u32 s4, s2, 0xfff80080
	s_addc_u32 s5, s3, -1
	s_add_i32 s9, 0, 0x10000
	s_cmp_eq_u32 s69, 28
	s_cselect_b32 s49, s35, s5
	s_cselect_b32 s48, s34, s4
	s_cselect_b32 s5, s37, s29
	s_cselect_b32 s4, s36, s15
	v_lshl_add_u64 v[138:139], s[2:3], 0, v[134:135]
	s_add_i32 m0, s39, 0xc000
	s_nop 0
	global_load_lds_dwordx4 v[138:139], off
	v_lshl_add_u64 v[138:139], s[2:3], 0, v[136:137]
	s_add_i32 m0, s39, 0xe000
	s_nop 0
	global_load_lds_dwordx4 v[138:139], off
	s_waitcnt vmcnt(8)
	s_waitcnt lgkmcnt(0)
	s_barrier
	v_mfma_f32_16x16x32_bf16 v[124:127], v[144:147], v[160:163], v[124:127]
	v_mfma_f32_16x16x32_bf16 v[120:123], v[152:155], v[160:163], v[120:123]
	v_mfma_f32_16x16x32_bf16 v[108:111], v[144:147], v[168:171], v[108:111]
	v_mfma_f32_16x16x32_bf16 v[104:107], v[152:155], v[168:171], v[104:107]
	v_mfma_f32_16x16x32_bf16 v[92:95], v[144:147], v[176:179], v[92:95]
	v_mfma_f32_16x16x32_bf16 v[88:91], v[152:155], v[176:179], v[88:91]
	v_mfma_f32_16x16x32_bf16 v[76:79], v[144:147], v[184:187], v[76:79]
	v_mfma_f32_16x16x32_bf16 v[72:75], v[152:155], v[184:187], v[72:75]
	v_mfma_f32_16x16x32_bf16 v[124:127], v[148:151], v[164:167], v[124:127]
	v_mfma_f32_16x16x32_bf16 v[120:123], v[156:159], v[164:167], v[120:123]
	v_mfma_f32_16x16x32_bf16 v[108:111], v[148:151], v[172:175], v[108:111]
	v_mfma_f32_16x16x32_bf16 v[104:107], v[156:159], v[172:175], v[104:107]
	v_mfma_f32_16x16x32_bf16 v[92:95], v[148:151], v[180:183], v[92:95]
	v_mfma_f32_16x16x32_bf16 v[88:91], v[156:159], v[180:183], v[88:91]
	v_mfma_f32_16x16x32_bf16 v[76:79], v[148:151], v[188:191], v[76:79]
	v_mfma_f32_16x16x32_bf16 v[72:75], v[156:159], v[188:191], v[72:75]
	v_mfma_f32_16x16x32_bf16 v[116:119], v[194:197], v[160:163], v[116:119]
	v_mfma_f32_16x16x32_bf16 v[112:115], v[202:205], v[160:163], v[112:115]
	v_mfma_f32_16x16x32_bf16 v[100:103], v[194:197], v[168:171], v[100:103]
	v_mfma_f32_16x16x32_bf16 v[96:99], v[202:205], v[168:171], v[96:99]
	v_mfma_f32_16x16x32_bf16 v[84:87], v[194:197], v[176:179], v[84:87]
	v_mfma_f32_16x16x32_bf16 v[80:83], v[202:205], v[176:179], v[80:83]
	v_mfma_f32_16x16x32_bf16 v[68:71], v[194:197], v[184:187], v[68:71]
	v_mfma_f32_16x16x32_bf16 v[64:67], v[202:205], v[184:187], v[64:67]
	v_mfma_f32_16x16x32_bf16 v[116:119], v[198:201], v[164:167], v[116:119]
	v_mfma_f32_16x16x32_bf16 v[112:115], v[206:209], v[164:167], v[112:115]
	v_mfma_f32_16x16x32_bf16 v[100:103], v[198:201], v[172:175], v[100:103]
	v_mfma_f32_16x16x32_bf16 v[96:99], v[206:209], v[172:175], v[96:99]
	v_mfma_f32_16x16x32_bf16 v[84:87], v[198:201], v[180:183], v[84:87]
	v_mfma_f32_16x16x32_bf16 v[80:83], v[206:209], v[180:183], v[80:83]
	v_mfma_f32_16x16x32_bf16 v[68:71], v[198:201], v[188:191], v[68:71]
	v_mfma_f32_16x16x32_bf16 v[64:67], v[206:209], v[188:191], v[64:67]
	s_barrier
	ds_read_b128 v[160:163], v142 offset:16384
	ds_read_b128 v[164:167], v142 offset:17408
	ds_read_b128 v[168:171], v142 offset:18432
	ds_read_b128 v[172:175], v142 offset:19456
	ds_read_b128 v[176:179], v142 offset:20480
	ds_read_b128 v[180:183], v142 offset:21504
	ds_read_b128 v[184:187], v142 offset:22528
	ds_read_b128 v[188:191], v142 offset:23552
	s_add_i32 s71, 0, 0x14000
	s_add_i32 s9, s9, s50
	v_lshl_add_u64 v[138:139], s[4:5], 0, v[192:193]
	s_mov_b32 m0, s9
	v_lshl_add_u64 v[210:211], s[4:5], 0, v[128:129]
	global_load_lds_dwordx4 v[138:139], off
	s_add_i32 m0, s9, 0x2000
	s_nop 0
	global_load_lds_dwordx4 v[210:211], off
	s_mov_b32 m0, s39
	v_lshl_add_u64 v[212:213], s[48:49], 0, v[132:133]
	global_load_lds_dwordx4 v[212:213], off
	v_lshl_add_u64 v[214:215], s[48:49], 0, v[130:131]
	s_mov_b32 m0, s54
	s_nop 0
	global_load_lds_dwordx4 v[214:215], off
	s_add_u32 s46, s4, 0x80000
	s_addc_u32 s47, s5, 0
	s_add_i32 s9, s71, s50
	v_lshl_add_u64 v[218:219], s[46:47], 0, v[192:193]
	s_mov_b32 m0, s9
	s_nop 0
	global_load_lds_dwordx4 v[218:219], off
	v_lshl_add_u64 v[220:221], s[46:47], 0, v[128:129]
	s_add_i32 m0, s9, 0x2000
	s_nop 0
	global_load_lds_dwordx4 v[220:221], off
	s_waitcnt vmcnt(8)
	s_waitcnt lgkmcnt(0)
	s_barrier
	v_mfma_f32_16x16x32_bf16 v[60:63], v[144:147], v[160:163], v[60:63]
	v_mfma_f32_16x16x32_bf16 v[56:59], v[152:155], v[160:163], v[56:59]
	v_mfma_f32_16x16x32_bf16 v[44:47], v[144:147], v[168:171], v[44:47]
	v_mfma_f32_16x16x32_bf16 v[40:43], v[152:155], v[168:171], v[40:43]
	v_mfma_f32_16x16x32_bf16 v[28:31], v[144:147], v[176:179], v[28:31]
	v_mfma_f32_16x16x32_bf16 v[24:27], v[152:155], v[176:179], v[24:27]
	v_mfma_f32_16x16x32_bf16 v[12:15], v[144:147], v[184:187], v[12:15]
	v_mfma_f32_16x16x32_bf16 v[8:11], v[152:155], v[184:187], v[8:11]
	v_mfma_f32_16x16x32_bf16 v[60:63], v[148:151], v[164:167], v[60:63]
	v_mfma_f32_16x16x32_bf16 v[56:59], v[156:159], v[164:167], v[56:59]
	v_mfma_f32_16x16x32_bf16 v[44:47], v[148:151], v[172:175], v[44:47]
	v_mfma_f32_16x16x32_bf16 v[40:43], v[156:159], v[172:175], v[40:43]
	v_mfma_f32_16x16x32_bf16 v[28:31], v[148:151], v[180:183], v[28:31]
	v_mfma_f32_16x16x32_bf16 v[24:27], v[156:159], v[180:183], v[24:27]
	v_mfma_f32_16x16x32_bf16 v[12:15], v[148:151], v[188:191], v[12:15]
	v_mfma_f32_16x16x32_bf16 v[8:11], v[156:159], v[188:191], v[8:11]
	v_mfma_f32_16x16x32_bf16 v[52:55], v[194:197], v[160:163], v[52:55]
	v_mfma_f32_16x16x32_bf16 v[48:51], v[202:205], v[160:163], v[48:51]
	v_mfma_f32_16x16x32_bf16 v[36:39], v[194:197], v[168:171], v[36:39]
	v_mfma_f32_16x16x32_bf16 v[32:35], v[202:205], v[168:171], v[32:35]
	v_mfma_f32_16x16x32_bf16 v[20:23], v[194:197], v[176:179], v[20:23]
	v_mfma_f32_16x16x32_bf16 v[16:19], v[202:205], v[176:179], v[16:19]
	v_mfma_f32_16x16x32_bf16 v[4:7], v[194:197], v[184:187], v[4:7]
	v_mfma_f32_16x16x32_bf16 v[0:3], v[202:205], v[184:187], v[0:3]
	v_mfma_f32_16x16x32_bf16 v[52:55], v[198:201], v[164:167], v[52:55]
	v_mfma_f32_16x16x32_bf16 v[48:51], v[206:209], v[164:167], v[48:51]
	v_mfma_f32_16x16x32_bf16 v[36:39], v[198:201], v[172:175], v[36:39]
	v_mfma_f32_16x16x32_bf16 v[32:35], v[206:209], v[172:175], v[32:35]
	v_mfma_f32_16x16x32_bf16 v[20:23], v[198:201], v[180:183], v[20:23]
	v_mfma_f32_16x16x32_bf16 v[16:19], v[206:209], v[180:183], v[16:19]
	v_mfma_f32_16x16x32_bf16 v[4:7], v[198:201], v[188:191], v[4:7]
	v_mfma_f32_16x16x32_bf16 v[0:3], v[206:209], v[188:191], v[0:3]
	s_barrier
	v_add_u32_e32 v143, 0x18000, v141
	ds_read_b128 v[144:147], v143
	ds_read_b128 v[148:151], v143 offset:1024
	ds_read_b128 v[152:155], v143 offset:2048
	ds_read_b128 v[156:159], v143 offset:3072
	ds_read_b128 v[160:163], v142 offset:32768
	ds_read_b128 v[164:167], v142 offset:33792
	ds_read_b128 v[168:171], v142 offset:34816
	ds_read_b128 v[172:175], v142 offset:35840
	ds_read_b128 v[176:179], v142 offset:36864
	ds_read_b128 v[180:183], v142 offset:37888
	ds_read_b128 v[184:187], v142 offset:38912
	ds_read_b128 v[188:191], v142 offset:39936
	v_add_u32_e32 v143, 0x1c000, v141
	ds_read_b128 v[194:197], v143
	ds_read_b128 v[198:201], v143 offset:1024
	ds_read_b128 v[202:205], v143 offset:2048
	ds_read_b128 v[206:209], v143 offset:3072
	s_add_i32 s9, 0, 0x18000
	s_add_u32 s46, s48, 0x80000
	s_addc_u32 s47, s49, 0
	s_mov_b32 m0, s55
	v_lshl_add_u64 v[218:219], s[46:47], 0, v[132:133]
	global_load_lds_dwordx4 v[218:219], off
	v_lshl_add_u64 v[220:221], s[46:47], 0, v[130:131]
	s_mov_b32 m0, s58
	s_nop 0
	global_load_lds_dwordx4 v[220:221], off
	s_waitcnt vmcnt(8)
	s_waitcnt lgkmcnt(0)
	s_barrier
	v_mfma_f32_16x16x32_bf16 v[124:127], v[144:147], v[160:163], v[124:127]
	v_mfma_f32_16x16x32_bf16 v[120:123], v[152:155], v[160:163], v[120:123]
	v_mfma_f32_16x16x32_bf16 v[108:111], v[144:147], v[168:171], v[108:111]
	v_mfma_f32_16x16x32_bf16 v[104:107], v[152:155], v[168:171], v[104:107]
	v_mfma_f32_16x16x32_bf16 v[92:95], v[144:147], v[176:179], v[92:95]
	v_mfma_f32_16x16x32_bf16 v[88:91], v[152:155], v[176:179], v[88:91]
	v_mfma_f32_16x16x32_bf16 v[76:79], v[144:147], v[184:187], v[76:79]
	v_mfma_f32_16x16x32_bf16 v[72:75], v[152:155], v[184:187], v[72:75]
	v_mfma_f32_16x16x32_bf16 v[124:127], v[148:151], v[164:167], v[124:127]
	v_mfma_f32_16x16x32_bf16 v[120:123], v[156:159], v[164:167], v[120:123]
	v_mfma_f32_16x16x32_bf16 v[108:111], v[148:151], v[172:175], v[108:111]
	v_mfma_f32_16x16x32_bf16 v[104:107], v[156:159], v[172:175], v[104:107]
	v_mfma_f32_16x16x32_bf16 v[92:95], v[148:151], v[180:183], v[92:95]
	v_mfma_f32_16x16x32_bf16 v[88:91], v[156:159], v[180:183], v[88:91]
	v_mfma_f32_16x16x32_bf16 v[76:79], v[148:151], v[188:191], v[76:79]
	v_mfma_f32_16x16x32_bf16 v[72:75], v[156:159], v[188:191], v[72:75]
	v_mfma_f32_16x16x32_bf16 v[116:119], v[194:197], v[160:163], v[116:119]
	v_mfma_f32_16x16x32_bf16 v[112:115], v[202:205], v[160:163], v[112:115]
	v_mfma_f32_16x16x32_bf16 v[100:103], v[194:197], v[168:171], v[100:103]
	v_mfma_f32_16x16x32_bf16 v[96:99], v[202:205], v[168:171], v[96:99]
	v_mfma_f32_16x16x32_bf16 v[84:87], v[194:197], v[176:179], v[84:87]
	v_mfma_f32_16x16x32_bf16 v[80:83], v[202:205], v[176:179], v[80:83]
	v_mfma_f32_16x16x32_bf16 v[68:71], v[194:197], v[184:187], v[68:71]
	v_mfma_f32_16x16x32_bf16 v[64:67], v[202:205], v[184:187], v[64:67]
	v_mfma_f32_16x16x32_bf16 v[116:119], v[198:201], v[164:167], v[116:119]
	v_mfma_f32_16x16x32_bf16 v[112:115], v[206:209], v[164:167], v[112:115]
	v_mfma_f32_16x16x32_bf16 v[100:103], v[198:201], v[172:175], v[100:103]
	v_mfma_f32_16x16x32_bf16 v[96:99], v[206:209], v[172:175], v[96:99]
	v_mfma_f32_16x16x32_bf16 v[84:87], v[198:201], v[180:183], v[84:87]
	v_mfma_f32_16x16x32_bf16 v[80:83], v[206:209], v[180:183], v[80:83]
	v_mfma_f32_16x16x32_bf16 v[68:71], v[198:201], v[188:191], v[68:71]
	v_mfma_f32_16x16x32_bf16 v[64:67], v[206:209], v[188:191], v[64:67]
	s_barrier
	ds_read_b128 v[160:163], v142 offset:49152
	ds_read_b128 v[164:167], v142 offset:50176
	ds_read_b128 v[168:171], v142 offset:51200
	ds_read_b128 v[172:175], v142 offset:52224
	ds_read_b128 v[176:179], v142 offset:53248
	ds_read_b128 v[180:183], v142 offset:54272
	ds_read_b128 v[184:187], v142 offset:55296
	ds_read_b128 v[188:191], v142 offset:56320
	s_add_i32 s46, 0, 0x1c000
	s_add_i32 s9, s9, s50
	v_lshl_add_u64 v[138:139], v[138:139], 0, s[72:73]
	s_mov_b32 m0, s9
	s_nop 0
	global_load_lds_dwordx4 v[138:139], off
	v_lshl_add_u64 v[138:139], v[210:211], 0, s[72:73]
	s_add_i32 m0, s9, 0x2000
	s_nop 0
	global_load_lds_dwordx4 v[138:139], off
	s_mov_b32 m0, s59
	v_lshl_add_u64 v[138:139], v[212:213], 0, s[72:73]
	global_load_lds_dwordx4 v[138:139], off
	v_lshl_add_u64 v[138:139], v[214:215], 0, s[72:73]
	s_mov_b32 m0, s62
	s_nop 0
	global_load_lds_dwordx4 v[138:139], off
	s_add_u32 s4, s4, 0x80080
	s_addc_u32 s5, s5, 0
	s_add_i32 s9, s46, s50
	v_lshl_add_u64 v[138:139], s[4:5], 0, v[192:193]
	s_mov_b32 m0, s9
	s_nop 0
	global_load_lds_dwordx4 v[138:139], off
	v_lshl_add_u64 v[138:139], s[4:5], 0, v[128:129]
	s_add_i32 m0, s9, 0x2000
	s_nop 0
	global_load_lds_dwordx4 v[138:139], off
	s_waitcnt vmcnt(8)
	s_waitcnt lgkmcnt(0)
	s_barrier
	v_mfma_f32_16x16x32_bf16 v[60:63], v[144:147], v[160:163], v[60:63]
	v_mfma_f32_16x16x32_bf16 v[56:59], v[152:155], v[160:163], v[56:59]
	v_mfma_f32_16x16x32_bf16 v[44:47], v[144:147], v[168:171], v[44:47]
	v_mfma_f32_16x16x32_bf16 v[40:43], v[152:155], v[168:171], v[40:43]
	v_mfma_f32_16x16x32_bf16 v[28:31], v[144:147], v[176:179], v[28:31]
	v_mfma_f32_16x16x32_bf16 v[24:27], v[152:155], v[176:179], v[24:27]
	v_mfma_f32_16x16x32_bf16 v[12:15], v[144:147], v[184:187], v[12:15]
	v_mfma_f32_16x16x32_bf16 v[8:11], v[152:155], v[184:187], v[8:11]
	v_mfma_f32_16x16x32_bf16 v[60:63], v[148:151], v[164:167], v[60:63]
	v_mfma_f32_16x16x32_bf16 v[56:59], v[156:159], v[164:167], v[56:59]
	v_mfma_f32_16x16x32_bf16 v[44:47], v[148:151], v[172:175], v[44:47]
	v_mfma_f32_16x16x32_bf16 v[40:43], v[156:159], v[172:175], v[40:43]
	v_mfma_f32_16x16x32_bf16 v[28:31], v[148:151], v[180:183], v[28:31]
	v_mfma_f32_16x16x32_bf16 v[24:27], v[156:159], v[180:183], v[24:27]
	v_mfma_f32_16x16x32_bf16 v[12:15], v[148:151], v[188:191], v[12:15]
	v_mfma_f32_16x16x32_bf16 v[8:11], v[156:159], v[188:191], v[8:11]
	v_mfma_f32_16x16x32_bf16 v[52:55], v[194:197], v[160:163], v[52:55]
	v_mfma_f32_16x16x32_bf16 v[48:51], v[202:205], v[160:163], v[48:51]
	v_mfma_f32_16x16x32_bf16 v[36:39], v[194:197], v[168:171], v[36:39]
	v_mfma_f32_16x16x32_bf16 v[32:35], v[202:205], v[168:171], v[32:35]
	v_mfma_f32_16x16x32_bf16 v[20:23], v[194:197], v[176:179], v[20:23]
	v_mfma_f32_16x16x32_bf16 v[16:19], v[202:205], v[176:179], v[16:19]
	v_mfma_f32_16x16x32_bf16 v[4:7], v[194:197], v[184:187], v[4:7]
	v_mfma_f32_16x16x32_bf16 v[0:3], v[202:205], v[184:187], v[0:3]
	v_mfma_f32_16x16x32_bf16 v[52:55], v[198:201], v[164:167], v[52:55]
	v_mfma_f32_16x16x32_bf16 v[48:51], v[206:209], v[164:167], v[48:51]
	v_mfma_f32_16x16x32_bf16 v[36:39], v[198:201], v[172:175], v[36:39]
	v_mfma_f32_16x16x32_bf16 v[32:35], v[206:209], v[172:175], v[32:35]
	v_mfma_f32_16x16x32_bf16 v[20:23], v[198:201], v[180:183], v[20:23]
	v_mfma_f32_16x16x32_bf16 v[16:19], v[206:209], v[180:183], v[16:19]
	v_mfma_f32_16x16x32_bf16 v[4:7], v[198:201], v[188:191], v[4:7]
	v_mfma_f32_16x16x32_bf16 v[0:3], v[206:209], v[188:191], v[0:3]
	s_add_i32 s69, s69, 2
	s_add_u32 s2, s2, 0x100
	s_addc_u32 s3, s3, 0
	s_add_u32 s15, s15, 0x100
	s_addc_u32 s29, s29, 0
	s_cmp_gt_u32 s69, 29
	s_barrier
	s_cbranch_scc0 .LBB0_256
	s_lshl_b32 s2, s38, 8
	v_mov_b32 v138, v140
	s_add_i32 s2, s2, s63
	v_and_or_b32 v144, v138, 15, s2
	s_lshl_b32 s2, s67, 8
	v_ashrrev_i32_e32 v138, 1, v138
	v_max_f32_e32 v120, v120, v120
	s_or_b32 s2, s2, s64
	v_and_b32_e32 v138, -8, v138
	v_max_f32_e32 v120, 0, v120
	v_max_f32_e32 v121, v121, v121
	v_max_f32_e32 v122, v122, v122
	v_add_u32_e32 v138, s2, v138
	v_ashrrev_i32_e32 v145, 31, v144
	v_readlane_b32 s2, v252, 63
	v_mul_f32_e32 v143, v120, v120
	v_max_f32_e32 v120, v125, v125
	v_max_f32_e32 v121, 0, v121
	v_max_f32_e32 v122, 0, v122
	v_ashrrev_i32_e32 v139, 31, v138
	v_lshlrev_b64 v[146:147], 14, v[144:145]
	v_readlane_b32 s3, v253, 0
	v_max_f32_e32 v124, v124, v124
	v_max_f32_e32 v120, 0, v120
	v_mul_f32_e32 v125, v121, v121
	v_max_f32_e32 v121, v126, v126
	v_mul_f32_e32 v126, v122, v122
	v_max_f32_e32 v122, v127, v127
	v_max_f32_e32 v123, v123, v123
	v_lshl_add_u64 v[146:147], s[2:3], 0, v[146:147]
	v_lshlrev_b64 v[148:149], 1, v[138:139]
	v_max_f32_e32 v124, 0, v124
	v_mul_f32_e32 v120, v120, v120
	v_max_f32_e32 v121, 0, v121
	v_max_f32_e32 v122, 0, v122
	v_max_f32_e32 v123, 0, v123
	v_max_f32_e32 v112, v112, v112
	v_lshl_add_u64 v[138:139], v[146:147], 0, v[148:149]
	v_mul_f32_e32 v124, v124, v124
	v_mul_f32_e32 v121, v121, v121
	v_mul_f32_e32 v122, v122, v122
	v_mul_f32_e32 v123, v123, v123
	v_cvt_pk_bf16_f32 v120, v124, v120
	v_max_f32_e32 v112, 0, v112
	v_max_f32_e32 v113, v113, v113
	v_max_f32_e32 v114, v114, v114
	v_cvt_pk_bf16_f32 v121, v121, v122
	v_cvt_pk_bf16_f32 v122, v143, v125
	v_cvt_pk_bf16_f32 v123, v126, v123
	global_store_dwordx4 v[138:139], v[120:123], off
	v_max_f32_e32 v113, 0, v113
	v_max_f32_e32 v114, 0, v114
	v_mul_f32_e32 v120, v112, v112
	v_max_f32_e32 v112, v117, v117
	v_max_f32_e32 v116, v116, v116
	v_max_f32_e32 v112, 0, v112
	v_mul_f32_e32 v117, v113, v113
	v_max_f32_e32 v113, v118, v118
	v_mul_f32_e32 v118, v114, v114
	v_max_f32_e32 v114, v119, v119
	v_max_f32_e32 v115, v115, v115
	v_max_f32_e32 v116, 0, v116
	v_mul_f32_e32 v112, v112, v112
	v_max_f32_e32 v113, 0, v113
	v_max_f32_e32 v114, 0, v114
	v_max_f32_e32 v115, 0, v115
	v_mul_f32_e32 v116, v116, v116
	v_mul_f32_e32 v113, v113, v113
	v_mul_f32_e32 v114, v114, v114
	v_mul_f32_e32 v115, v115, v115
	v_cvt_pk_bf16_f32 v112, v116, v112
	v_max_f32_e32 v104, v104, v104
	v_cvt_pk_bf16_f32 v113, v113, v114
	v_cvt_pk_bf16_f32 v114, v120, v117
	v_cvt_pk_bf16_f32 v115, v118, v115
	global_store_dwordx4 v[138:139], v[112:115], off offset:256
	v_max_f32_e32 v104, 0, v104
	v_max_f32_e32 v105, v105, v105
	v_or_b32_e32 v112, 16, v144
	v_max_f32_e32 v106, v106, v106
	v_ashrrev_i32_e32 v113, 31, v112
	v_mul_f32_e32 v114, v104, v104
	v_max_f32_e32 v104, v109, v109
	v_max_f32_e32 v105, 0, v105
	v_max_f32_e32 v106, 0, v106
	v_lshlrev_b64 v[112:113], 14, v[112:113]
	v_max_f32_e32 v108, v108, v108
	v_max_f32_e32 v104, 0, v104
	v_mul_f32_e32 v109, v105, v105
	v_max_f32_e32 v105, v110, v110
	v_mul_f32_e32 v110, v106, v106
	v_max_f32_e32 v106, v111, v111
	v_max_f32_e32 v107, v107, v107
	v_lshl_add_u64 v[112:113], s[2:3], 0, v[112:113]
	v_max_f32_e32 v108, 0, v108
	v_mul_f32_e32 v104, v104, v104
	v_max_f32_e32 v105, 0, v105
	v_max_f32_e32 v106, 0, v106
	v_max_f32_e32 v107, 0, v107
	v_max_f32_e32 v96, v96, v96
	v_lshl_add_u64 v[112:113], v[112:113], 0, v[148:149]
	v_mul_f32_e32 v108, v108, v108
	v_mul_f32_e32 v105, v105, v105
	v_mul_f32_e32 v106, v106, v106
	v_mul_f32_e32 v107, v107, v107
	v_cvt_pk_bf16_f32 v104, v108, v104
	v_max_f32_e32 v96, 0, v96
	v_max_f32_e32 v97, v97, v97
	v_max_f32_e32 v98, v98, v98
	v_cvt_pk_bf16_f32 v105, v105, v106
	v_cvt_pk_bf16_f32 v106, v114, v109
	v_cvt_pk_bf16_f32 v107, v110, v107
	global_store_dwordx4 v[112:113], v[104:107], off
	v_max_f32_e32 v97, 0, v97
	v_max_f32_e32 v98, 0, v98
	v_mul_f32_e32 v104, v96, v96
	v_max_f32_e32 v96, v101, v101
	v_max_f32_e32 v100, v100, v100
	v_max_f32_e32 v96, 0, v96
	v_mul_f32_e32 v101, v97, v97
	v_max_f32_e32 v97, v102, v102
	v_mul_f32_e32 v102, v98, v98
	v_max_f32_e32 v98, v103, v103
	v_max_f32_e32 v99, v99, v99
	v_max_f32_e32 v100, 0, v100
	v_mul_f32_e32 v96, v96, v96
	v_max_f32_e32 v97, 0, v97
	v_max_f32_e32 v98, 0, v98
	v_max_f32_e32 v99, 0, v99
	v_mul_f32_e32 v100, v100, v100
	v_mul_f32_e32 v97, v97, v97
	v_mul_f32_e32 v98, v98, v98
	v_mul_f32_e32 v99, v99, v99
	v_cvt_pk_bf16_f32 v96, v100, v96
	v_max_f32_e32 v88, v88, v88
	v_cvt_pk_bf16_f32 v97, v97, v98
	v_cvt_pk_bf16_f32 v98, v104, v101
	v_cvt_pk_bf16_f32 v99, v102, v99
	global_store_dwordx4 v[112:113], v[96:99], off offset:256
	v_max_f32_e32 v88, 0, v88
	v_max_f32_e32 v89, v89, v89
	v_or_b32_e32 v96, 32, v144
	v_max_f32_e32 v90, v90, v90
	v_ashrrev_i32_e32 v97, 31, v96
	v_mul_f32_e32 v98, v88, v88
	v_max_f32_e32 v88, v93, v93
	v_max_f32_e32 v89, 0, v89
	v_max_f32_e32 v90, 0, v90
	v_lshlrev_b64 v[96:97], 14, v[96:97]
	v_max_f32_e32 v92, v92, v92
	v_max_f32_e32 v88, 0, v88
	v_mul_f32_e32 v93, v89, v89
	v_max_f32_e32 v89, v94, v94
	v_mul_f32_e32 v94, v90, v90
	v_max_f32_e32 v90, v95, v95
	v_max_f32_e32 v91, v91, v91
	v_lshl_add_u64 v[96:97], s[2:3], 0, v[96:97]
	v_max_f32_e32 v92, 0, v92
	v_mul_f32_e32 v88, v88, v88
	v_max_f32_e32 v89, 0, v89
	v_max_f32_e32 v90, 0, v90
	v_max_f32_e32 v91, 0, v91
	v_max_f32_e32 v80, v80, v80
	v_lshl_add_u64 v[96:97], v[96:97], 0, v[148:149]
	v_mul_f32_e32 v92, v92, v92
	v_mul_f32_e32 v89, v89, v89
	v_mul_f32_e32 v90, v90, v90
	v_mul_f32_e32 v91, v91, v91
	v_cvt_pk_bf16_f32 v88, v92, v88
	v_max_f32_e32 v80, 0, v80
	v_max_f32_e32 v81, v81, v81
	v_max_f32_e32 v82, v82, v82
	v_cvt_pk_bf16_f32 v89, v89, v90
	v_cvt_pk_bf16_f32 v90, v98, v93
	v_cvt_pk_bf16_f32 v91, v94, v91
	global_store_dwordx4 v[96:97], v[88:91], off
	v_max_f32_e32 v81, 0, v81
	v_max_f32_e32 v82, 0, v82
	v_mul_f32_e32 v88, v80, v80
	v_max_f32_e32 v80, v85, v85
	v_max_f32_e32 v84, v84, v84
	v_max_f32_e32 v80, 0, v80
	v_mul_f32_e32 v85, v81, v81
	v_max_f32_e32 v81, v86, v86
	v_mul_f32_e32 v86, v82, v82
	v_max_f32_e32 v82, v87, v87
	v_max_f32_e32 v83, v83, v83
	v_max_f32_e32 v84, 0, v84
	v_mul_f32_e32 v80, v80, v80
	v_max_f32_e32 v81, 0, v81
	v_max_f32_e32 v82, 0, v82
	v_max_f32_e32 v83, 0, v83
	v_mul_f32_e32 v84, v84, v84
	v_mul_f32_e32 v81, v81, v81
	v_mul_f32_e32 v82, v82, v82
	v_mul_f32_e32 v83, v83, v83
	v_cvt_pk_bf16_f32 v80, v84, v80
	v_max_f32_e32 v72, v72, v72
	v_cvt_pk_bf16_f32 v81, v81, v82
	v_cvt_pk_bf16_f32 v82, v88, v85
	v_cvt_pk_bf16_f32 v83, v86, v83
	global_store_dwordx4 v[96:97], v[80:83], off offset:256
	v_max_f32_e32 v72, 0, v72
	v_max_f32_e32 v73, v73, v73
	v_or_b32_e32 v80, 48, v144
	v_max_f32_e32 v74, v74, v74
	v_ashrrev_i32_e32 v81, 31, v80
	v_mul_f32_e32 v82, v72, v72
	v_max_f32_e32 v72, v77, v77
	v_max_f32_e32 v73, 0, v73
	v_max_f32_e32 v74, 0, v74
	v_lshlrev_b64 v[80:81], 14, v[80:81]
	v_max_f32_e32 v76, v76, v76
	v_max_f32_e32 v72, 0, v72
	v_mul_f32_e32 v77, v73, v73
	v_max_f32_e32 v73, v78, v78
	v_mul_f32_e32 v78, v74, v74
	v_max_f32_e32 v74, v79, v79
	v_max_f32_e32 v75, v75, v75
	v_lshl_add_u64 v[80:81], s[2:3], 0, v[80:81]
	v_max_f32_e32 v76, 0, v76
	v_mul_f32_e32 v72, v72, v72
	v_max_f32_e32 v73, 0, v73
	v_max_f32_e32 v74, 0, v74
	v_max_f32_e32 v75, 0, v75
	v_max_f32_e32 v64, v64, v64
	v_max_f32_e32 v65, v65, v65
	v_max_f32_e32 v66, v66, v66
	v_lshl_add_u64 v[80:81], v[80:81], 0, v[148:149]
	v_mul_f32_e32 v76, v76, v76
	v_mul_f32_e32 v73, v73, v73
	v_mul_f32_e32 v74, v74, v74
	v_mul_f32_e32 v75, v75, v75
	v_cvt_pk_bf16_f32 v72, v76, v72
	v_max_f32_e32 v64, 0, v64
	v_max_f32_e32 v65, 0, v65
	v_max_f32_e32 v66, 0, v66
	v_cvt_pk_bf16_f32 v73, v73, v74
	v_cvt_pk_bf16_f32 v74, v82, v77
	v_cvt_pk_bf16_f32 v75, v78, v75
	global_store_dwordx4 v[80:81], v[72:75], off
	v_max_f32_e32 v68, v68, v68
	v_max_f32_e32 v67, v67, v67
	v_mul_f32_e32 v72, v64, v64
	v_max_f32_e32 v64, v69, v69
	v_mul_f32_e32 v69, v65, v65
	v_max_f32_e32 v65, v70, v70
	v_mul_f32_e32 v70, v66, v66
	v_max_f32_e32 v66, v71, v71
	v_max_f32_e32 v64, 0, v64
	v_max_f32_e32 v65, 0, v65
	v_max_f32_e32 v66, 0, v66
	v_max_f32_e32 v68, 0, v68
	v_mul_f32_e32 v64, v64, v64
	v_mul_f32_e32 v65, v65, v65
	v_max_f32_e32 v67, 0, v67
	v_mul_f32_e32 v66, v66, v66
	v_max_f32_e32 v56, v56, v56
	v_mul_f32_e32 v68, v68, v68
	v_mul_f32_e32 v67, v67, v67
	v_cvt_pk_bf16_f32 v64, v68, v64
	v_cvt_pk_bf16_f32 v65, v65, v66
	v_cvt_pk_bf16_f32 v66, v72, v69
	v_max_f32_e32 v56, 0, v56
	v_max_f32_e32 v57, v57, v57
	v_max_f32_e32 v58, v58, v58
	v_cvt_pk_bf16_f32 v67, v70, v67
	global_store_dwordx4 v[80:81], v[64:67], off offset:256
	v_max_f32_e32 v60, v60, v60
	v_max_f32_e32 v57, 0, v57
	v_mul_f32_e32 v66, v56, v56
	v_max_f32_e32 v56, v61, v61
	v_max_f32_e32 v58, 0, v58
	s_mov_b64 s[2:3], 0x200000
	v_max_f32_e32 v60, 0, v60
	v_max_f32_e32 v56, 0, v56
	v_mul_f32_e32 v61, v57, v57
	v_max_f32_e32 v57, v62, v62
	v_mul_f32_e32 v62, v58, v58
	v_max_f32_e32 v58, v63, v63
	v_lshl_add_u64 v[64:65], v[138:139], 0, s[2:3]
	v_mul_f32_e32 v60, v60, v60
	v_mul_f32_e32 v56, v56, v56
	v_max_f32_e32 v57, 0, v57
	v_max_f32_e32 v58, 0, v58
	v_max_f32_e32 v59, v59, v59
	s_mov_b32 s2, 0x200000
	v_mul_f32_e32 v57, v57, v57
	v_max_f32_e32 v59, 0, v59
	v_mul_f32_e32 v58, v58, v58
	v_cvt_pk_bf16_f32 v56, v60, v56
	v_add_co_u32_e32 v60, vcc, s2, v138
	v_max_f32_e32 v48, v48, v48
	v_max_f32_e32 v49, v49, v49
	v_max_f32_e32 v50, v50, v50
	v_mul_f32_e32 v59, v59, v59
	v_cvt_pk_bf16_f32 v57, v57, v58
	v_cvt_pk_bf16_f32 v58, v66, v61
	v_addc_co_u32_e32 v61, vcc, 0, v139, vcc
	v_max_f32_e32 v48, 0, v48
	v_max_f32_e32 v49, 0, v49
	v_max_f32_e32 v50, 0, v50
	v_cvt_pk_bf16_f32 v59, v62, v59
	global_store_dwordx4 v[60:61], v[56:59], off
	v_max_f32_e32 v52, v52, v52
	v_max_f32_e32 v51, v51, v51
	v_mul_f32_e32 v56, v48, v48
	v_max_f32_e32 v48, v53, v53
	v_mul_f32_e32 v53, v49, v49
	v_max_f32_e32 v49, v54, v54
	v_mul_f32_e32 v54, v50, v50
	v_max_f32_e32 v50, v55, v55
	v_max_f32_e32 v48, 0, v48
	v_max_f32_e32 v49, 0, v49
	v_max_f32_e32 v50, 0, v50
	v_max_f32_e32 v52, 0, v52
	v_mul_f32_e32 v48, v48, v48
	v_mul_f32_e32 v49, v49, v49
	v_max_f32_e32 v51, 0, v51
	v_mul_f32_e32 v50, v50, v50
	v_max_f32_e32 v40, v40, v40
	v_mul_f32_e32 v52, v52, v52
	v_mul_f32_e32 v51, v51, v51
	v_cvt_pk_bf16_f32 v48, v52, v48
	v_cvt_pk_bf16_f32 v49, v49, v50
	v_cvt_pk_bf16_f32 v50, v56, v53
	v_max_f32_e32 v40, 0, v40
	v_max_f32_e32 v41, v41, v41
	v_max_f32_e32 v42, v42, v42
	v_cvt_pk_bf16_f32 v51, v54, v51
	global_store_dwordx4 v[64:65], v[48:51], off offset:256
	v_max_f32_e32 v44, v44, v44
	v_max_f32_e32 v41, 0, v41
	v_mul_f32_e32 v50, v40, v40
	v_max_f32_e32 v40, v45, v45
	v_max_f32_e32 v42, 0, v42
	s_mov_b64 s[2:3], 0x240000
	v_max_f32_e32 v44, 0, v44
	v_max_f32_e32 v40, 0, v40
	v_mul_f32_e32 v45, v41, v41
	v_max_f32_e32 v41, v46, v46
	v_mul_f32_e32 v46, v42, v42
	v_max_f32_e32 v42, v47, v47
	v_lshl_add_u64 v[48:49], v[138:139], 0, s[2:3]
	v_mul_f32_e32 v44, v44, v44
	v_mul_f32_e32 v40, v40, v40
	v_max_f32_e32 v41, 0, v41
	v_max_f32_e32 v42, 0, v42
	v_max_f32_e32 v43, v43, v43
	s_mov_b32 s2, 0x240000
	v_mul_f32_e32 v41, v41, v41
	v_max_f32_e32 v43, 0, v43
	v_mul_f32_e32 v42, v42, v42
	v_cvt_pk_bf16_f32 v40, v44, v40
	v_add_co_u32_e32 v44, vcc, s2, v138
	v_max_f32_e32 v32, v32, v32
	v_max_f32_e32 v33, v33, v33
	v_max_f32_e32 v34, v34, v34
	v_mul_f32_e32 v43, v43, v43
	v_cvt_pk_bf16_f32 v41, v41, v42
	v_cvt_pk_bf16_f32 v42, v50, v45
	v_addc_co_u32_e32 v45, vcc, 0, v139, vcc
	v_max_f32_e32 v32, 0, v32
	v_max_f32_e32 v33, 0, v33
	v_max_f32_e32 v34, 0, v34
	v_cvt_pk_bf16_f32 v43, v46, v43
	global_store_dwordx4 v[44:45], v[40:43], off
	v_max_f32_e32 v36, v36, v36
	v_max_f32_e32 v35, v35, v35
	v_mul_f32_e32 v40, v32, v32
	v_max_f32_e32 v32, v37, v37
	v_mul_f32_e32 v37, v33, v33
	v_max_f32_e32 v33, v38, v38
	v_mul_f32_e32 v38, v34, v34
	v_max_f32_e32 v34, v39, v39
	v_max_f32_e32 v32, 0, v32
	v_max_f32_e32 v33, 0, v33
	v_max_f32_e32 v34, 0, v34
	v_max_f32_e32 v36, 0, v36
	v_mul_f32_e32 v32, v32, v32
	v_mul_f32_e32 v33, v33, v33
	v_max_f32_e32 v35, 0, v35
	v_mul_f32_e32 v34, v34, v34
	v_max_f32_e32 v24, v24, v24
	v_mul_f32_e32 v36, v36, v36
	v_mul_f32_e32 v35, v35, v35
	v_cvt_pk_bf16_f32 v32, v36, v32
	v_cvt_pk_bf16_f32 v33, v33, v34
	v_cvt_pk_bf16_f32 v34, v40, v37
	v_max_f32_e32 v24, 0, v24
	v_max_f32_e32 v25, v25, v25
	v_max_f32_e32 v26, v26, v26
	v_cvt_pk_bf16_f32 v35, v38, v35
	global_store_dwordx4 v[48:49], v[32:35], off offset:256
	v_max_f32_e32 v28, v28, v28
	v_max_f32_e32 v25, 0, v25
	v_mul_f32_e32 v34, v24, v24
	v_max_f32_e32 v24, v29, v29
	v_max_f32_e32 v26, 0, v26
	s_mov_b64 s[2:3], 0x280000
	v_max_f32_e32 v28, 0, v28
	v_max_f32_e32 v24, 0, v24
	v_mul_f32_e32 v29, v25, v25
	v_max_f32_e32 v25, v30, v30
	v_mul_f32_e32 v30, v26, v26
	v_max_f32_e32 v26, v31, v31
	v_lshl_add_u64 v[32:33], v[138:139], 0, s[2:3]
	v_mul_f32_e32 v28, v28, v28
	v_mul_f32_e32 v24, v24, v24
	v_max_f32_e32 v25, 0, v25
	v_max_f32_e32 v26, 0, v26
	v_max_f32_e32 v27, v27, v27
	s_mov_b32 s2, 0x280000
	v_mul_f32_e32 v25, v25, v25
	v_max_f32_e32 v27, 0, v27
	v_mul_f32_e32 v26, v26, v26
	v_cvt_pk_bf16_f32 v24, v28, v24
	v_add_co_u32_e32 v28, vcc, s2, v138
	v_max_f32_e32 v16, v16, v16
	v_max_f32_e32 v17, v17, v17
	v_max_f32_e32 v18, v18, v18
	v_mul_f32_e32 v27, v27, v27
	v_cvt_pk_bf16_f32 v25, v25, v26
	v_cvt_pk_bf16_f32 v26, v34, v29
	v_addc_co_u32_e32 v29, vcc, 0, v139, vcc
	v_max_f32_e32 v16, 0, v16
	v_max_f32_e32 v17, 0, v17
	v_max_f32_e32 v18, 0, v18
	v_cvt_pk_bf16_f32 v27, v30, v27
	global_store_dwordx4 v[28:29], v[24:27], off
	v_max_f32_e32 v20, v20, v20
	v_max_f32_e32 v19, v19, v19
	v_mul_f32_e32 v24, v16, v16
	v_max_f32_e32 v16, v21, v21
	v_mul_f32_e32 v21, v17, v17
	v_max_f32_e32 v17, v22, v22
	v_mul_f32_e32 v22, v18, v18
	v_max_f32_e32 v18, v23, v23
	v_max_f32_e32 v16, 0, v16
	v_max_f32_e32 v17, 0, v17
	v_max_f32_e32 v18, 0, v18
	v_max_f32_e32 v20, 0, v20
	v_mul_f32_e32 v16, v16, v16
	v_mul_f32_e32 v17, v17, v17
	v_max_f32_e32 v19, 0, v19
	v_mul_f32_e32 v18, v18, v18
	v_max_f32_e32 v8, v8, v8
	v_mul_f32_e32 v20, v20, v20
	v_mul_f32_e32 v19, v19, v19
	v_cvt_pk_bf16_f32 v16, v20, v16
	v_cvt_pk_bf16_f32 v17, v17, v18
	v_cvt_pk_bf16_f32 v18, v24, v21
	v_max_f32_e32 v8, 0, v8
	v_max_f32_e32 v9, v9, v9
	v_max_f32_e32 v10, v10, v10
	v_cvt_pk_bf16_f32 v19, v22, v19
	global_store_dwordx4 v[32:33], v[16:19], off offset:256
	v_max_f32_e32 v12, v12, v12
	v_max_f32_e32 v9, 0, v9
	v_mul_f32_e32 v18, v8, v8
	v_max_f32_e32 v8, v13, v13
	v_max_f32_e32 v10, 0, v10
	s_mov_b64 s[2:3], 0x2c0000
	v_max_f32_e32 v12, 0, v12
	v_max_f32_e32 v8, 0, v8
	v_mul_f32_e32 v13, v9, v9
	v_max_f32_e32 v9, v14, v14
	v_mul_f32_e32 v14, v10, v10
	v_max_f32_e32 v10, v15, v15
	v_lshl_add_u64 v[16:17], v[138:139], 0, s[2:3]
	v_mul_f32_e32 v12, v12, v12
	v_mul_f32_e32 v8, v8, v8
	v_max_f32_e32 v9, 0, v9
	v_max_f32_e32 v10, 0, v10
	v_max_f32_e32 v11, v11, v11
	s_mov_b32 s2, 0x2c0000
	v_mul_f32_e32 v9, v9, v9
	v_max_f32_e32 v11, 0, v11
	v_mul_f32_e32 v10, v10, v10
	v_cvt_pk_bf16_f32 v8, v12, v8
	v_add_co_u32_e32 v12, vcc, s2, v138
	v_max_f32_e32 v0, v0, v0
	v_max_f32_e32 v1, v1, v1
	v_max_f32_e32 v2, v2, v2
	v_mul_f32_e32 v11, v11, v11
	v_cvt_pk_bf16_f32 v9, v9, v10
	v_cvt_pk_bf16_f32 v10, v18, v13
	v_addc_co_u32_e32 v13, vcc, 0, v139, vcc
	v_max_f32_e32 v0, 0, v0
	v_max_f32_e32 v1, 0, v1
	v_max_f32_e32 v2, 0, v2
	v_cvt_pk_bf16_f32 v11, v14, v11
	global_store_dwordx4 v[12:13], v[8:11], off
	v_max_f32_e32 v3, v3, v3
	v_max_f32_e32 v4, v4, v4
	v_mul_f32_e32 v8, v0, v0
	v_max_f32_e32 v0, v5, v5
	v_mul_f32_e32 v5, v1, v1
	v_max_f32_e32 v1, v6, v6
	v_mul_f32_e32 v6, v2, v2
	v_max_f32_e32 v2, v7, v7
	v_max_f32_e32 v0, 0, v0
	v_max_f32_e32 v1, 0, v1
	v_max_f32_e32 v2, 0, v2
	v_max_f32_e32 v3, 0, v3
	v_max_f32_e32 v4, 0, v4
	v_mul_f32_e32 v0, v0, v0
	v_mul_f32_e32 v1, v1, v1
	v_mul_f32_e32 v2, v2, v2
	v_mul_f32_e32 v3, v3, v3
	s_and_b64 vcc, exec, s[0:1]
	s_mov_b32 s67, s14
	s_mov_b32 s38, s28
	s_mov_b64 s[4:5], s[36:37]
	s_mov_b64 s[2:3], s[34:35]
	v_mul_f32_e32 v4, v4, v4
	v_cvt_pk_bf16_f32 v0, v4, v0
	v_cvt_pk_bf16_f32 v1, v1, v2
	v_cvt_pk_bf16_f32 v2, v8, v5
	v_cvt_pk_bf16_f32 v3, v6, v3
	global_store_dwordx4 v[16:17], v[0:3], off offset:256
	s_cbranch_vccz .LBB0_253
	s_waitcnt vmcnt(0)
	v_readlane_b32 s62, v254, 59
	s_cmpk_gt_u32 s41, 0xff
	v_readlane_b32 s55, v254, 57
	v_readlane_b32 s58, v254, 58
	v_readlane_b32 s63, v254, 60
	v_readlane_b32 s59, v255, 1
	s_movk_i32 s66, 0x3000
	v_readlane_b32 s49, v255, 18
	s_cbranch_scc1 .LBB0_260
	s_barrier

.LBB0_329:
	v_add_u32_e32 v140, 0x10000, v249
	ds_read_b128 v[128:131], v140
	ds_read_b128 v[132:135], v140 offset:1024
	ds_read_b128 v[136:139], v140 offset:2048
	ds_read_b128 v[140:143], v140 offset:3072
	ds_read_b128 v[144:147], v250
	ds_read_b128 v[148:151], v250 offset:1024
	ds_read_b128 v[152:155], v250 offset:2048
	ds_read_b128 v[156:159], v250 offset:3072
	ds_read_b128 v[160:163], v250 offset:4096
	ds_read_b128 v[164:167], v250 offset:5120
	ds_read_b128 v[168:171], v250 offset:6144
	ds_read_b128 v[172:175], v250 offset:7168
	v_add_u32_e32 v188, 0x14000, v249
	ds_read_b128 v[176:179], v188
	ds_read_b128 v[180:183], v188 offset:1024
	ds_read_b128 v[184:187], v188 offset:2048
	ds_read_b128 v[188:191], v188 offset:3072
	s_add_u32 s2, s0, 0xfff80080
	s_addc_u32 s3, s1, -1
	s_add_i32 s9, 0, 0x10000
	s_cmp_eq_u32 s40, 28
	s_cselect_b32 s5, s53, s3
	s_cselect_b32 s4, s52, s2
	s_cselect_b32 s3, s67, s37
	s_cselect_b32 s2, s66, s36
	v_lshl_add_u64 v[218:219], s[0:1], 0, v[202:203]
	s_add_i32 m0, s51, 0xc000
	s_nop 0
	global_load_lds_dwordx4 v[218:219], off
	v_lshl_add_u64 v[220:221], s[0:1], 0, v[204:205]
	s_add_i32 m0, s51, 0xe000
	s_nop 0
	global_load_lds_dwordx4 v[220:221], off
	s_waitcnt vmcnt(8)
	s_waitcnt lgkmcnt(0)
	s_barrier
	v_mfma_f32_16x16x32_bf16 v[124:127], v[128:131], v[144:147], v[124:127]
	v_mfma_f32_16x16x32_bf16 v[120:123], v[136:139], v[144:147], v[120:123]
	v_mfma_f32_16x16x32_bf16 v[108:111], v[128:131], v[152:155], v[108:111]
	v_mfma_f32_16x16x32_bf16 v[104:107], v[136:139], v[152:155], v[104:107]
	v_mfma_f32_16x16x32_bf16 v[92:95], v[128:131], v[160:163], v[92:95]
	v_mfma_f32_16x16x32_bf16 v[88:91], v[136:139], v[160:163], v[88:91]
	v_mfma_f32_16x16x32_bf16 v[76:79], v[128:131], v[168:171], v[76:79]
	v_mfma_f32_16x16x32_bf16 v[72:75], v[136:139], v[168:171], v[72:75]
	v_mfma_f32_16x16x32_bf16 v[124:127], v[132:135], v[148:151], v[124:127]
	v_mfma_f32_16x16x32_bf16 v[120:123], v[140:143], v[148:151], v[120:123]
	v_mfma_f32_16x16x32_bf16 v[108:111], v[132:135], v[156:159], v[108:111]
	v_mfma_f32_16x16x32_bf16 v[104:107], v[140:143], v[156:159], v[104:107]
	v_mfma_f32_16x16x32_bf16 v[92:95], v[132:135], v[164:167], v[92:95]
	v_mfma_f32_16x16x32_bf16 v[88:91], v[140:143], v[164:167], v[88:91]
	v_mfma_f32_16x16x32_bf16 v[76:79], v[132:135], v[172:175], v[76:79]
	v_mfma_f32_16x16x32_bf16 v[72:75], v[140:143], v[172:175], v[72:75]
	v_mfma_f32_16x16x32_bf16 v[116:119], v[176:179], v[144:147], v[116:119]
	v_mfma_f32_16x16x32_bf16 v[112:115], v[184:187], v[144:147], v[112:115]
	v_mfma_f32_16x16x32_bf16 v[100:103], v[176:179], v[152:155], v[100:103]
	v_mfma_f32_16x16x32_bf16 v[96:99], v[184:187], v[152:155], v[96:99]
	v_mfma_f32_16x16x32_bf16 v[84:87], v[176:179], v[160:163], v[84:87]
	v_mfma_f32_16x16x32_bf16 v[80:83], v[184:187], v[160:163], v[80:83]
	v_mfma_f32_16x16x32_bf16 v[68:71], v[176:179], v[168:171], v[68:71]
	v_mfma_f32_16x16x32_bf16 v[64:67], v[184:187], v[168:171], v[64:67]
	v_mfma_f32_16x16x32_bf16 v[116:119], v[180:183], v[148:151], v[116:119]
	v_mfma_f32_16x16x32_bf16 v[112:115], v[188:191], v[148:151], v[112:115]
	v_mfma_f32_16x16x32_bf16 v[100:103], v[180:183], v[156:159], v[100:103]
	v_mfma_f32_16x16x32_bf16 v[96:99], v[188:191], v[156:159], v[96:99]
	v_mfma_f32_16x16x32_bf16 v[84:87], v[180:183], v[164:167], v[84:87]
	v_mfma_f32_16x16x32_bf16 v[80:83], v[188:191], v[164:167], v[80:83]
	v_mfma_f32_16x16x32_bf16 v[68:71], v[180:183], v[172:175], v[68:71]
	v_mfma_f32_16x16x32_bf16 v[64:67], v[188:191], v[172:175], v[64:67]
	s_barrier
	ds_read_b128 v[144:147], v250 offset:16384
	ds_read_b128 v[148:151], v250 offset:17408
	ds_read_b128 v[152:155], v250 offset:18432
	ds_read_b128 v[156:159], v250 offset:19456
	ds_read_b128 v[160:163], v250 offset:20480
	ds_read_b128 v[164:167], v250 offset:21504
	ds_read_b128 v[168:171], v250 offset:22528
	ds_read_b128 v[172:175], v250 offset:23552
	s_add_i32 s41, 0, 0x14000
	s_add_i32 s9, s9, s50
	v_lshl_add_u64 v[206:207], s[2:3], 0, v[196:197]
	s_mov_b32 m0, s9
	s_nop 0
	global_load_lds_dwordx4 v[206:207], off
	v_lshl_add_u64 v[208:209], s[2:3], 0, v[200:201]
	s_add_i32 m0, s9, 0x2000
	s_nop 0
	global_load_lds_dwordx4 v[208:209], off
	s_mov_b32 m0, s51
	v_lshl_add_u64 v[210:211], s[4:5], 0, v[194:195]
	global_load_lds_dwordx4 v[210:211], off
	v_lshl_add_u64 v[212:213], s[4:5], 0, v[198:199]
	s_mov_b32 m0, s62
	s_nop 0
	global_load_lds_dwordx4 v[212:213], off
	s_add_u32 s46, s2, 0x80000
	s_addc_u32 s47, s3, 0
	s_add_i32 s9, s41, s50
	v_lshl_add_u64 v[218:219], s[46:47], 0, v[196:197]
	s_mov_b32 m0, s9
	s_nop 0
	global_load_lds_dwordx4 v[218:219], off
	v_lshl_add_u64 v[220:221], s[46:47], 0, v[200:201]
	s_add_i32 m0, s9, 0x2000
	s_nop 0
	global_load_lds_dwordx4 v[220:221], off
	s_waitcnt vmcnt(8)
	s_waitcnt lgkmcnt(0)
	s_barrier
	v_mfma_f32_16x16x32_bf16 v[60:63], v[128:131], v[144:147], v[60:63]
	v_mfma_f32_16x16x32_bf16 v[56:59], v[136:139], v[144:147], v[56:59]
	v_mfma_f32_16x16x32_bf16 v[44:47], v[128:131], v[152:155], v[44:47]
	v_mfma_f32_16x16x32_bf16 v[40:43], v[136:139], v[152:155], v[40:43]
	v_mfma_f32_16x16x32_bf16 v[28:31], v[128:131], v[160:163], v[28:31]
	v_mfma_f32_16x16x32_bf16 v[24:27], v[136:139], v[160:163], v[24:27]
	v_mfma_f32_16x16x32_bf16 v[12:15], v[128:131], v[168:171], v[12:15]
	v_mfma_f32_16x16x32_bf16 v[8:11], v[136:139], v[168:171], v[8:11]
	v_mfma_f32_16x16x32_bf16 v[60:63], v[132:135], v[148:151], v[60:63]
	v_mfma_f32_16x16x32_bf16 v[56:59], v[140:143], v[148:151], v[56:59]
	v_mfma_f32_16x16x32_bf16 v[44:47], v[132:135], v[156:159], v[44:47]
	v_mfma_f32_16x16x32_bf16 v[40:43], v[140:143], v[156:159], v[40:43]
	v_mfma_f32_16x16x32_bf16 v[28:31], v[132:135], v[164:167], v[28:31]
	v_mfma_f32_16x16x32_bf16 v[24:27], v[140:143], v[164:167], v[24:27]
	v_mfma_f32_16x16x32_bf16 v[12:15], v[132:135], v[172:175], v[12:15]
	v_mfma_f32_16x16x32_bf16 v[8:11], v[140:143], v[172:175], v[8:11]
	v_mfma_f32_16x16x32_bf16 v[52:55], v[176:179], v[144:147], v[52:55]
	v_mfma_f32_16x16x32_bf16 v[48:51], v[184:187], v[144:147], v[48:51]
	v_mfma_f32_16x16x32_bf16 v[36:39], v[176:179], v[152:155], v[36:39]
	v_mfma_f32_16x16x32_bf16 v[32:35], v[184:187], v[152:155], v[32:35]
	v_mfma_f32_16x16x32_bf16 v[20:23], v[176:179], v[160:163], v[20:23]
	v_mfma_f32_16x16x32_bf16 v[16:19], v[184:187], v[160:163], v[16:19]
	v_mfma_f32_16x16x32_bf16 v[4:7], v[176:179], v[168:171], v[4:7]
	v_mfma_f32_16x16x32_bf16 v[0:3], v[184:187], v[168:171], v[0:3]
	v_mfma_f32_16x16x32_bf16 v[52:55], v[180:183], v[148:151], v[52:55]
	v_mfma_f32_16x16x32_bf16 v[48:51], v[188:191], v[148:151], v[48:51]
	v_mfma_f32_16x16x32_bf16 v[36:39], v[180:183], v[156:159], v[36:39]
	v_mfma_f32_16x16x32_bf16 v[32:35], v[188:191], v[156:159], v[32:35]
	v_mfma_f32_16x16x32_bf16 v[20:23], v[180:183], v[164:167], v[20:23]
	v_mfma_f32_16x16x32_bf16 v[16:19], v[188:191], v[164:167], v[16:19]
	v_mfma_f32_16x16x32_bf16 v[4:7], v[180:183], v[172:175], v[4:7]
	v_mfma_f32_16x16x32_bf16 v[0:3], v[188:191], v[172:175], v[0:3]
	s_barrier
	v_add_u32_e32 v140, 0x18000, v249
	ds_read_b128 v[128:131], v140
	ds_read_b128 v[132:135], v140 offset:1024
	ds_read_b128 v[136:139], v140 offset:2048
	ds_read_b128 v[140:143], v140 offset:3072
	ds_read_b128 v[144:147], v250 offset:32768
	ds_read_b128 v[148:151], v250 offset:33792
	ds_read_b128 v[152:155], v250 offset:34816
	ds_read_b128 v[156:159], v250 offset:35840
	ds_read_b128 v[160:163], v250 offset:36864
	ds_read_b128 v[164:167], v250 offset:37888
	ds_read_b128 v[168:171], v250 offset:38912
	ds_read_b128 v[172:175], v250 offset:39936
	v_add_u32_e32 v188, 0x1c000, v249
	ds_read_b128 v[176:179], v188
	ds_read_b128 v[180:183], v188 offset:1024
	ds_read_b128 v[184:187], v188 offset:2048
	ds_read_b128 v[188:191], v188 offset:3072
	s_add_i32 s9, 0, 0x18000
	s_add_u32 s4, s4, 0x80000
	s_addc_u32 s5, s5, 0
	s_mov_b32 m0, s63
	v_lshl_add_u64 v[218:219], s[4:5], 0, v[194:195]
	global_load_lds_dwordx4 v[218:219], off
	v_lshl_add_u64 v[220:221], s[4:5], 0, v[198:199]
	s_mov_b32 m0, s69
	s_nop 0
	global_load_lds_dwordx4 v[220:221], off
	s_waitcnt vmcnt(8)
	s_waitcnt lgkmcnt(0)
	s_barrier
	v_mfma_f32_16x16x32_bf16 v[124:127], v[128:131], v[144:147], v[124:127]
	v_mfma_f32_16x16x32_bf16 v[120:123], v[136:139], v[144:147], v[120:123]
	v_mfma_f32_16x16x32_bf16 v[108:111], v[128:131], v[152:155], v[108:111]
	v_mfma_f32_16x16x32_bf16 v[104:107], v[136:139], v[152:155], v[104:107]
	v_mfma_f32_16x16x32_bf16 v[92:95], v[128:131], v[160:163], v[92:95]
	v_mfma_f32_16x16x32_bf16 v[88:91], v[136:139], v[160:163], v[88:91]
	v_mfma_f32_16x16x32_bf16 v[76:79], v[128:131], v[168:171], v[76:79]
	v_mfma_f32_16x16x32_bf16 v[72:75], v[136:139], v[168:171], v[72:75]
	v_mfma_f32_16x16x32_bf16 v[124:127], v[132:135], v[148:151], v[124:127]
	v_mfma_f32_16x16x32_bf16 v[120:123], v[140:143], v[148:151], v[120:123]
	v_mfma_f32_16x16x32_bf16 v[108:111], v[132:135], v[156:159], v[108:111]
	v_mfma_f32_16x16x32_bf16 v[104:107], v[140:143], v[156:159], v[104:107]
	v_mfma_f32_16x16x32_bf16 v[92:95], v[132:135], v[164:167], v[92:95]
	v_mfma_f32_16x16x32_bf16 v[88:91], v[140:143], v[164:167], v[88:91]
	v_mfma_f32_16x16x32_bf16 v[76:79], v[132:135], v[172:175], v[76:79]
	v_mfma_f32_16x16x32_bf16 v[72:75], v[140:143], v[172:175], v[72:75]
	v_mfma_f32_16x16x32_bf16 v[116:119], v[176:179], v[144:147], v[116:119]
	v_mfma_f32_16x16x32_bf16 v[112:115], v[184:187], v[144:147], v[112:115]
	v_mfma_f32_16x16x32_bf16 v[100:103], v[176:179], v[152:155], v[100:103]
	v_mfma_f32_16x16x32_bf16 v[96:99], v[184:187], v[152:155], v[96:99]
	v_mfma_f32_16x16x32_bf16 v[84:87], v[176:179], v[160:163], v[84:87]
	v_mfma_f32_16x16x32_bf16 v[80:83], v[184:187], v[160:163], v[80:83]
	v_mfma_f32_16x16x32_bf16 v[68:71], v[176:179], v[168:171], v[68:71]
	v_mfma_f32_16x16x32_bf16 v[64:67], v[184:187], v[168:171], v[64:67]
	v_mfma_f32_16x16x32_bf16 v[116:119], v[180:183], v[148:151], v[116:119]
	v_mfma_f32_16x16x32_bf16 v[112:115], v[188:191], v[148:151], v[112:115]
	v_mfma_f32_16x16x32_bf16 v[100:103], v[180:183], v[156:159], v[100:103]
	v_mfma_f32_16x16x32_bf16 v[96:99], v[188:191], v[156:159], v[96:99]
	v_mfma_f32_16x16x32_bf16 v[84:87], v[180:183], v[164:167], v[84:87]
	v_mfma_f32_16x16x32_bf16 v[80:83], v[188:191], v[164:167], v[80:83]
	v_mfma_f32_16x16x32_bf16 v[68:71], v[180:183], v[172:175], v[68:71]
	v_mfma_f32_16x16x32_bf16 v[64:67], v[188:191], v[172:175], v[64:67]
	s_barrier
	ds_read_b128 v[144:147], v250 offset:49152
	ds_read_b128 v[148:151], v250 offset:50176
	ds_read_b128 v[152:155], v250 offset:51200
	ds_read_b128 v[156:159], v250 offset:52224
	ds_read_b128 v[160:163], v250 offset:53248
	ds_read_b128 v[164:167], v250 offset:54272
	ds_read_b128 v[168:171], v250 offset:55296
	ds_read_b128 v[172:175], v250 offset:56320
	s_add_i32 s4, 0, 0x1c000
	s_add_i32 s5, s9, s50
	v_lshl_add_u64 v[206:207], v[206:207], 0, s[72:73]
	s_mov_b32 m0, s5
	s_nop 0
	global_load_lds_dwordx4 v[206:207], off
	v_lshl_add_u64 v[206:207], v[208:209], 0, s[72:73]
	s_add_i32 m0, s5, 0x2000
	s_nop 0
	global_load_lds_dwordx4 v[206:207], off
	s_mov_b32 m0, s71
	v_lshl_add_u64 v[206:207], v[210:211], 0, s[72:73]
	global_load_lds_dwordx4 v[206:207], off
	v_lshl_add_u64 v[206:207], v[212:213], 0, s[72:73]
	s_mov_b32 m0, s75
	s_nop 0
	global_load_lds_dwordx4 v[206:207], off
	s_add_u32 s2, s2, 0x80080
	s_addc_u32 s3, s3, 0
	s_add_i32 s4, s4, s50
	v_lshl_add_u64 v[218:219], s[2:3], 0, v[196:197]
	s_mov_b32 m0, s4
	s_nop 0
	global_load_lds_dwordx4 v[218:219], off
	v_lshl_add_u64 v[220:221], s[2:3], 0, v[200:201]
	s_add_i32 m0, s4, 0x2000
	s_nop 0
	global_load_lds_dwordx4 v[220:221], off
	s_waitcnt vmcnt(8)
	s_waitcnt lgkmcnt(0)
	s_barrier
	v_mfma_f32_16x16x32_bf16 v[60:63], v[128:131], v[144:147], v[60:63]
	v_mfma_f32_16x16x32_bf16 v[56:59], v[136:139], v[144:147], v[56:59]
	v_mfma_f32_16x16x32_bf16 v[44:47], v[128:131], v[152:155], v[44:47]
	v_mfma_f32_16x16x32_bf16 v[40:43], v[136:139], v[152:155], v[40:43]
	v_mfma_f32_16x16x32_bf16 v[28:31], v[128:131], v[160:163], v[28:31]
	v_mfma_f32_16x16x32_bf16 v[24:27], v[136:139], v[160:163], v[24:27]
	v_mfma_f32_16x16x32_bf16 v[12:15], v[128:131], v[168:171], v[12:15]
	v_mfma_f32_16x16x32_bf16 v[8:11], v[136:139], v[168:171], v[8:11]
	v_mfma_f32_16x16x32_bf16 v[60:63], v[132:135], v[148:151], v[60:63]
	v_mfma_f32_16x16x32_bf16 v[56:59], v[140:143], v[148:151], v[56:59]
	v_mfma_f32_16x16x32_bf16 v[44:47], v[132:135], v[156:159], v[44:47]
	v_mfma_f32_16x16x32_bf16 v[40:43], v[140:143], v[156:159], v[40:43]
	v_mfma_f32_16x16x32_bf16 v[28:31], v[132:135], v[164:167], v[28:31]
	v_mfma_f32_16x16x32_bf16 v[24:27], v[140:143], v[164:167], v[24:27]
	v_mfma_f32_16x16x32_bf16 v[12:15], v[132:135], v[172:175], v[12:15]
	v_mfma_f32_16x16x32_bf16 v[8:11], v[140:143], v[172:175], v[8:11]
	v_mfma_f32_16x16x32_bf16 v[52:55], v[176:179], v[144:147], v[52:55]
	v_mfma_f32_16x16x32_bf16 v[48:51], v[184:187], v[144:147], v[48:51]
	v_mfma_f32_16x16x32_bf16 v[36:39], v[176:179], v[152:155], v[36:39]
	v_mfma_f32_16x16x32_bf16 v[32:35], v[184:187], v[152:155], v[32:35]
	v_mfma_f32_16x16x32_bf16 v[20:23], v[176:179], v[160:163], v[20:23]
	v_mfma_f32_16x16x32_bf16 v[16:19], v[184:187], v[160:163], v[16:19]
	v_mfma_f32_16x16x32_bf16 v[4:7], v[176:179], v[168:171], v[4:7]
	v_mfma_f32_16x16x32_bf16 v[0:3], v[184:187], v[168:171], v[0:3]
	v_mfma_f32_16x16x32_bf16 v[52:55], v[180:183], v[148:151], v[52:55]
	v_mfma_f32_16x16x32_bf16 v[48:51], v[188:191], v[148:151], v[48:51]
	v_mfma_f32_16x16x32_bf16 v[36:39], v[180:183], v[156:159], v[36:39]
	v_mfma_f32_16x16x32_bf16 v[32:35], v[188:191], v[156:159], v[32:35]
	v_mfma_f32_16x16x32_bf16 v[20:23], v[180:183], v[164:167], v[20:23]
	v_mfma_f32_16x16x32_bf16 v[16:19], v[188:191], v[164:167], v[16:19]
	v_mfma_f32_16x16x32_bf16 v[4:7], v[180:183], v[172:175], v[4:7]
	v_mfma_f32_16x16x32_bf16 v[0:3], v[188:191], v[172:175], v[0:3]
	s_add_i32 s40, s40, 2
	s_add_u32 s0, s0, 0x100
	s_addc_u32 s1, s1, 0
	s_add_u32 s36, s36, 0x100
	s_addc_u32 s37, s37, 0
	s_cmp_gt_u32 s40, 29
	s_barrier
	s_cbranch_scc0 .LBB0_329
	v_mov_b32 v128, v248
	s_cmp_gt_u32 s38, 1
	v_and_b32_e32 v246, 15, v128
	v_ashrrev_i32_e32 v247, 4, v128
	s_mov_b64 s[0:1], -1
	s_cbranch_scc0 .LBB0_413
	s_and_b32 s4, s39, 3
	s_cmp_lg_u32 s38, 2
	s_cbranch_scc0 .LBB0_400
	s_lshl_b32 s40, s49, 8
	v_or_b32_e32 v128, s78, v246
	v_add_u32_e32 v134, s40, v128
	v_min_i32_e32 v130, 0x2000, v134
	v_lshlrev_b32_e32 v130, 8, v130
	v_add_lshl_u32 v206, v247, s85, 2
	v_readlane_b32 s0, v251, 61
	v_and_b32_e32 v192, 0x7cf00, v130
	v_or_b32_e32 v130, 16, v134
	v_ashrrev_i32_e32 v207, 31, v206
	v_readlane_b32 s1, v251, 62
	v_min_i32_e32 v130, 0x2000, v130
	v_or_b32_e32 v132, 32, v134
	v_lshl_add_u64 v[128:129], v[206:207], 2, s[0:1]
	v_lshlrev_b32_e32 v130, 8, v130
	v_min_i32_e32 v132, 0x2000, v132
	v_lshl_add_u64 v[210:211], v[128:129], 0, v[192:193]
	v_and_b32_e32 v192, 0x7ff00, v130
	v_lshlrev_b32_e32 v132, 8, v132
	v_lshl_add_u64 v[130:131], v[128:129], 0, v[192:193]
	v_and_b32_e32 v192, 0x7ff00, v132
	global_load_dwordx4 v[188:191], v[210:211], off offset:128
	global_load_dwordx4 v[176:179], v[130:131], off
	v_lshl_add_u64 v[132:133], v[128:129], 0, v[192:193]
	global_load_dwordx4 v[180:183], v[130:131], off offset:128
	global_load_dwordx4 v[168:171], v[132:133], off
	v_or_b32_e32 v130, 48, v134
	v_min_i32_e32 v130, 0x2000, v130
	v_lshlrev_b32_e32 v130, 8, v130
	v_and_b32_e32 v192, 0x7ff00, v130
	v_lshl_add_u64 v[130:131], v[128:129], 0, v[192:193]
	global_load_dwordx4 v[172:175], v[132:133], off offset:128
	global_load_dwordx4 v[160:163], v[130:131], off
	v_add_u32_e32 v132, 0x80, v134
	v_min_i32_e32 v132, 0x2000, v132
	v_lshlrev_b32_e32 v132, 8, v132
	v_and_b32_e32 v192, 0x7ff00, v132
	v_lshl_add_u64 v[132:133], v[128:129], 0, v[192:193]
	global_load_dwordx4 v[164:167], v[130:131], off offset:128
	global_load_dwordx4 v[152:155], v[132:133], off
	v_add_u32_e32 v130, 0x90, v134
	v_min_i32_e32 v130, 0x2000, v130
	v_lshlrev_b32_e32 v130, 8, v130
	v_and_b32_e32 v192, 0x7ff00, v130
	v_lshl_add_u64 v[130:131], v[128:129], 0, v[192:193]
	global_load_dwordx4 v[156:159], v[132:133], off offset:128
	global_load_dwordx4 v[144:147], v[130:131], off
	v_add_u32_e32 v132, 0xa0, v134
	v_min_i32_e32 v132, 0x2000, v132
	v_lshlrev_b32_e32 v132, 8, v132
	v_and_b32_e32 v192, 0x7ff00, v132
	v_lshl_add_u64 v[132:133], v[128:129], 0, v[192:193]
	global_load_dwordx4 v[148:151], v[130:131], off offset:128
	global_load_dwordx4 v[136:139], v[132:133], off
	v_add_u32_e32 v130, 0xb0, v134
	v_min_i32_e32 v130, 0x2000, v130
	v_lshlrev_b32_e32 v130, 8, v130
	v_and_b32_e32 v192, 0x7ff00, v130
	v_lshl_add_u64 v[128:129], v[128:129], 0, v[192:193]
	global_load_dwordx4 v[140:143], v[132:133], off offset:128
	s_nop 0
	global_load_dwordx4 v[132:135], v[128:129], off
	s_nop 0
	global_load_dwordx4 v[128:131], v[128:129], off offset:128
	s_add_i32 s2, s40, s78
	v_or_b32_e32 v208, s2, v246
	v_mov_b32_e32 v184, 1.0
	v_cmp_gt_i32_e32 vcc, s33, v208
	v_mov_b32_e32 v185, v184
	v_mov_b32_e32 v186, v184
	v_mov_b32_e32 v187, v184
	s_and_saveexec_b64 s[0:1], vcc
	s_cbranch_execz .LBB0_334
	global_load_dwordx4 v[184:187], v[210:211], off
